# GEMM K-loops: the four B0 fragment LDS reads of the second K-tile's 16-read load segment issued inside the preceding MFMA block (LDS-read balancing; an LDS probe showed the 16-read segments are LDS-bo
# speedup vs baseline: 1.0042x; 1.0003x over previous
; #define PG8_STAGE(bufoff, gbase, voff) do { if constexpr (!pg8_noload<Epi>::value) { _Pragma("unroll") for (int _i = 0; _i < 2; ++_i) \
;         __builtin_amdgcn_global_load_lds((const unsigned*)((const char*)(gbase) + (size_t)_i * pstep + (voff)[0]), (PG8_LAS unsigned*)(lds + (bufoff) + ldsw + _i * 8192), 16, 0, 0); } } while (0)
; #define PG8_LDA(dst, b, h) do { _Pragma("unroll") for (int m = 0; m < 4; ++m) _Pragma("unroll") for (int k = 0; k < 2; ++k) dst[m][k] = *(const PG8_LAS bf16x8*)(lds + PG8_SA(b, h) + aoff + m * 2048 + k * 1024); } while (0)
; #define PG8_LDB(dst, b, h) do { _Pragma("unroll") for (int n = 0; n < 2; ++n) _Pragma("unroll") for (int k = 0; k < 2; ++k) dst[n][k] = *(const PG8_LAS bf16x8*)(lds + PG8_SB(b, h) + boff + n * 2048 + k * 1024); } while (0)
; #define PG8_MMA(ai, bj, At, Bt) do { __builtin_amdgcn_s_setprio(1); _Pragma("unroll") for (int m = 0; m < 4; ++m) _Pragma("unroll") for (int n = 0; n < 2; ++n) _Pragma("unroll") for (int k = 0; k < 2; ++k) \
;         acc[ai][bj][m][n] = __builtin_amdgcn_mfma_f32_16x16x32_bf16(Bt[n][k], At[m][k], acc[ai][bj][m][n], 0, 0, 0); __builtin_amdgcn_s_setprio(0); } while (0)
; #define PG8_WAIT_V(n) asm volatile("s_waitcnt vmcnt(" #n ")" ::: "memory")
; #define PG8_WAIT_L(n) asm volatile("s_waitcnt lgkmcnt(" #n ")" ::: "memory")
; #define PG8_BAR __builtin_amdgcn_s_barrier()
; #define PG8_SCHED __builtin_amdgcn_sched_barrier(0)
; template <class Epi, class Sched, bool ALIGN_EPI = false, bool SP2 = false, bool ABLK = false>
; __device__ __forceinline__ void gemm_phase(PG8_LAS unsigned char* lds, const Gemm g, const Sched& S, const Epi& E) {
;     ...
;             PG8_LDB(B0, 0, 0); PG8_LDB(B1, 0, 1); PG8_SCHED; PG8_LDA(At, 0, 0); PG8_STAGE(PG8_SA(1, 1), a1 + hstep, voffA);
;             PG8_WAIT_V(8); PG8_WAIT_L(0); PG8_BAR; PG8_MMA(0, 0, At, B0); PG8_MMA(0, 1, At, B1); PG8_BAR; PG8_SCHED;
;             PG8_LDA(At, 0, 1); PG8_STAGE(PG8_SB(0, 0), b2, voffB); PG8_STAGE(PG8_SB(0, 1), b2 + hstep, voffB); PG8_STAGE(PG8_SA(0, 0), a2, voffA);
;             PG8_WAIT_V(8); PG8_WAIT_L(0); PG8_BAR; PG8_MMA(1, 0, At, B0); PG8_MMA(1, 1, At, B1); PG8_BAR; PG8_SCHED;
.LBB0_114:
	ds_read_b128 v[144:147], v168
	ds_read_b128 v[184:187], v168 offset:1024
	ds_read_b128 v[188:191], v168 offset:2048
	ds_read_b128 v[192:195], v168 offset:3072
	ds_read_b128 v[196:199], v169
	ds_read_b128 v[200:203], v169 offset:1024
	ds_read_b128 v[204:207], v169 offset:2048
	ds_read_b128 v[208:211], v169 offset:3072
	s_add_u32 s71, vcc_lo, 0xfff80800
	s_addc_u32 s73, vcc_hi, -1
	s_cmp_eq_u32 s70, 28
	s_cselect_b32 s75, s3, s73
	s_cselect_b32 s74, s7, s71
	s_cselect_b32 s77, s21, s17
	s_cselect_b32 s76, s72, s16
	v_lshl_add_u64 v[244:245], vcc, 0, v[136:137]
	s_add_i32 m0, s53, 0xc000
	ds_read_b128 v[212:215], v170
	ds_read_b128 v[216:219], v170 offset:1024
	ds_read_b128 v[220:223], v170 offset:2048
	ds_read_b128 v[224:227], v170 offset:3072
	ds_read_b128 v[228:231], v170 offset:4096
	ds_read_b128 v[232:235], v170 offset:5120
	ds_read_b128 v[236:239], v170 offset:6144
	ds_read_b128 v[240:243], v170 offset:7168
	global_load_lds_dwordx4 v[244:245], off
	v_lshl_add_u64 v[244:245], v[244:245], 0, s[0:1]
	s_add_i32 m0, s53, 0xe000
	s_nop 0
	global_load_lds_dwordx4 v[244:245], off
	s_waitcnt vmcnt(8)
	s_waitcnt lgkmcnt(0)
	s_barrier
	s_setprio 1
	s_waitcnt lgkmcnt(0)
	v_mfma_f32_16x16x32_bf16 v[126:129], v[144:147], v[212:215], v[126:129]
	v_mfma_f32_16x16x32_bf16 v[126:129], v[184:187], v[216:219], v[126:129]
	v_mfma_f32_16x16x32_bf16 v[110:113], v[184:187], v[224:227], v[110:113]
	v_mfma_f32_16x16x32_bf16 v[110:113], v[144:147], v[220:223], v[110:113]
	v_mfma_f32_16x16x32_bf16 v[94:97], v[144:147], v[228:231], v[94:97]
	v_mfma_f32_16x16x32_bf16 v[94:97], v[184:187], v[232:235], v[94:97]
	v_mfma_f32_16x16x32_bf16 v[78:81], v[184:187], v[240:243], v[78:81]
	v_mfma_f32_16x16x32_bf16 v[78:81], v[144:147], v[236:239], v[78:81]
	v_mfma_f32_16x16x32_bf16 v[74:77], v[188:191], v[236:239], v[74:77]
	v_mfma_f32_16x16x32_bf16 v[74:77], v[192:195], v[240:243], v[74:77]
	v_mfma_f32_16x16x32_bf16 v[90:93], v[192:195], v[232:235], v[90:93]
	v_mfma_f32_16x16x32_bf16 v[90:93], v[188:191], v[228:231], v[90:93]
	v_mfma_f32_16x16x32_bf16 v[106:109], v[188:191], v[220:223], v[106:109]
	v_mfma_f32_16x16x32_bf16 v[106:109], v[192:195], v[224:227], v[106:109]
	v_mfma_f32_16x16x32_bf16 v[122:125], v[192:195], v[216:219], v[122:125]
	v_mfma_f32_16x16x32_bf16 v[122:125], v[188:191], v[212:215], v[122:125]
	v_mfma_f32_16x16x32_bf16 v[118:121], v[196:199], v[212:215], v[118:121]
	v_mfma_f32_16x16x32_bf16 v[118:121], v[200:203], v[216:219], v[118:121]
	v_mfma_f32_16x16x32_bf16 v[102:105], v[200:203], v[224:227], v[102:105]
	v_mfma_f32_16x16x32_bf16 v[102:105], v[196:199], v[220:223], v[102:105]
	v_mfma_f32_16x16x32_bf16 v[86:89], v[196:199], v[228:231], v[86:89]
	v_mfma_f32_16x16x32_bf16 v[86:89], v[200:203], v[232:235], v[86:89]
	v_mfma_f32_16x16x32_bf16 v[70:73], v[200:203], v[240:243], v[70:73]
	v_mfma_f32_16x16x32_bf16 v[70:73], v[196:199], v[236:239], v[70:73]
	v_mfma_f32_16x16x32_bf16 v[66:69], v[204:207], v[236:239], v[66:69]
	v_mfma_f32_16x16x32_bf16 v[66:69], v[208:211], v[240:243], v[66:69]
	v_mfma_f32_16x16x32_bf16 v[82:85], v[208:211], v[232:235], v[82:85]
	v_mfma_f32_16x16x32_bf16 v[82:85], v[204:207], v[228:231], v[82:85]
	s_barrier
	s_setprio 2
	v_mfma_f32_16x16x32_bf16 v[98:101], v[204:207], v[220:223], v[98:101]
	v_mfma_f32_16x16x32_bf16 v[98:101], v[208:211], v[224:227], v[98:101]
	v_mfma_f32_16x16x32_bf16 v[114:117], v[208:211], v[216:219], v[114:117]
	v_mfma_f32_16x16x32_bf16 v[114:117], v[204:207], v[212:215], v[114:117]
	s_setprio 0
	s_add_i32 s71, s64, s52
	v_lshl_add_u64 v[244:245], s[76:77], 0, v[130:131]
	s_mov_b32 m0, s71
	ds_read_b128 v[212:215], v170 offset:16384
	ds_read_b128 v[216:219], v170 offset:17408
	ds_read_b128 v[220:223], v170 offset:18432
	ds_read_b128 v[224:227], v170 offset:19456
	ds_read_b128 v[228:231], v170 offset:20480
	ds_read_b128 v[232:235], v170 offset:21504
	ds_read_b128 v[236:239], v170 offset:22528
	ds_read_b128 v[240:243], v170 offset:23552
	global_load_lds_dwordx4 v[244:245], off
	v_lshl_add_u64 v[246:247], v[244:245], 0, s[0:1]
	s_add_i32 m0, s71, 0x2000
	s_add_i32 s71, s65, s52
	global_load_lds_dwordx4 v[246:247], off
	v_lshl_add_u64 v[246:247], v[244:245], 0, s[14:15]
	s_mov_b32 m0, s71
	s_nop 0
	global_load_lds_dwordx4 v[246:247], off
	v_lshl_add_u64 v[246:247], v[244:245], 0, s[18:19]
	s_add_i32 m0, s71, 0x2000
	s_nop 0
	global_load_lds_dwordx4 v[246:247], off
	v_lshl_add_u64 v[246:247], s[74:75], 0, v[130:131]
	s_mov_b32 m0, s53
	v_lshl_add_u64 v[248:249], v[246:247], 0, s[0:1]
	global_load_lds_dwordx4 v[246:247], off
	s_mov_b32 m0, s54
	s_nop 0
	global_load_lds_dwordx4 v[248:249], off
	s_waitcnt vmcnt(8)
	s_waitcnt lgkmcnt(0)
	s_barrier
; #define PG8_STAGE(bufoff, gbase, voff) do { if constexpr (!pg8_noload<Epi>::value) { _Pragma("unroll") for (int _i = 0; _i < 2; ++_i) \
;         __builtin_amdgcn_global_load_lds((const unsigned*)((const char*)(gbase) + (size_t)_i * pstep + (voff)[0]), (PG8_LAS unsigned*)(lds + (bufoff) + ldsw + _i * 8192), 16, 0, 0); } } while (0)
; #define PG8_LDA(dst, b, h) do { _Pragma("unroll") for (int m = 0; m < 4; ++m) _Pragma("unroll") for (int k = 0; k < 2; ++k) dst[m][k] = *(const PG8_LAS bf16x8*)(lds + PG8_SA(b, h) + aoff + m * 2048 + k * 1024); } while (0)
; #define PG8_LDB(dst, b, h) do { _Pragma("unroll") for (int n = 0; n < 2; ++n) _Pragma("unroll") for (int k = 0; k < 2; ++k) dst[n][k] = *(const PG8_LAS bf16x8*)(lds + PG8_SB(b, h) + boff + n * 2048 + k * 1024); } while (0)
; #define PG8_MMA(ai, bj, At, Bt) do { __builtin_amdgcn_s_setprio(1); _Pragma("unroll") for (int m = 0; m < 4; ++m) _Pragma("unroll") for (int n = 0; n < 2; ++n) _Pragma("unroll") for (int k = 0; k < 2; ++k) \
;         acc[ai][bj][m][n] = __builtin_amdgcn_mfma_f32_16x16x32_bf16(Bt[n][k], At[m][k], acc[ai][bj][m][n], 0, 0, 0); __builtin_amdgcn_s_setprio(0); } while (0)
; #define PG8_WAIT_V(n) asm volatile("s_waitcnt vmcnt(" #n ")" ::: "memory")
; #define PG8_WAIT_L(n) asm volatile("s_waitcnt lgkmcnt(" #n ")" ::: "memory")
; #define PG8_BAR __builtin_amdgcn_s_barrier()
; #define PG8_SCHED __builtin_amdgcn_sched_barrier(0)
; template <class Epi, class Sched, bool ALIGN_EPI = false, bool SP2 = false, bool ABLK = false>
; __device__ __forceinline__ void gemm_phase(PG8_LAS unsigned char* lds, const Gemm g, const Sched& S, const Epi& E) {
;     ...
;             PG8_LDB(B0, 0, 0); PG8_LDB(B1, 0, 1); PG8_SCHED; PG8_LDA(At, 0, 0); PG8_STAGE(PG8_SA(1, 1), a1 + hstep, voffA);
;             PG8_WAIT_V(8); PG8_WAIT_L(0); PG8_BAR; PG8_MMA(0, 0, At, B0); PG8_MMA(0, 1, At, B1); PG8_BAR; PG8_SCHED;
;             PG8_LDA(At, 0, 1); PG8_STAGE(PG8_SB(0, 0), b2, voffB); PG8_STAGE(PG8_SB(0, 1), b2 + hstep, voffB); PG8_STAGE(PG8_SA(0, 0), a2, voffA);
;             PG8_WAIT_V(8); PG8_WAIT_L(0); PG8_BAR; PG8_MMA(1, 0, At, B0); PG8_MMA(1, 1, At, B1); PG8_BAR; PG8_SCHED;
;             PG8_LDB(B0, 1, 0); PG8_LDB(B1, 1, 1); PG8_SCHED; PG8_LDA(At, 1, 0); PG8_STAGE(PG8_SA(0, 1), a2 + hstep, voffA);
	s_setprio 1
	s_waitcnt lgkmcnt(0)
	v_mfma_f32_16x16x32_bf16 v[62:65], v[144:147], v[212:215], v[62:65]
	v_mfma_f32_16x16x32_bf16 v[62:65], v[184:187], v[216:219], v[62:65]
	v_mfma_f32_16x16x32_bf16 v[46:49], v[184:187], v[224:227], v[46:49]
	v_mfma_f32_16x16x32_bf16 v[46:49], v[144:147], v[220:223], v[46:49]
	v_mfma_f32_16x16x32_bf16 v[30:33], v[144:147], v[228:231], v[30:33]
	v_mfma_f32_16x16x32_bf16 v[30:33], v[184:187], v[232:235], v[30:33]
	v_mfma_f32_16x16x32_bf16 v[14:17], v[184:187], v[240:243], v[14:17]
	v_mfma_f32_16x16x32_bf16 v[14:17], v[144:147], v[236:239], v[14:17]
	v_mfma_f32_16x16x32_bf16 v[10:13], v[188:191], v[236:239], v[10:13]
	v_mfma_f32_16x16x32_bf16 v[10:13], v[192:195], v[240:243], v[10:13]
	v_mfma_f32_16x16x32_bf16 v[26:29], v[192:195], v[232:235], v[26:29]
	v_mfma_f32_16x16x32_bf16 v[26:29], v[188:191], v[228:231], v[26:29]
	v_mfma_f32_16x16x32_bf16 v[42:45], v[188:191], v[220:223], v[42:45]
	v_mfma_f32_16x16x32_bf16 v[42:45], v[192:195], v[224:227], v[42:45]
	v_mfma_f32_16x16x32_bf16 v[58:61], v[192:195], v[216:219], v[58:61]
	v_mfma_f32_16x16x32_bf16 v[58:61], v[188:191], v[212:215], v[58:61]
	v_mfma_f32_16x16x32_bf16 v[54:57], v[196:199], v[212:215], v[54:57]
	v_mfma_f32_16x16x32_bf16 v[54:57], v[200:203], v[216:219], v[54:57]
	s_add_i32 s71, 0, 0x18000
	v_add_u32_e32 v133, s71, v149
	ds_read_b128 v[144:147], v133
	v_mfma_f32_16x16x32_bf16 v[38:41], v[200:203], v[224:227], v[38:41]
	v_mfma_f32_16x16x32_bf16 v[38:41], v[196:199], v[220:223], v[38:41]
	ds_read_b128 v[184:187], v133 offset:1024
	v_mfma_f32_16x16x32_bf16 v[22:25], v[196:199], v[228:231], v[22:25]
	v_mfma_f32_16x16x32_bf16 v[22:25], v[200:203], v[232:235], v[22:25]
	ds_read_b128 v[188:191], v133 offset:2048
	v_mfma_f32_16x16x32_bf16 v[6:9], v[200:203], v[240:243], v[6:9]
	v_mfma_f32_16x16x32_bf16 v[6:9], v[196:199], v[236:239], v[6:9]
	ds_read_b128 v[192:195], v133 offset:3072
	v_mfma_f32_16x16x32_bf16 v[2:5], v[204:207], v[236:239], v[2:5]
	v_mfma_f32_16x16x32_bf16 v[2:5], v[208:211], v[240:243], v[2:5]
	v_mfma_f32_16x16x32_bf16 v[18:21], v[208:211], v[232:235], v[18:21]
	v_mfma_f32_16x16x32_bf16 v[18:21], v[204:207], v[228:231], v[18:21]
	s_barrier
	s_setprio 2
	v_mfma_f32_16x16x32_bf16 v[34:37], v[204:207], v[220:223], v[34:37]
	v_mfma_f32_16x16x32_bf16 v[34:37], v[208:211], v[224:227], v[34:37]
	v_mfma_f32_16x16x32_bf16 v[50:53], v[208:211], v[216:219], v[50:53]
	v_mfma_f32_16x16x32_bf16 v[50:53], v[204:207], v[212:215], v[50:53]
	s_setprio 0
	s_add_i32 s73, 0, 0x1c000
	v_add_u32_e32 v133, s73, v149
	ds_read_b128 v[196:199], v133
	ds_read_b128 v[200:203], v133 offset:1024
	ds_read_b128 v[204:207], v133 offset:2048
	ds_read_b128 v[208:211], v133 offset:3072
	s_mov_b32 m0, s55
	v_lshl_add_u64 v[248:249], v[246:247], 0, s[14:15]
	ds_read_b128 v[212:215], v170 offset:32768
	ds_read_b128 v[216:219], v170 offset:33792
	ds_read_b128 v[220:223], v170 offset:34816
	ds_read_b128 v[224:227], v170 offset:35840
	ds_read_b128 v[228:231], v170 offset:36864
	ds_read_b128 v[232:235], v170 offset:37888
	ds_read_b128 v[236:239], v170 offset:38912
	ds_read_b128 v[240:243], v170 offset:39936
	global_load_lds_dwordx4 v[248:249], off
	v_lshl_add_u64 v[248:249], v[246:247], 0, s[18:19]
	s_mov_b32 m0, s56
	s_nop 0
	global_load_lds_dwordx4 v[248:249], off
	s_waitcnt vmcnt(8)
	s_waitcnt lgkmcnt(0)
	s_barrier
	s_setprio 1
	s_waitcnt lgkmcnt(0)
	v_mfma_f32_16x16x32_bf16 v[126:129], v[144:147], v[212:215], v[126:129]
	v_mfma_f32_16x16x32_bf16 v[126:129], v[184:187], v[216:219], v[126:129]
	v_mfma_f32_16x16x32_bf16 v[110:113], v[184:187], v[224:227], v[110:113]
	v_mfma_f32_16x16x32_bf16 v[110:113], v[144:147], v[220:223], v[110:113]
	v_mfma_f32_16x16x32_bf16 v[94:97], v[144:147], v[228:231], v[94:97]
	v_mfma_f32_16x16x32_bf16 v[94:97], v[184:187], v[232:235], v[94:97]
	v_mfma_f32_16x16x32_bf16 v[78:81], v[184:187], v[240:243], v[78:81]
	v_mfma_f32_16x16x32_bf16 v[78:81], v[144:147], v[236:239], v[78:81]
	v_mfma_f32_16x16x32_bf16 v[74:77], v[188:191], v[236:239], v[74:77]
	v_mfma_f32_16x16x32_bf16 v[74:77], v[192:195], v[240:243], v[74:77]
	v_mfma_f32_16x16x32_bf16 v[90:93], v[192:195], v[232:235], v[90:93]
	v_mfma_f32_16x16x32_bf16 v[90:93], v[188:191], v[228:231], v[90:93]
	v_mfma_f32_16x16x32_bf16 v[106:109], v[188:191], v[220:223], v[106:109]
	v_mfma_f32_16x16x32_bf16 v[106:109], v[192:195], v[224:227], v[106:109]
	v_mfma_f32_16x16x32_bf16 v[122:125], v[192:195], v[216:219], v[122:125]
	v_mfma_f32_16x16x32_bf16 v[122:125], v[188:191], v[212:215], v[122:125]
	v_mfma_f32_16x16x32_bf16 v[118:121], v[196:199], v[212:215], v[118:121]
	v_mfma_f32_16x16x32_bf16 v[118:121], v[200:203], v[216:219], v[118:121]
	v_mfma_f32_16x16x32_bf16 v[102:105], v[200:203], v[224:227], v[102:105]
	v_mfma_f32_16x16x32_bf16 v[102:105], v[196:199], v[220:223], v[102:105]
	v_mfma_f32_16x16x32_bf16 v[86:89], v[196:199], v[228:231], v[86:89]
	v_mfma_f32_16x16x32_bf16 v[86:89], v[200:203], v[232:235], v[86:89]
	v_mfma_f32_16x16x32_bf16 v[70:73], v[200:203], v[240:243], v[70:73]
	v_mfma_f32_16x16x32_bf16 v[70:73], v[196:199], v[236:239], v[70:73]
	v_mfma_f32_16x16x32_bf16 v[66:69], v[204:207], v[236:239], v[66:69]
	v_mfma_f32_16x16x32_bf16 v[66:69], v[208:211], v[240:243], v[66:69]
	v_mfma_f32_16x16x32_bf16 v[82:85], v[208:211], v[232:235], v[82:85]
	v_mfma_f32_16x16x32_bf16 v[82:85], v[204:207], v[228:231], v[82:85]
	s_barrier
; #define PG8_STAGE(bufoff, gbase, voff) do { if constexpr (!pg8_noload<Epi>::value) { _Pragma("unroll") for (int _i = 0; _i < 2; ++_i) \
;         __builtin_amdgcn_global_load_lds((const unsigned*)((const char*)(gbase) + (size_t)_i * pstep + (voff)[0]), (PG8_LAS unsigned*)(lds + (bufoff) + ldsw + _i * 8192), 16, 0, 0); } } while (0)
; #define PG8_LDA(dst, b, h) do { _Pragma("unroll") for (int m = 0; m < 4; ++m) _Pragma("unroll") for (int k = 0; k < 2; ++k) dst[m][k] = *(const PG8_LAS bf16x8*)(lds + PG8_SA(b, h) + aoff + m * 2048 + k * 1024); } while (0)
; #define PG8_MMA(ai, bj, At, Bt) do { __builtin_amdgcn_s_setprio(1); _Pragma("unroll") for (int m = 0; m < 4; ++m) _Pragma("unroll") for (int n = 0; n < 2; ++n) _Pragma("unroll") for (int k = 0; k < 2; ++k) \
;         acc[ai][bj][m][n] = __builtin_amdgcn_mfma_f32_16x16x32_bf16(Bt[n][k], At[m][k], acc[ai][bj][m][n], 0, 0, 0); __builtin_amdgcn_s_setprio(0); } while (0)
; #define PG8_WAIT_V(n) asm volatile("s_waitcnt vmcnt(" #n ")" ::: "memory")
; #define PG8_WAIT_L(n) asm volatile("s_waitcnt lgkmcnt(" #n ")" ::: "memory")
; #define PG8_BAR __builtin_amdgcn_s_barrier()
; #define PG8_SCHED __builtin_amdgcn_sched_barrier(0)
; template <class Epi, class Sched, bool ALIGN_EPI = false, bool SP2 = false, bool ABLK = false>
; __device__ __forceinline__ void gemm_phase(PG8_LAS unsigned char* lds, const Gemm g, const Sched& S, const Epi& E) {
;     ...
;             PG8_WAIT_V(8); PG8_WAIT_L(0); PG8_BAR; PG8_MMA(0, 0, At, B0); PG8_MMA(0, 1, At, B1); PG8_BAR; PG8_SCHED;
;             PG8_LDA(At, 1, 1); PG8_STAGE(PG8_SB(1, 0), b3, voffB); PG8_STAGE(PG8_SB(1, 1), b3 + hstep, voffB); PG8_STAGE(PG8_SA(1, 0), a3, voffA);
;             PG8_WAIT_V(8); PG8_WAIT_L(0); PG8_BAR; PG8_MMA(1, 0, At, B0); PG8_MMA(1, 1, At, B1); PG8_BAR; PG8_SCHED;
;     ...
;         if constexpr (ALIGN_EPI) { if (wr == 0) PG8_BAR; }
	s_setprio 2
	v_mfma_f32_16x16x32_bf16 v[98:101], v[204:207], v[220:223], v[98:101]
	v_mfma_f32_16x16x32_bf16 v[98:101], v[208:211], v[224:227], v[98:101]
	v_mfma_f32_16x16x32_bf16 v[114:117], v[208:211], v[216:219], v[114:117]
	v_mfma_f32_16x16x32_bf16 v[114:117], v[204:207], v[212:215], v[114:117]
	s_setprio 0
	s_add_i32 s71, s71, s52
	v_lshl_add_u64 v[248:249], v[244:245], 0, s[28:29]
	s_mov_b32 m0, s71
	ds_read_b128 v[212:215], v170 offset:49152
	ds_read_b128 v[216:219], v170 offset:50176
	ds_read_b128 v[220:223], v170 offset:51200
	ds_read_b128 v[224:227], v170 offset:52224
	ds_read_b128 v[228:231], v170 offset:53248
	ds_read_b128 v[232:235], v170 offset:54272
	ds_read_b128 v[236:239], v170 offset:55296
	ds_read_b128 v[240:243], v170 offset:56320
	global_load_lds_dwordx4 v[248:249], off
	v_lshl_add_u64 v[248:249], v[244:245], 0, s[30:31]
	s_add_i32 m0, s71, 0x2000
	s_add_i32 s71, s73, s52
	global_load_lds_dwordx4 v[248:249], off
	v_lshl_add_u64 v[248:249], v[244:245], 0, s[34:35]
	s_mov_b32 m0, s71
	v_lshl_add_u64 v[244:245], v[244:245], 0, s[36:37]
	global_load_lds_dwordx4 v[248:249], off
	s_add_i32 m0, s71, 0x2000
	s_nop 0
	global_load_lds_dwordx4 v[244:245], off
	v_lshl_add_u64 v[244:245], v[246:247], 0, s[28:29]
	s_mov_b32 m0, s59
	s_nop 0
	global_load_lds_dwordx4 v[244:245], off
	v_lshl_add_u64 v[244:245], v[246:247], 0, s[30:31]
	s_mov_b32 m0, s60
	s_nop 0
	global_load_lds_dwordx4 v[244:245], off
	s_waitcnt vmcnt(8)
	s_waitcnt lgkmcnt(0)
	s_barrier
	s_setprio 1
	s_waitcnt lgkmcnt(0)
	v_mfma_f32_16x16x32_bf16 v[62:65], v[144:147], v[212:215], v[62:65]
	v_mfma_f32_16x16x32_bf16 v[62:65], v[184:187], v[216:219], v[62:65]
	v_mfma_f32_16x16x32_bf16 v[46:49], v[184:187], v[224:227], v[46:49]
	v_mfma_f32_16x16x32_bf16 v[46:49], v[144:147], v[220:223], v[46:49]
	v_mfma_f32_16x16x32_bf16 v[30:33], v[144:147], v[228:231], v[30:33]
	v_mfma_f32_16x16x32_bf16 v[30:33], v[184:187], v[232:235], v[30:33]
	v_mfma_f32_16x16x32_bf16 v[14:17], v[184:187], v[240:243], v[14:17]
	v_mfma_f32_16x16x32_bf16 v[14:17], v[144:147], v[236:239], v[14:17]
	v_mfma_f32_16x16x32_bf16 v[10:13], v[188:191], v[236:239], v[10:13]
	v_mfma_f32_16x16x32_bf16 v[10:13], v[192:195], v[240:243], v[10:13]
	v_mfma_f32_16x16x32_bf16 v[26:29], v[192:195], v[232:235], v[26:29]
	v_mfma_f32_16x16x32_bf16 v[26:29], v[188:191], v[228:231], v[26:29]
	v_mfma_f32_16x16x32_bf16 v[42:45], v[188:191], v[220:223], v[42:45]
	v_mfma_f32_16x16x32_bf16 v[42:45], v[192:195], v[224:227], v[42:45]
	v_mfma_f32_16x16x32_bf16 v[58:61], v[192:195], v[216:219], v[58:61]
	v_mfma_f32_16x16x32_bf16 v[58:61], v[188:191], v[212:215], v[58:61]
	v_mfma_f32_16x16x32_bf16 v[54:57], v[196:199], v[212:215], v[54:57]
	v_mfma_f32_16x16x32_bf16 v[54:57], v[200:203], v[216:219], v[54:57]
	v_mfma_f32_16x16x32_bf16 v[38:41], v[200:203], v[224:227], v[38:41]
	v_mfma_f32_16x16x32_bf16 v[38:41], v[196:199], v[220:223], v[38:41]
	v_mfma_f32_16x16x32_bf16 v[22:25], v[196:199], v[228:231], v[22:25]
	v_mfma_f32_16x16x32_bf16 v[22:25], v[200:203], v[232:235], v[22:25]
	v_mfma_f32_16x16x32_bf16 v[6:9], v[200:203], v[240:243], v[6:9]
	v_mfma_f32_16x16x32_bf16 v[6:9], v[196:199], v[236:239], v[6:9]
	v_mfma_f32_16x16x32_bf16 v[2:5], v[204:207], v[236:239], v[2:5]
	v_mfma_f32_16x16x32_bf16 v[2:5], v[208:211], v[240:243], v[2:5]
	v_mfma_f32_16x16x32_bf16 v[18:21], v[208:211], v[232:235], v[18:21]
	v_mfma_f32_16x16x32_bf16 v[18:21], v[204:207], v[228:231], v[18:21]
	s_barrier
	s_setprio 2
	v_mfma_f32_16x16x32_bf16 v[34:37], v[204:207], v[220:223], v[34:37]
	v_mfma_f32_16x16x32_bf16 v[34:37], v[208:211], v[224:227], v[34:37]
	v_mfma_f32_16x16x32_bf16 v[50:53], v[208:211], v[216:219], v[50:53]
	v_mfma_f32_16x16x32_bf16 v[50:53], v[204:207], v[212:215], v[50:53]
	s_setprio 0
	s_add_i32 s70, s70, 2
	s_add_u32 vcc_lo, vcc_lo, 0x1000
	s_addc_u32 vcc_hi, vcc_hi, 0
	s_add_u32 s16, s16, 0x1000
	s_addc_u32 s17, s17, 0
	s_cmp_gt_u32 s70, 29
	s_cbranch_scc0 .LBB0_114
	s_and_b64 vcc, exec, s[38:39]
	s_cbranch_vccz .LBB0_117
	s_barrier

; #define PG8_STAGE(bufoff, gbase, voff) do { if constexpr (!pg8_noload<Epi>::value) { _Pragma("unroll") for (int _i = 0; _i < 2; ++_i) \
;         __builtin_amdgcn_global_load_lds((const unsigned*)((const char*)(gbase) + (size_t)_i * pstep + (voff)[0]), (PG8_LAS unsigned*)(lds + (bufoff) + ldsw + _i * 8192), 16, 0, 0); } } while (0)
; #define PG8_LDA(dst, b, h) do { _Pragma("unroll") for (int m = 0; m < 4; ++m) _Pragma("unroll") for (int k = 0; k < 2; ++k) dst[m][k] = *(const PG8_LAS bf16x8*)(lds + PG8_SA(b, h) + aoff + m * 2048 + k * 1024); } while (0)
; #define PG8_LDB(dst, b, h) do { _Pragma("unroll") for (int n = 0; n < 2; ++n) _Pragma("unroll") for (int k = 0; k < 2; ++k) dst[n][k] = *(const PG8_LAS bf16x8*)(lds + PG8_SB(b, h) + boff + n * 2048 + k * 1024); } while (0)
; #define PG8_MMA(ai, bj, At, Bt) do { __builtin_amdgcn_s_setprio(1); _Pragma("unroll") for (int m = 0; m < 4; ++m) _Pragma("unroll") for (int n = 0; n < 2; ++n) _Pragma("unroll") for (int k = 0; k < 2; ++k) \
;         acc[ai][bj][m][n] = __builtin_amdgcn_mfma_f32_16x16x32_bf16(Bt[n][k], At[m][k], acc[ai][bj][m][n], 0, 0, 0); __builtin_amdgcn_s_setprio(0); } while (0)
; #define PG8_WAIT_V(n) asm volatile("s_waitcnt vmcnt(" #n ")" ::: "memory")
; #define PG8_WAIT_L(n) asm volatile("s_waitcnt lgkmcnt(" #n ")" ::: "memory")
; #define PG8_BAR __builtin_amdgcn_s_barrier()
; template <class Epi, class Sched, bool ALIGN_EPI = false, bool SP2 = false, bool ABLK = false>
; __device__ __forceinline__ void gemm_phase(PG8_LAS unsigned char* lds, const Gemm g, const Sched& S, const Epi& E) {
;     ...
;             const bool last = (t == nt - 2);
;             const char* a1 = cA + (size_t)(t + 1) * kstep;
;             const char* a2 = last ? nA : cA + (size_t)(t + 2) * kstep; const char* b2 = last ? nB : cB + (size_t)(t + 2) * kstepB;
;             const char* a3 = a2 + kstep; const char* b3 = b2 + kstepB;
;             if (last && has_next) S.a_ready(nxt);
;             if constexpr (SP2) {
;             PG8_LDB(B0, 0, 0); PG8_LDB(B1, 0, 1); PG8_SCHED; PG8_LDA(At, 0, 0); PG8_STAGE(PG8_SA(1, 1), a1 + hstep, voffA);
;             PG8_WAIT_V(8); PG8_WAIT_L(0); PG8_BAR; PG8_MMA(0, 0, At, B0); PG8_MMA(0, 1, At, B1); PG8_BAR; PG8_SCHED;
;             PG8_LDA(At, 0, 1); PG8_STAGE(PG8_SB(0, 0), b2, voffB); PG8_STAGE(PG8_SB(0, 1), b2 + hstep, voffB); PG8_STAGE(PG8_SA(0, 0), a2, voffA);
.LBB0_487:
	ds_read_b128 v[114:117], v167
	ds_read_b128 v[126:129], v167 offset:1024
	ds_read_b128 v[130:133], v167 offset:2048
	ds_read_b128 v[142:145], v167 offset:3072
	ds_read_b128 v[146:149], v168
	ds_read_b128 v[150:153], v168 offset:1024
	ds_read_b128 v[174:177], v168 offset:2048
	ds_read_b128 v[178:181], v168 offset:3072
	s_add_i32 s65, s39, 2
	s_add_u32 s68, s92, 0xfff00800
	s_addc_u32 s69, s93, -1
	s_cmp_eq_u32 s3, s39
	s_cselect_b32 s69, s79, s69
	s_cselect_b32 s68, s78, s68
	s_cselect_b32 s71, s89, s37
	s_cselect_b32 s70, s88, s11
	v_lshl_add_u64 v[162:163], s[92:93], 0, v[158:159]
	s_add_i32 m0, s56, 0xc000
	ds_read_b128 v[184:187], v169
	ds_read_b128 v[188:191], v169 offset:1024
	ds_read_b128 v[192:195], v169 offset:2048
	ds_read_b128 v[196:199], v169 offset:3072
	ds_read_b128 v[200:203], v169 offset:4096
	ds_read_b128 v[204:207], v169 offset:5120
	ds_read_b128 v[208:211], v169 offset:6144
	ds_read_b128 v[212:215], v169 offset:7168
	global_load_lds_dwordx4 v[162:163], off
	v_lshl_add_u64 v[162:163], v[162:163], 0, s[12:13]
	s_add_i32 m0, s56, 0xe000
	s_nop 0
	global_load_lds_dwordx4 v[162:163], off
	s_waitcnt vmcnt(8)
	s_waitcnt lgkmcnt(0)
	s_barrier
	s_setprio 1
	s_waitcnt lgkmcnt(0)
	v_mfma_f32_16x16x32_bf16 v[138:141], v[114:117], v[184:187], v[138:141]
	v_mfma_f32_16x16x32_bf16 v[138:141], v[126:129], v[188:191], v[138:141]
	v_mfma_f32_16x16x32_bf16 v[110:113], v[126:129], v[196:199], v[110:113]
	v_mfma_f32_16x16x32_bf16 v[110:113], v[114:117], v[192:195], v[110:113]
	v_mfma_f32_16x16x32_bf16 v[94:97], v[114:117], v[200:203], v[94:97]
	v_mfma_f32_16x16x32_bf16 v[94:97], v[126:129], v[204:207], v[94:97]
	v_mfma_f32_16x16x32_bf16 v[78:81], v[126:129], v[212:215], v[78:81]
	v_mfma_f32_16x16x32_bf16 v[78:81], v[114:117], v[208:211], v[78:81]
	v_mfma_f32_16x16x32_bf16 v[74:77], v[130:133], v[208:211], v[74:77]
	v_mfma_f32_16x16x32_bf16 v[74:77], v[142:145], v[212:215], v[74:77]
	v_mfma_f32_16x16x32_bf16 v[90:93], v[142:145], v[204:207], v[90:93]
	v_mfma_f32_16x16x32_bf16 v[90:93], v[130:133], v[200:203], v[90:93]
	v_mfma_f32_16x16x32_bf16 v[106:109], v[130:133], v[192:195], v[106:109]
	v_mfma_f32_16x16x32_bf16 v[106:109], v[142:145], v[196:199], v[106:109]
	v_mfma_f32_16x16x32_bf16 v[134:137], v[142:145], v[188:191], v[134:137]
	v_mfma_f32_16x16x32_bf16 v[134:137], v[130:133], v[184:187], v[134:137]
	v_mfma_f32_16x16x32_bf16 v[122:125], v[146:149], v[184:187], v[122:125]
	v_mfma_f32_16x16x32_bf16 v[122:125], v[150:153], v[188:191], v[122:125]
	v_mfma_f32_16x16x32_bf16 v[102:105], v[150:153], v[196:199], v[102:105]
	v_mfma_f32_16x16x32_bf16 v[102:105], v[146:149], v[192:195], v[102:105]
	v_mfma_f32_16x16x32_bf16 v[86:89], v[146:149], v[200:203], v[86:89]
	v_mfma_f32_16x16x32_bf16 v[86:89], v[150:153], v[204:207], v[86:89]
	v_mfma_f32_16x16x32_bf16 v[70:73], v[150:153], v[212:215], v[70:73]
	v_mfma_f32_16x16x32_bf16 v[70:73], v[146:149], v[208:211], v[70:73]
	v_mfma_f32_16x16x32_bf16 v[66:69], v[174:177], v[208:211], v[66:69]
	v_mfma_f32_16x16x32_bf16 v[66:69], v[178:181], v[212:215], v[66:69]
	v_mfma_f32_16x16x32_bf16 v[82:85], v[178:181], v[204:207], v[82:85]
	v_mfma_f32_16x16x32_bf16 v[82:85], v[174:177], v[200:203], v[82:85]
	s_barrier
	s_setprio 2
	v_mfma_f32_16x16x32_bf16 v[98:101], v[174:177], v[192:195], v[98:101]
	v_mfma_f32_16x16x32_bf16 v[98:101], v[178:181], v[196:199], v[98:101]
	v_mfma_f32_16x16x32_bf16 v[118:121], v[178:181], v[188:191], v[118:121]
	v_mfma_f32_16x16x32_bf16 v[118:121], v[174:177], v[184:187], v[118:121]
	s_setprio 0
	s_add_i32 s39, s73, s55
	v_lshl_add_u64 v[162:163], s[70:71], 0, v[154:155]
	s_mov_b32 m0, s39
	ds_read_b128 v[184:187], v169 offset:16384
	ds_read_b128 v[188:191], v169 offset:17408
	ds_read_b128 v[192:195], v169 offset:18432
	ds_read_b128 v[196:199], v169 offset:19456
	ds_read_b128 v[200:203], v169 offset:20480
	ds_read_b128 v[204:207], v169 offset:21504
	ds_read_b128 v[208:211], v169 offset:22528
	ds_read_b128 v[212:215], v169 offset:23552
	global_load_lds_dwordx4 v[162:163], off
	v_lshl_add_u64 v[216:217], v[162:163], 0, s[12:13]
	s_add_i32 m0, s39, 0x2000
	s_add_i32 s39, s74, s55
	global_load_lds_dwordx4 v[216:217], off
	v_lshl_add_u64 v[216:217], v[162:163], 0, s[14:15]
	s_mov_b32 m0, s39
	s_nop 0
	global_load_lds_dwordx4 v[216:217], off
	v_lshl_add_u64 v[216:217], v[162:163], 0, s[16:17]
	s_add_i32 m0, s39, 0x2000
	s_nop 0
	global_load_lds_dwordx4 v[216:217], off
	v_lshl_add_u64 v[216:217], s[68:69], 0, v[154:155]
	s_mov_b32 m0, s56
	v_lshl_add_u64 v[218:219], v[216:217], 0, s[12:13]
	global_load_lds_dwordx4 v[216:217], off
	s_mov_b32 m0, s57
	s_nop 0
	global_load_lds_dwordx4 v[218:219], off
	s_waitcnt vmcnt(8)
	s_waitcnt lgkmcnt(0)
	s_barrier
; #define PG8_STAGE(bufoff, gbase, voff) do { if constexpr (!pg8_noload<Epi>::value) { _Pragma("unroll") for (int _i = 0; _i < 2; ++_i) \
;         __builtin_amdgcn_global_load_lds((const unsigned*)((const char*)(gbase) + (size_t)_i * pstep + (voff)[0]), (PG8_LAS unsigned*)(lds + (bufoff) + ldsw + _i * 8192), 16, 0, 0); } } while (0)
; #define PG8_LDA(dst, b, h) do { _Pragma("unroll") for (int m = 0; m < 4; ++m) _Pragma("unroll") for (int k = 0; k < 2; ++k) dst[m][k] = *(const PG8_LAS bf16x8*)(lds + PG8_SA(b, h) + aoff + m * 2048 + k * 1024); } while (0)
; #define PG8_LDB(dst, b, h) do { _Pragma("unroll") for (int n = 0; n < 2; ++n) _Pragma("unroll") for (int k = 0; k < 2; ++k) dst[n][k] = *(const PG8_LAS bf16x8*)(lds + PG8_SB(b, h) + boff + n * 2048 + k * 1024); } while (0)
; #define PG8_MMA(ai, bj, At, Bt) do { __builtin_amdgcn_s_setprio(1); _Pragma("unroll") for (int m = 0; m < 4; ++m) _Pragma("unroll") for (int n = 0; n < 2; ++n) _Pragma("unroll") for (int k = 0; k < 2; ++k) \
;         acc[ai][bj][m][n] = __builtin_amdgcn_mfma_f32_16x16x32_bf16(Bt[n][k], At[m][k], acc[ai][bj][m][n], 0, 0, 0); __builtin_amdgcn_s_setprio(0); } while (0)
; #define PG8_WAIT_V(n) asm volatile("s_waitcnt vmcnt(" #n ")" ::: "memory")
; #define PG8_WAIT_L(n) asm volatile("s_waitcnt lgkmcnt(" #n ")" ::: "memory")
; #define PG8_BAR __builtin_amdgcn_s_barrier()
; #define PG8_SCHED __builtin_amdgcn_sched_barrier(0)
; template <class Epi, class Sched, bool ALIGN_EPI = false, bool SP2 = false, bool ABLK = false>
; __device__ __forceinline__ void gemm_phase(PG8_LAS unsigned char* lds, const Gemm g, const Sched& S, const Epi& E) {
;     ...
;             PG8_WAIT_V(8); PG8_WAIT_L(0); PG8_BAR; PG8_MMA(1, 0, At, B0); PG8_MMA(1, 1, At, B1); PG8_BAR; PG8_SCHED;
;             PG8_LDB(B0, 1, 0); PG8_LDB(B1, 1, 1); PG8_SCHED; PG8_LDA(At, 1, 0); PG8_STAGE(PG8_SA(0, 1), a2 + hstep, voffA);
;             PG8_WAIT_V(8); PG8_WAIT_L(0); PG8_BAR; PG8_MMA(0, 0, At, B0); PG8_MMA(0, 1, At, B1); PG8_BAR; PG8_SCHED;
	s_setprio 1
	s_waitcnt lgkmcnt(0)
	v_mfma_f32_16x16x32_bf16 v[62:65], v[114:117], v[184:187], v[62:65]
	v_mfma_f32_16x16x32_bf16 v[62:65], v[126:129], v[188:191], v[62:65]
	v_mfma_f32_16x16x32_bf16 v[46:49], v[126:129], v[196:199], v[46:49]
	v_mfma_f32_16x16x32_bf16 v[46:49], v[114:117], v[192:195], v[46:49]
	v_mfma_f32_16x16x32_bf16 v[30:33], v[114:117], v[200:203], v[30:33]
	v_mfma_f32_16x16x32_bf16 v[30:33], v[126:129], v[204:207], v[30:33]
	v_mfma_f32_16x16x32_bf16 v[14:17], v[126:129], v[212:215], v[14:17]
	v_mfma_f32_16x16x32_bf16 v[14:17], v[114:117], v[208:211], v[14:17]
	v_mfma_f32_16x16x32_bf16 v[10:13], v[130:133], v[208:211], v[10:13]
	v_mfma_f32_16x16x32_bf16 v[10:13], v[142:145], v[212:215], v[10:13]
	v_mfma_f32_16x16x32_bf16 v[26:29], v[142:145], v[204:207], v[26:29]
	v_mfma_f32_16x16x32_bf16 v[26:29], v[130:133], v[200:203], v[26:29]
	v_mfma_f32_16x16x32_bf16 v[42:45], v[130:133], v[192:195], v[42:45]
	v_mfma_f32_16x16x32_bf16 v[42:45], v[142:145], v[196:199], v[42:45]
	v_mfma_f32_16x16x32_bf16 v[58:61], v[142:145], v[188:191], v[58:61]
	v_mfma_f32_16x16x32_bf16 v[58:61], v[130:133], v[184:187], v[58:61]
	v_mfma_f32_16x16x32_bf16 v[54:57], v[146:149], v[184:187], v[54:57]
	v_mfma_f32_16x16x32_bf16 v[54:57], v[150:153], v[188:191], v[54:57]
	s_add_i32 s39, 0, 0x18000
	v_add_u32_e32 v142, s39, v1
	ds_read_b128 v[114:117], v142
	v_mfma_f32_16x16x32_bf16 v[38:41], v[150:153], v[196:199], v[38:41]
	v_mfma_f32_16x16x32_bf16 v[38:41], v[146:149], v[192:195], v[38:41]
	ds_read_b128 v[126:129], v142 offset:1024
	v_mfma_f32_16x16x32_bf16 v[22:25], v[146:149], v[200:203], v[22:25]
	v_mfma_f32_16x16x32_bf16 v[22:25], v[150:153], v[204:207], v[22:25]
	ds_read_b128 v[130:133], v142 offset:2048
	v_mfma_f32_16x16x32_bf16 v[6:9], v[150:153], v[212:215], v[6:9]
	v_mfma_f32_16x16x32_bf16 v[6:9], v[146:149], v[208:211], v[6:9]
	ds_read_b128 v[142:145], v142 offset:3072
	v_mfma_f32_16x16x32_bf16 v[2:5], v[174:177], v[208:211], v[2:5]
	v_mfma_f32_16x16x32_bf16 v[2:5], v[178:181], v[212:215], v[2:5]
	v_mfma_f32_16x16x32_bf16 v[18:21], v[178:181], v[204:207], v[18:21]
	v_mfma_f32_16x16x32_bf16 v[18:21], v[174:177], v[200:203], v[18:21]
	s_barrier
	s_setprio 2
	v_mfma_f32_16x16x32_bf16 v[34:37], v[174:177], v[192:195], v[34:37]
	v_mfma_f32_16x16x32_bf16 v[34:37], v[178:181], v[196:199], v[34:37]
	v_mfma_f32_16x16x32_bf16 v[50:53], v[178:181], v[188:191], v[50:53]
	v_mfma_f32_16x16x32_bf16 v[50:53], v[174:177], v[184:187], v[50:53]
	s_setprio 0
	s_add_i32 s68, 0, 0x1c000
	v_add_u32_e32 v173, s68, v1
	ds_read_b128 v[146:149], v173
	ds_read_b128 v[150:153], v173 offset:1024
	ds_read_b128 v[174:177], v173 offset:2048
	ds_read_b128 v[178:181], v173 offset:3072
	s_mov_b32 m0, s58
	v_lshl_add_u64 v[218:219], v[216:217], 0, s[14:15]
	ds_read_b128 v[184:187], v169 offset:32768
	ds_read_b128 v[188:191], v169 offset:33792
	ds_read_b128 v[192:195], v169 offset:34816
	ds_read_b128 v[196:199], v169 offset:35840
	ds_read_b128 v[200:203], v169 offset:36864
	ds_read_b128 v[204:207], v169 offset:37888
	ds_read_b128 v[208:211], v169 offset:38912
	ds_read_b128 v[212:215], v169 offset:39936
	global_load_lds_dwordx4 v[218:219], off
	v_lshl_add_u64 v[218:219], v[216:217], 0, s[16:17]
	s_mov_b32 m0, s59
	s_nop 0
	global_load_lds_dwordx4 v[218:219], off
	s_waitcnt vmcnt(8)
	s_waitcnt lgkmcnt(0)
	s_barrier
	s_setprio 1
	s_waitcnt lgkmcnt(0)
	v_mfma_f32_16x16x32_bf16 v[138:141], v[114:117], v[184:187], v[138:141]
	v_mfma_f32_16x16x32_bf16 v[138:141], v[126:129], v[188:191], v[138:141]
	v_mfma_f32_16x16x32_bf16 v[110:113], v[126:129], v[196:199], v[110:113]
	v_mfma_f32_16x16x32_bf16 v[110:113], v[114:117], v[192:195], v[110:113]
	v_mfma_f32_16x16x32_bf16 v[94:97], v[114:117], v[200:203], v[94:97]
	v_mfma_f32_16x16x32_bf16 v[94:97], v[126:129], v[204:207], v[94:97]
	v_mfma_f32_16x16x32_bf16 v[78:81], v[126:129], v[212:215], v[78:81]
	v_mfma_f32_16x16x32_bf16 v[78:81], v[114:117], v[208:211], v[78:81]
	v_mfma_f32_16x16x32_bf16 v[74:77], v[130:133], v[208:211], v[74:77]
	v_mfma_f32_16x16x32_bf16 v[74:77], v[142:145], v[212:215], v[74:77]
	v_mfma_f32_16x16x32_bf16 v[90:93], v[142:145], v[204:207], v[90:93]
	v_mfma_f32_16x16x32_bf16 v[90:93], v[130:133], v[200:203], v[90:93]
	v_mfma_f32_16x16x32_bf16 v[106:109], v[130:133], v[192:195], v[106:109]
	v_mfma_f32_16x16x32_bf16 v[106:109], v[142:145], v[196:199], v[106:109]
	v_mfma_f32_16x16x32_bf16 v[134:137], v[142:145], v[188:191], v[134:137]
	v_mfma_f32_16x16x32_bf16 v[134:137], v[130:133], v[184:187], v[134:137]
	v_mfma_f32_16x16x32_bf16 v[122:125], v[146:149], v[184:187], v[122:125]
	v_mfma_f32_16x16x32_bf16 v[122:125], v[150:153], v[188:191], v[122:125]
	v_mfma_f32_16x16x32_bf16 v[102:105], v[150:153], v[196:199], v[102:105]
	v_mfma_f32_16x16x32_bf16 v[102:105], v[146:149], v[192:195], v[102:105]
	v_mfma_f32_16x16x32_bf16 v[86:89], v[146:149], v[200:203], v[86:89]
	v_mfma_f32_16x16x32_bf16 v[86:89], v[150:153], v[204:207], v[86:89]
	v_mfma_f32_16x16x32_bf16 v[70:73], v[150:153], v[212:215], v[70:73]
	v_mfma_f32_16x16x32_bf16 v[70:73], v[146:149], v[208:211], v[70:73]
	v_mfma_f32_16x16x32_bf16 v[66:69], v[174:177], v[208:211], v[66:69]
	v_mfma_f32_16x16x32_bf16 v[66:69], v[178:181], v[212:215], v[66:69]
	v_mfma_f32_16x16x32_bf16 v[82:85], v[178:181], v[204:207], v[82:85]
	v_mfma_f32_16x16x32_bf16 v[82:85], v[174:177], v[200:203], v[82:85]
	s_barrier
; #define PG8_STAGE(bufoff, gbase, voff) do { if constexpr (!pg8_noload<Epi>::value) { _Pragma("unroll") for (int _i = 0; _i < 2; ++_i) \
;         __builtin_amdgcn_global_load_lds((const unsigned*)((const char*)(gbase) + (size_t)_i * pstep + (voff)[0]), (PG8_LAS unsigned*)(lds + (bufoff) + ldsw + _i * 8192), 16, 0, 0); } } while (0)
; #define PG8_LDA(dst, b, h) do { _Pragma("unroll") for (int m = 0; m < 4; ++m) _Pragma("unroll") for (int k = 0; k < 2; ++k) dst[m][k] = *(const PG8_LAS bf16x8*)(lds + PG8_SA(b, h) + aoff + m * 2048 + k * 1024); } while (0)
; #define PG8_MMA(ai, bj, At, Bt) do { __builtin_amdgcn_s_setprio(1); _Pragma("unroll") for (int m = 0; m < 4; ++m) _Pragma("unroll") for (int n = 0; n < 2; ++n) _Pragma("unroll") for (int k = 0; k < 2; ++k) \
;         acc[ai][bj][m][n] = __builtin_amdgcn_mfma_f32_16x16x32_bf16(Bt[n][k], At[m][k], acc[ai][bj][m][n], 0, 0, 0); __builtin_amdgcn_s_setprio(0); } while (0)
; #define PG8_WAIT_V(n) asm volatile("s_waitcnt vmcnt(" #n ")" ::: "memory")
; #define PG8_WAIT_L(n) asm volatile("s_waitcnt lgkmcnt(" #n ")" ::: "memory")
; #define PG8_BAR __builtin_amdgcn_s_barrier()
; #define PG8_SCHED __builtin_amdgcn_sched_barrier(0)
;     __device__ __forceinline__ void operator()(const f32x4 (&acc)[2][2][4][2], const Unit& u, int wr, int wc, int fr, int fq) const {
;     ...
;         if (u.pm * BM < seq) {
; template <class Epi, class Sched, bool ALIGN_EPI = false, bool SP2 = false, bool ABLK = false>
; __device__ __forceinline__ void gemm_phase(PG8_LAS unsigned char* lds, const Gemm g, const Sched& S, const Epi& E) {
;     ...
;             PG8_WAIT_V(8); PG8_WAIT_L(0); PG8_BAR; PG8_MMA(0, 0, At, B0); PG8_MMA(0, 1, At, B1); PG8_BAR; PG8_SCHED;
;             PG8_LDA(At, 1, 1); PG8_STAGE(PG8_SB(1, 0), b3, voffB); PG8_STAGE(PG8_SB(1, 1), b3 + hstep, voffB); PG8_STAGE(PG8_SA(1, 0), a3, voffA);
;             PG8_WAIT_V(8); PG8_WAIT_L(0); PG8_BAR; PG8_MMA(1, 0, At, B0); PG8_MMA(1, 1, At, B1); PG8_BAR; PG8_SCHED;
	s_setprio 2
	v_mfma_f32_16x16x32_bf16 v[98:101], v[174:177], v[192:195], v[98:101]
	v_mfma_f32_16x16x32_bf16 v[98:101], v[178:181], v[196:199], v[98:101]
	v_mfma_f32_16x16x32_bf16 v[118:121], v[178:181], v[188:191], v[118:121]
	v_mfma_f32_16x16x32_bf16 v[118:121], v[174:177], v[184:187], v[118:121]
	s_setprio 0
	s_add_i32 s39, s39, s55
	v_lshl_add_u64 v[218:219], v[162:163], 0, s[24:25]
	s_mov_b32 m0, s39
	ds_read_b128 v[184:187], v169 offset:49152
	ds_read_b128 v[188:191], v169 offset:50176
	ds_read_b128 v[192:195], v169 offset:51200
	ds_read_b128 v[196:199], v169 offset:52224
	ds_read_b128 v[200:203], v169 offset:53248
	ds_read_b128 v[204:207], v169 offset:54272
	ds_read_b128 v[208:211], v169 offset:55296
	ds_read_b128 v[212:215], v169 offset:56320
	global_load_lds_dwordx4 v[218:219], off
	v_lshl_add_u64 v[218:219], v[162:163], 0, s[26:27]
	s_add_i32 m0, s39, 0x2000
	s_add_i32 s39, s68, s55
	global_load_lds_dwordx4 v[218:219], off
	v_lshl_add_u64 v[218:219], v[162:163], 0, s[28:29]
	s_mov_b32 m0, s39
	v_lshl_add_u64 v[162:163], v[162:163], 0, s[30:31]
	global_load_lds_dwordx4 v[218:219], off
	s_add_i32 m0, s39, 0x2000
	s_nop 0
	global_load_lds_dwordx4 v[162:163], off
	v_lshl_add_u64 v[162:163], v[216:217], 0, s[24:25]
	s_mov_b32 m0, s62
	s_nop 0
	global_load_lds_dwordx4 v[162:163], off
	v_lshl_add_u64 v[162:163], v[216:217], 0, s[26:27]
	s_mov_b32 m0, s63
	s_nop 0
	global_load_lds_dwordx4 v[162:163], off
	s_waitcnt vmcnt(8)
	s_waitcnt lgkmcnt(0)
	s_barrier
	s_setprio 1
	s_waitcnt lgkmcnt(0)
	v_mfma_f32_16x16x32_bf16 v[62:65], v[114:117], v[184:187], v[62:65]
	v_mfma_f32_16x16x32_bf16 v[62:65], v[126:129], v[188:191], v[62:65]
	v_mfma_f32_16x16x32_bf16 v[46:49], v[126:129], v[196:199], v[46:49]
	v_mfma_f32_16x16x32_bf16 v[46:49], v[114:117], v[192:195], v[46:49]
	v_mfma_f32_16x16x32_bf16 v[30:33], v[114:117], v[200:203], v[30:33]
	v_mfma_f32_16x16x32_bf16 v[30:33], v[126:129], v[204:207], v[30:33]
	v_mfma_f32_16x16x32_bf16 v[14:17], v[126:129], v[212:215], v[14:17]
	v_mfma_f32_16x16x32_bf16 v[14:17], v[114:117], v[208:211], v[14:17]
	v_mfma_f32_16x16x32_bf16 v[10:13], v[130:133], v[208:211], v[10:13]
	v_mfma_f32_16x16x32_bf16 v[10:13], v[142:145], v[212:215], v[10:13]
	v_mfma_f32_16x16x32_bf16 v[26:29], v[142:145], v[204:207], v[26:29]
	v_mfma_f32_16x16x32_bf16 v[26:29], v[130:133], v[200:203], v[26:29]
	v_mfma_f32_16x16x32_bf16 v[42:45], v[130:133], v[192:195], v[42:45]
	v_mfma_f32_16x16x32_bf16 v[42:45], v[142:145], v[196:199], v[42:45]
	v_mfma_f32_16x16x32_bf16 v[58:61], v[142:145], v[188:191], v[58:61]
	v_mfma_f32_16x16x32_bf16 v[58:61], v[130:133], v[184:187], v[58:61]
	v_mfma_f32_16x16x32_bf16 v[54:57], v[146:149], v[184:187], v[54:57]
	v_mfma_f32_16x16x32_bf16 v[54:57], v[150:153], v[188:191], v[54:57]
	v_mfma_f32_16x16x32_bf16 v[38:41], v[150:153], v[196:199], v[38:41]
	v_mfma_f32_16x16x32_bf16 v[38:41], v[146:149], v[192:195], v[38:41]
	v_mfma_f32_16x16x32_bf16 v[22:25], v[146:149], v[200:203], v[22:25]
	v_mfma_f32_16x16x32_bf16 v[22:25], v[150:153], v[204:207], v[22:25]
	v_mfma_f32_16x16x32_bf16 v[6:9], v[150:153], v[212:215], v[6:9]
	v_mfma_f32_16x16x32_bf16 v[6:9], v[146:149], v[208:211], v[6:9]
	v_mfma_f32_16x16x32_bf16 v[2:5], v[174:177], v[208:211], v[2:5]
	v_mfma_f32_16x16x32_bf16 v[2:5], v[178:181], v[212:215], v[2:5]
	v_mfma_f32_16x16x32_bf16 v[18:21], v[178:181], v[204:207], v[18:21]
	v_mfma_f32_16x16x32_bf16 v[18:21], v[174:177], v[200:203], v[18:21]
	s_barrier
	s_setprio 2
	v_mfma_f32_16x16x32_bf16 v[34:37], v[174:177], v[192:195], v[34:37]
	v_mfma_f32_16x16x32_bf16 v[34:37], v[178:181], v[196:199], v[34:37]
	v_mfma_f32_16x16x32_bf16 v[50:53], v[178:181], v[188:191], v[50:53]
	v_mfma_f32_16x16x32_bf16 v[50:53], v[174:177], v[184:187], v[50:53]
	s_setprio 0
	s_add_u32 s92, s92, 0x1000
	s_addc_u32 s93, s93, 0
	s_add_u32 s11, s11, 0x1000
	s_addc_u32 s37, s37, 0
	s_cmp_ge_i32 s65, s80
	s_mov_b32 s39, s65
	s_cbranch_scc0 .LBB0_487
	s_and_b64 vcc, exec, s[34:35]
	s_cbranch_vccnz .LBB0_492
	s_lshl_b32 s11, s2, 8
	s_cmp_gt_i32 s2, 63
	s_mov_b64 s[68:69], -1
	s_cbranch_scc1 .LBB0_493

; #define PG8_STAGE(bufoff, gbase, voff) do { if constexpr (!pg8_noload<Epi>::value) { _Pragma("unroll") for (int _i = 0; _i < 2; ++_i) \
;         __builtin_amdgcn_global_load_lds((const unsigned*)((const char*)(gbase) + (size_t)_i * pstep + (voff)[0]), (PG8_LAS unsigned*)(lds + (bufoff) + ldsw + _i * 8192), 16, 0, 0); } } while (0)
; #define PG8_LDA(dst, b, h) do { _Pragma("unroll") for (int m = 0; m < 4; ++m) _Pragma("unroll") for (int k = 0; k < 2; ++k) dst[m][k] = *(const PG8_LAS bf16x8*)(lds + PG8_SA(b, h) + aoff + m * 2048 + k * 1024); } while (0)
; #define PG8_LDB(dst, b, h) do { _Pragma("unroll") for (int n = 0; n < 2; ++n) _Pragma("unroll") for (int k = 0; k < 2; ++k) dst[n][k] = *(const PG8_LAS bf16x8*)(lds + PG8_SB(b, h) + boff + n * 2048 + k * 1024); } while (0)
; #define PG8_MMA(ai, bj, At, Bt) do { __builtin_amdgcn_s_setprio(1); _Pragma("unroll") for (int m = 0; m < 4; ++m) _Pragma("unroll") for (int n = 0; n < 2; ++n) _Pragma("unroll") for (int k = 0; k < 2; ++k) \
;         acc[ai][bj][m][n] = __builtin_amdgcn_mfma_f32_16x16x32_bf16(Bt[n][k], At[m][k], acc[ai][bj][m][n], 0, 0, 0); __builtin_amdgcn_s_setprio(0); } while (0)
; #define PG8_WAIT_V(n) asm volatile("s_waitcnt vmcnt(" #n ")" ::: "memory")
; #define PG8_WAIT_L(n) asm volatile("s_waitcnt lgkmcnt(" #n ")" ::: "memory")
; #define PG8_BAR __builtin_amdgcn_s_barrier()
; #define PG8_SCHED __builtin_amdgcn_sched_barrier(0)
; template <class Epi, class Sched, bool ALIGN_EPI = false, bool SP2 = false, bool ABLK = false>
; __device__ __forceinline__ void gemm_phase(PG8_LAS unsigned char* lds, const Gemm g, const Sched& S, const Epi& E) {
;     ...
;             const char* a1 = cA + (size_t)(t + 1) * kstep;
;             const char* a2 = last ? nA : cA + (size_t)(t + 2) * kstep; const char* b2 = last ? nB : cB + (size_t)(t + 2) * kstepB;
;             const char* a3 = a2 + kstep; const char* b3 = b2 + kstepB;
;             if (last && has_next) S.a_ready(nxt);
;             if constexpr (SP2) {
;             PG8_LDB(B0, 0, 0); PG8_LDB(B1, 0, 1); PG8_SCHED; PG8_LDA(At, 0, 0); PG8_STAGE(PG8_SA(1, 1), a1 + hstep, voffA);
;             PG8_WAIT_V(8); PG8_WAIT_L(0); PG8_BAR; PG8_MMA(0, 0, At, B0); PG8_MMA(0, 1, At, B1); PG8_BAR; PG8_SCHED;
;             PG8_LDA(At, 0, 1); PG8_STAGE(PG8_SB(0, 0), b2, voffB); PG8_STAGE(PG8_SB(0, 1), b2 + hstep, voffB); PG8_STAGE(PG8_SA(0, 0), a2, voffA);
.LBB0_619:
	s_or_b32 s28, s57, 1
	s_lshl_b64 s[58:59], s[28:29], 11
	s_add_u32 s58, s2, s58
	s_addc_u32 s59, s3, s59
	s_add_i32 s28, s57, 2
	v_add_u32_e32 v160, s78, v168
	v_add_u32_e32 v180, s79, v168
	s_lshl_b64 s[60:61], s[28:29], 11
	ds_read_b128 v[130:133], v160
	ds_read_b128 v[134:137], v160 offset:1024
	ds_read_b128 v[156:159], v160 offset:2048
	ds_read_b128 v[160:163], v160 offset:3072
	ds_read_b128 v[164:167], v180
	ds_read_b128 v[176:179], v180 offset:1024
	ds_read_b128 v[184:187], v180 offset:2048
	ds_read_b128 v[188:191], v180 offset:3072
	s_add_u32 s66, s2, s60
	s_addc_u32 s67, s3, s61
	s_and_b64 s[62:63], s[68:69], exec
	s_cselect_b32 s73, s67, s7
	s_cselect_b32 s72, s66, s15
	s_add_u32 s62, s16, s60
	s_addc_u32 s63, s17, s61
	s_and_b64 s[60:61], s[68:69], exec
	s_cselect_b32 s61, s63, s9
	s_cselect_b32 s60, s62, s56
	v_lshl_add_u64 v[180:181], s[58:59], 0, v[138:139]
	v_lshl_add_u64 v[224:225], v[180:181], 0, s[24:25]
	s_add_i32 m0, s70, 0xc000
	ds_read_b128 v[192:195], v173
	ds_read_b128 v[196:199], v173 offset:1024
	ds_read_b128 v[200:203], v173 offset:2048
	ds_read_b128 v[204:207], v173 offset:3072
	ds_read_b128 v[208:211], v173 offset:4096
	ds_read_b128 v[212:215], v173 offset:5120
	ds_read_b128 v[216:219], v173 offset:6144
	ds_read_b128 v[220:223], v173 offset:7168
	global_load_lds_dwordx4 v[224:225], off
	v_lshl_add_u64 v[180:181], v[180:181], 0, s[26:27]
	s_add_i32 m0, s70, 0xe000
	s_nop 0
	global_load_lds_dwordx4 v[180:181], off
	s_waitcnt vmcnt(8)
	s_waitcnt lgkmcnt(0)
	s_barrier
	s_setprio 1
	s_waitcnt lgkmcnt(0)
	v_mfma_f32_16x16x32_bf16 v[126:129], v[130:133], v[192:195], v[126:129]
	v_mfma_f32_16x16x32_bf16 v[126:129], v[134:137], v[196:199], v[126:129]
	v_mfma_f32_16x16x32_bf16 v[110:113], v[134:137], v[204:207], v[110:113]
	v_mfma_f32_16x16x32_bf16 v[110:113], v[130:133], v[200:203], v[110:113]
	v_mfma_f32_16x16x32_bf16 v[94:97], v[130:133], v[208:211], v[94:97]
	v_mfma_f32_16x16x32_bf16 v[94:97], v[134:137], v[212:215], v[94:97]
	v_mfma_f32_16x16x32_bf16 v[78:81], v[134:137], v[220:223], v[78:81]
	v_mfma_f32_16x16x32_bf16 v[78:81], v[130:133], v[216:219], v[78:81]
	v_mfma_f32_16x16x32_bf16 v[74:77], v[156:159], v[216:219], v[74:77]
	v_mfma_f32_16x16x32_bf16 v[74:77], v[160:163], v[220:223], v[74:77]
	v_mfma_f32_16x16x32_bf16 v[90:93], v[160:163], v[212:215], v[90:93]
	v_mfma_f32_16x16x32_bf16 v[90:93], v[156:159], v[208:211], v[90:93]
	v_mfma_f32_16x16x32_bf16 v[106:109], v[156:159], v[200:203], v[106:109]
	v_mfma_f32_16x16x32_bf16 v[106:109], v[160:163], v[204:207], v[106:109]
	v_mfma_f32_16x16x32_bf16 v[122:125], v[160:163], v[196:199], v[122:125]
	v_mfma_f32_16x16x32_bf16 v[122:125], v[156:159], v[192:195], v[122:125]
	v_mfma_f32_16x16x32_bf16 v[118:121], v[164:167], v[192:195], v[118:121]
	v_mfma_f32_16x16x32_bf16 v[118:121], v[176:179], v[196:199], v[118:121]
	v_mfma_f32_16x16x32_bf16 v[102:105], v[176:179], v[204:207], v[102:105]
	v_mfma_f32_16x16x32_bf16 v[102:105], v[164:167], v[200:203], v[102:105]
	v_mfma_f32_16x16x32_bf16 v[86:89], v[164:167], v[208:211], v[86:89]
	v_mfma_f32_16x16x32_bf16 v[86:89], v[176:179], v[212:215], v[86:89]
	v_mfma_f32_16x16x32_bf16 v[70:73], v[176:179], v[220:223], v[70:73]
	v_mfma_f32_16x16x32_bf16 v[70:73], v[164:167], v[216:219], v[70:73]
	v_mfma_f32_16x16x32_bf16 v[66:69], v[184:187], v[216:219], v[66:69]
	v_mfma_f32_16x16x32_bf16 v[66:69], v[188:191], v[220:223], v[66:69]
	v_mfma_f32_16x16x32_bf16 v[82:85], v[188:191], v[212:215], v[82:85]
	v_mfma_f32_16x16x32_bf16 v[82:85], v[184:187], v[208:211], v[82:85]
	s_barrier
	s_setprio 2
	v_mfma_f32_16x16x32_bf16 v[98:101], v[184:187], v[200:203], v[98:101]
	v_mfma_f32_16x16x32_bf16 v[98:101], v[188:191], v[204:207], v[98:101]
	v_mfma_f32_16x16x32_bf16 v[114:117], v[188:191], v[196:199], v[114:117]
	v_mfma_f32_16x16x32_bf16 v[114:117], v[184:187], v[192:195], v[114:117]
	s_setprio 0
	s_add_i32 s58, s78, s91
	v_lshl_add_u64 v[180:181], s[60:61], 0, v[138:139]
	s_mov_b32 m0, s58
	ds_read_b128 v[192:195], v173 offset:16384
	ds_read_b128 v[196:199], v173 offset:17408
	ds_read_b128 v[200:203], v173 offset:18432
	ds_read_b128 v[204:207], v173 offset:19456
	ds_read_b128 v[208:211], v173 offset:20480
	ds_read_b128 v[212:215], v173 offset:21504
	ds_read_b128 v[216:219], v173 offset:22528
	ds_read_b128 v[220:223], v173 offset:23552
	global_load_lds_dwordx4 v[180:181], off
	v_lshl_add_u64 v[224:225], v[180:181], 0, s[22:23]
	s_add_i32 m0, s58, 0x2000
	s_add_i32 s58, s79, s91
	global_load_lds_dwordx4 v[224:225], off
	v_lshl_add_u64 v[224:225], v[180:181], 0, s[24:25]
	s_mov_b32 m0, s58
	s_nop 0
	global_load_lds_dwordx4 v[224:225], off
	v_lshl_add_u64 v[224:225], v[180:181], 0, s[26:27]
	s_add_i32 m0, s58, 0x2000
	s_nop 0
	global_load_lds_dwordx4 v[224:225], off
	v_lshl_add_u64 v[224:225], s[72:73], 0, v[138:139]
	s_mov_b32 m0, s70
	v_lshl_add_u64 v[226:227], v[224:225], 0, s[22:23]
	global_load_lds_dwordx4 v[224:225], off
	s_mov_b32 m0, s71
	s_nop 0
	global_load_lds_dwordx4 v[226:227], off
	s_waitcnt vmcnt(8)
	s_waitcnt lgkmcnt(0)
	s_barrier
; #define PG8_STAGE(bufoff, gbase, voff) do { if constexpr (!pg8_noload<Epi>::value) { _Pragma("unroll") for (int _i = 0; _i < 2; ++_i) \
;         __builtin_amdgcn_global_load_lds((const unsigned*)((const char*)(gbase) + (size_t)_i * pstep + (voff)[0]), (PG8_LAS unsigned*)(lds + (bufoff) + ldsw + _i * 8192), 16, 0, 0); } } while (0)
; #define PG8_LDA(dst, b, h) do { _Pragma("unroll") for (int m = 0; m < 4; ++m) _Pragma("unroll") for (int k = 0; k < 2; ++k) dst[m][k] = *(const PG8_LAS bf16x8*)(lds + PG8_SA(b, h) + aoff + m * 2048 + k * 1024); } while (0)
; #define PG8_LDB(dst, b, h) do { _Pragma("unroll") for (int n = 0; n < 2; ++n) _Pragma("unroll") for (int k = 0; k < 2; ++k) dst[n][k] = *(const PG8_LAS bf16x8*)(lds + PG8_SB(b, h) + boff + n * 2048 + k * 1024); } while (0)
; #define PG8_MMA(ai, bj, At, Bt) do { __builtin_amdgcn_s_setprio(1); _Pragma("unroll") for (int m = 0; m < 4; ++m) _Pragma("unroll") for (int n = 0; n < 2; ++n) _Pragma("unroll") for (int k = 0; k < 2; ++k) \
;         acc[ai][bj][m][n] = __builtin_amdgcn_mfma_f32_16x16x32_bf16(Bt[n][k], At[m][k], acc[ai][bj][m][n], 0, 0, 0); __builtin_amdgcn_s_setprio(0); } while (0)
; #define PG8_WAIT_V(n) asm volatile("s_waitcnt vmcnt(" #n ")" ::: "memory")
; #define PG8_WAIT_L(n) asm volatile("s_waitcnt lgkmcnt(" #n ")" ::: "memory")
; #define PG8_BAR __builtin_amdgcn_s_barrier()
; #define PG8_SCHED __builtin_amdgcn_sched_barrier(0)
; template <class Epi, class Sched, bool ALIGN_EPI = false, bool SP2 = false, bool ABLK = false>
; __device__ __forceinline__ void gemm_phase(PG8_LAS unsigned char* lds, const Gemm g, const Sched& S, const Epi& E) {
;     ...
;             PG8_WAIT_V(8); PG8_WAIT_L(0); PG8_BAR; PG8_MMA(1, 0, At, B0); PG8_MMA(1, 1, At, B1); PG8_BAR; PG8_SCHED;
;             PG8_LDB(B0, 1, 0); PG8_LDB(B1, 1, 1); PG8_SCHED; PG8_LDA(At, 1, 0); PG8_STAGE(PG8_SA(0, 1), a2 + hstep, voffA);
;             PG8_WAIT_V(8); PG8_WAIT_L(0); PG8_BAR; PG8_MMA(0, 0, At, B0); PG8_MMA(0, 1, At, B1); PG8_BAR; PG8_SCHED;
	s_setprio 1
	s_waitcnt lgkmcnt(0)
	v_mfma_f32_16x16x32_bf16 v[62:65], v[130:133], v[192:195], v[62:65]
	v_mfma_f32_16x16x32_bf16 v[62:65], v[134:137], v[196:199], v[62:65]
	v_mfma_f32_16x16x32_bf16 v[46:49], v[134:137], v[204:207], v[46:49]
	v_mfma_f32_16x16x32_bf16 v[46:49], v[130:133], v[200:203], v[46:49]
	v_mfma_f32_16x16x32_bf16 v[30:33], v[130:133], v[208:211], v[30:33]
	v_mfma_f32_16x16x32_bf16 v[30:33], v[134:137], v[212:215], v[30:33]
	v_mfma_f32_16x16x32_bf16 v[14:17], v[134:137], v[220:223], v[14:17]
	v_mfma_f32_16x16x32_bf16 v[14:17], v[130:133], v[216:219], v[14:17]
	v_mfma_f32_16x16x32_bf16 v[10:13], v[156:159], v[216:219], v[10:13]
	v_mfma_f32_16x16x32_bf16 v[10:13], v[160:163], v[220:223], v[10:13]
	v_mfma_f32_16x16x32_bf16 v[26:29], v[160:163], v[212:215], v[26:29]
	v_mfma_f32_16x16x32_bf16 v[26:29], v[156:159], v[208:211], v[26:29]
	v_mfma_f32_16x16x32_bf16 v[42:45], v[156:159], v[200:203], v[42:45]
	v_mfma_f32_16x16x32_bf16 v[42:45], v[160:163], v[204:207], v[42:45]
	v_mfma_f32_16x16x32_bf16 v[58:61], v[160:163], v[196:199], v[58:61]
	v_mfma_f32_16x16x32_bf16 v[58:61], v[156:159], v[192:195], v[58:61]
	v_mfma_f32_16x16x32_bf16 v[54:57], v[164:167], v[192:195], v[54:57]
	v_mfma_f32_16x16x32_bf16 v[54:57], v[176:179], v[196:199], v[54:57]
	s_add_i32 s58, 0, 0x18000
	v_add_u32_e32 v160, s58, v168
	ds_read_b128 v[130:133], v160
	v_mfma_f32_16x16x32_bf16 v[38:41], v[176:179], v[204:207], v[38:41]
	v_mfma_f32_16x16x32_bf16 v[38:41], v[164:167], v[200:203], v[38:41]
	ds_read_b128 v[134:137], v160 offset:1024
	v_mfma_f32_16x16x32_bf16 v[22:25], v[164:167], v[208:211], v[22:25]
	v_mfma_f32_16x16x32_bf16 v[22:25], v[176:179], v[212:215], v[22:25]
	ds_read_b128 v[156:159], v160 offset:2048
	v_mfma_f32_16x16x32_bf16 v[6:9], v[176:179], v[220:223], v[6:9]
	v_mfma_f32_16x16x32_bf16 v[6:9], v[164:167], v[216:219], v[6:9]
	ds_read_b128 v[160:163], v160 offset:3072
	v_mfma_f32_16x16x32_bf16 v[2:5], v[184:187], v[216:219], v[2:5]
	v_mfma_f32_16x16x32_bf16 v[2:5], v[188:191], v[220:223], v[2:5]
	v_mfma_f32_16x16x32_bf16 v[18:21], v[188:191], v[212:215], v[18:21]
	v_mfma_f32_16x16x32_bf16 v[18:21], v[184:187], v[208:211], v[18:21]
	s_barrier
	s_setprio 2
	v_mfma_f32_16x16x32_bf16 v[34:37], v[184:187], v[200:203], v[34:37]
	v_mfma_f32_16x16x32_bf16 v[34:37], v[188:191], v[204:207], v[34:37]
	v_mfma_f32_16x16x32_bf16 v[50:53], v[188:191], v[196:199], v[50:53]
	v_mfma_f32_16x16x32_bf16 v[50:53], v[184:187], v[192:195], v[50:53]
	s_setprio 0
	s_add_i32 s59, 0, 0x1c000
	v_add_u32_e32 v188, s59, v168
	ds_read_b128 v[164:167], v188
	ds_read_b128 v[176:179], v188 offset:1024
	ds_read_b128 v[184:187], v188 offset:2048
	ds_read_b128 v[188:191], v188 offset:3072
	s_mov_b32 m0, s34
	v_lshl_add_u64 v[226:227], v[224:225], 0, s[24:25]
	ds_read_b128 v[192:195], v173 offset:32768
	ds_read_b128 v[196:199], v173 offset:33792
	ds_read_b128 v[200:203], v173 offset:34816
	ds_read_b128 v[204:207], v173 offset:35840
	ds_read_b128 v[208:211], v173 offset:36864
	ds_read_b128 v[212:215], v173 offset:37888
	ds_read_b128 v[216:219], v173 offset:38912
	ds_read_b128 v[220:223], v173 offset:39936
	global_load_lds_dwordx4 v[226:227], off
	v_lshl_add_u64 v[226:227], v[224:225], 0, s[26:27]
	s_mov_b32 m0, s35
	s_nop 0
	global_load_lds_dwordx4 v[226:227], off
	s_waitcnt vmcnt(8)
	s_waitcnt lgkmcnt(0)
	s_barrier
	s_setprio 1
	s_waitcnt lgkmcnt(0)
	v_mfma_f32_16x16x32_bf16 v[126:129], v[130:133], v[192:195], v[126:129]
	v_mfma_f32_16x16x32_bf16 v[126:129], v[134:137], v[196:199], v[126:129]
	v_mfma_f32_16x16x32_bf16 v[110:113], v[134:137], v[204:207], v[110:113]
	v_mfma_f32_16x16x32_bf16 v[110:113], v[130:133], v[200:203], v[110:113]
	v_mfma_f32_16x16x32_bf16 v[94:97], v[130:133], v[208:211], v[94:97]
	v_mfma_f32_16x16x32_bf16 v[94:97], v[134:137], v[212:215], v[94:97]
	v_mfma_f32_16x16x32_bf16 v[78:81], v[134:137], v[220:223], v[78:81]
	v_mfma_f32_16x16x32_bf16 v[78:81], v[130:133], v[216:219], v[78:81]
	v_mfma_f32_16x16x32_bf16 v[74:77], v[156:159], v[216:219], v[74:77]
	v_mfma_f32_16x16x32_bf16 v[74:77], v[160:163], v[220:223], v[74:77]
	v_mfma_f32_16x16x32_bf16 v[90:93], v[160:163], v[212:215], v[90:93]
	v_mfma_f32_16x16x32_bf16 v[90:93], v[156:159], v[208:211], v[90:93]
	v_mfma_f32_16x16x32_bf16 v[106:109], v[156:159], v[200:203], v[106:109]
	v_mfma_f32_16x16x32_bf16 v[106:109], v[160:163], v[204:207], v[106:109]
	v_mfma_f32_16x16x32_bf16 v[122:125], v[160:163], v[196:199], v[122:125]
	v_mfma_f32_16x16x32_bf16 v[122:125], v[156:159], v[192:195], v[122:125]
	v_mfma_f32_16x16x32_bf16 v[118:121], v[164:167], v[192:195], v[118:121]
	v_mfma_f32_16x16x32_bf16 v[118:121], v[176:179], v[196:199], v[118:121]
	v_mfma_f32_16x16x32_bf16 v[102:105], v[176:179], v[204:207], v[102:105]
	v_mfma_f32_16x16x32_bf16 v[102:105], v[164:167], v[200:203], v[102:105]
	v_mfma_f32_16x16x32_bf16 v[86:89], v[164:167], v[208:211], v[86:89]
	v_mfma_f32_16x16x32_bf16 v[86:89], v[176:179], v[212:215], v[86:89]
	v_mfma_f32_16x16x32_bf16 v[70:73], v[176:179], v[220:223], v[70:73]
	v_mfma_f32_16x16x32_bf16 v[70:73], v[164:167], v[216:219], v[70:73]
	v_mfma_f32_16x16x32_bf16 v[66:69], v[184:187], v[216:219], v[66:69]
	v_mfma_f32_16x16x32_bf16 v[66:69], v[188:191], v[220:223], v[66:69]
	v_mfma_f32_16x16x32_bf16 v[82:85], v[188:191], v[212:215], v[82:85]
	v_mfma_f32_16x16x32_bf16 v[82:85], v[184:187], v[208:211], v[82:85]
	s_barrier
; #define PG8_STAGE(bufoff, gbase, voff) do { if constexpr (!pg8_noload<Epi>::value) { _Pragma("unroll") for (int _i = 0; _i < 2; ++_i) \
;         __builtin_amdgcn_global_load_lds((const unsigned*)((const char*)(gbase) + (size_t)_i * pstep + (voff)[0]), (PG8_LAS unsigned*)(lds + (bufoff) + ldsw + _i * 8192), 16, 0, 0); } } while (0)
; #define PG8_LDA(dst, b, h) do { _Pragma("unroll") for (int m = 0; m < 4; ++m) _Pragma("unroll") for (int k = 0; k < 2; ++k) dst[m][k] = *(const PG8_LAS bf16x8*)(lds + PG8_SA(b, h) + aoff + m * 2048 + k * 1024); } while (0)
; #define PG8_MMA(ai, bj, At, Bt) do { __builtin_amdgcn_s_setprio(1); _Pragma("unroll") for (int m = 0; m < 4; ++m) _Pragma("unroll") for (int n = 0; n < 2; ++n) _Pragma("unroll") for (int k = 0; k < 2; ++k) \
;         acc[ai][bj][m][n] = __builtin_amdgcn_mfma_f32_16x16x32_bf16(Bt[n][k], At[m][k], acc[ai][bj][m][n], 0, 0, 0); __builtin_amdgcn_s_setprio(0); } while (0)
; #define PG8_WAIT_V(n) asm volatile("s_waitcnt vmcnt(" #n ")" ::: "memory")
; #define PG8_WAIT_L(n) asm volatile("s_waitcnt lgkmcnt(" #n ")" ::: "memory")
; #define PG8_BAR __builtin_amdgcn_s_barrier()
; #define PG8_SCHED __builtin_amdgcn_sched_barrier(0)
; template <class Epi, class Sched, bool ALIGN_EPI = false, bool SP2 = false, bool ABLK = false>
; __device__ __forceinline__ void gemm_phase(PG8_LAS unsigned char* lds, const Gemm g, const Sched& S, const Epi& E) {
;     ...
;         for (int t = 0; t < nt; t += 2) {
;     ...
;             PG8_WAIT_V(8); PG8_WAIT_L(0); PG8_BAR; PG8_MMA(0, 0, At, B0); PG8_MMA(0, 1, At, B1); PG8_BAR; PG8_SCHED;
;             PG8_LDA(At, 1, 1); PG8_STAGE(PG8_SB(1, 0), b3, voffB); PG8_STAGE(PG8_SB(1, 1), b3 + hstep, voffB); PG8_STAGE(PG8_SA(1, 0), a3, voffA);
;             PG8_WAIT_V(8); PG8_WAIT_L(0); PG8_BAR; PG8_MMA(1, 0, At, B0); PG8_MMA(1, 1, At, B1); PG8_BAR; PG8_SCHED;
	s_setprio 2
	v_mfma_f32_16x16x32_bf16 v[98:101], v[184:187], v[200:203], v[98:101]
	v_mfma_f32_16x16x32_bf16 v[98:101], v[188:191], v[204:207], v[98:101]
	v_mfma_f32_16x16x32_bf16 v[114:117], v[188:191], v[196:199], v[114:117]
	v_mfma_f32_16x16x32_bf16 v[114:117], v[184:187], v[192:195], v[114:117]
	s_setprio 0
	s_add_i32 s58, s58, s91
	v_lshl_add_u64 v[226:227], v[180:181], 0, s[92:93]
	s_mov_b32 m0, s58
	ds_read_b128 v[192:195], v173 offset:49152
	ds_read_b128 v[196:199], v173 offset:50176
	ds_read_b128 v[200:203], v173 offset:51200
	ds_read_b128 v[204:207], v173 offset:52224
	ds_read_b128 v[208:211], v173 offset:53248
	ds_read_b128 v[212:215], v173 offset:54272
	ds_read_b128 v[216:219], v173 offset:55296
	ds_read_b128 v[220:223], v173 offset:56320
	global_load_lds_dwordx4 v[226:227], off
	v_lshl_add_u64 v[226:227], v[180:181], 0, s[94:95]
	s_add_i32 m0, s58, 0x2000
	s_add_i32 s58, s59, s91
	global_load_lds_dwordx4 v[226:227], off
	v_lshl_add_u64 v[226:227], v[180:181], 0, s[96:97]
	s_mov_b32 m0, s58
	v_lshl_add_u64 v[180:181], v[180:181], 0, s[88:89]
	global_load_lds_dwordx4 v[226:227], off
	s_add_i32 m0, s58, 0x2000
	s_nop 0
	global_load_lds_dwordx4 v[180:181], off
	v_lshl_add_u64 v[180:181], v[224:225], 0, s[92:93]
	s_mov_b32 m0, s10
	s_nop 0
	global_load_lds_dwordx4 v[180:181], off
	v_lshl_add_u64 v[180:181], v[224:225], 0, s[94:95]
	s_mov_b32 m0, s11
	s_nop 0
	global_load_lds_dwordx4 v[180:181], off
	s_waitcnt vmcnt(8)
	s_waitcnt lgkmcnt(0)
	s_barrier
	s_setprio 1
	s_waitcnt lgkmcnt(0)
	v_mfma_f32_16x16x32_bf16 v[62:65], v[130:133], v[192:195], v[62:65]
	v_mfma_f32_16x16x32_bf16 v[62:65], v[134:137], v[196:199], v[62:65]
	v_mfma_f32_16x16x32_bf16 v[46:49], v[134:137], v[204:207], v[46:49]
	v_mfma_f32_16x16x32_bf16 v[46:49], v[130:133], v[200:203], v[46:49]
	v_mfma_f32_16x16x32_bf16 v[30:33], v[130:133], v[208:211], v[30:33]
	v_mfma_f32_16x16x32_bf16 v[30:33], v[134:137], v[212:215], v[30:33]
	v_mfma_f32_16x16x32_bf16 v[14:17], v[134:137], v[220:223], v[14:17]
	v_mfma_f32_16x16x32_bf16 v[14:17], v[130:133], v[216:219], v[14:17]
	v_mfma_f32_16x16x32_bf16 v[10:13], v[156:159], v[216:219], v[10:13]
	v_mfma_f32_16x16x32_bf16 v[10:13], v[160:163], v[220:223], v[10:13]
	v_mfma_f32_16x16x32_bf16 v[26:29], v[160:163], v[212:215], v[26:29]
	v_mfma_f32_16x16x32_bf16 v[26:29], v[156:159], v[208:211], v[26:29]
	v_mfma_f32_16x16x32_bf16 v[42:45], v[156:159], v[200:203], v[42:45]
	v_mfma_f32_16x16x32_bf16 v[42:45], v[160:163], v[204:207], v[42:45]
	v_mfma_f32_16x16x32_bf16 v[58:61], v[160:163], v[196:199], v[58:61]
	v_mfma_f32_16x16x32_bf16 v[58:61], v[156:159], v[192:195], v[58:61]
	v_mfma_f32_16x16x32_bf16 v[54:57], v[164:167], v[192:195], v[54:57]
	v_mfma_f32_16x16x32_bf16 v[54:57], v[176:179], v[196:199], v[54:57]
	v_mfma_f32_16x16x32_bf16 v[38:41], v[176:179], v[204:207], v[38:41]
	v_mfma_f32_16x16x32_bf16 v[38:41], v[164:167], v[200:203], v[38:41]
	v_mfma_f32_16x16x32_bf16 v[22:25], v[164:167], v[208:211], v[22:25]
	v_mfma_f32_16x16x32_bf16 v[22:25], v[176:179], v[212:215], v[22:25]
	v_mfma_f32_16x16x32_bf16 v[6:9], v[176:179], v[220:223], v[6:9]
	v_mfma_f32_16x16x32_bf16 v[6:9], v[164:167], v[216:219], v[6:9]
	v_mfma_f32_16x16x32_bf16 v[2:5], v[184:187], v[216:219], v[2:5]
	v_mfma_f32_16x16x32_bf16 v[2:5], v[188:191], v[220:223], v[2:5]
	v_mfma_f32_16x16x32_bf16 v[18:21], v[188:191], v[212:215], v[18:21]
	v_mfma_f32_16x16x32_bf16 v[18:21], v[184:187], v[208:211], v[18:21]
	s_barrier
	s_setprio 2
	v_mfma_f32_16x16x32_bf16 v[34:37], v[184:187], v[200:203], v[34:37]
	v_mfma_f32_16x16x32_bf16 v[34:37], v[188:191], v[204:207], v[34:37]
	v_mfma_f32_16x16x32_bf16 v[50:53], v[188:191], v[196:199], v[50:53]
	v_mfma_f32_16x16x32_bf16 v[50:53], v[184:187], v[192:195], v[50:53]
	s_setprio 0
	s_cmp_gt_u32 s57, 29
	s_mov_b32 s57, s28
	s_cbranch_scc1 .LBB0_631

; #define PG8_STAGE(bufoff, gbase, voff) do { if constexpr (!pg8_noload<Epi>::value) { _Pragma("unroll") for (int _i = 0; _i < 2; ++_i) \
;         __builtin_amdgcn_global_load_lds((const unsigned*)((const char*)(gbase) + (size_t)_i * pstep + (voff)[0]), (PG8_LAS unsigned*)(lds + (bufoff) + ldsw + _i * 8192), 16, 0, 0); } } while (0)
; #define PG8_LDA(dst, b, h) do { _Pragma("unroll") for (int m = 0; m < 4; ++m) _Pragma("unroll") for (int k = 0; k < 2; ++k) dst[m][k] = *(const PG8_LAS bf16x8*)(lds + PG8_SA(b, h) + aoff + m * 2048 + k * 1024); } while (0)
; #define PG8_LDB(dst, b, h) do { _Pragma("unroll") for (int n = 0; n < 2; ++n) _Pragma("unroll") for (int k = 0; k < 2; ++k) dst[n][k] = *(const PG8_LAS bf16x8*)(lds + PG8_SB(b, h) + boff + n * 2048 + k * 1024); } while (0)
; #define PG8_MMA(ai, bj, At, Bt) do { __builtin_amdgcn_s_setprio(1); _Pragma("unroll") for (int m = 0; m < 4; ++m) _Pragma("unroll") for (int n = 0; n < 2; ++n) _Pragma("unroll") for (int k = 0; k < 2; ++k) \
;         acc[ai][bj][m][n] = __builtin_amdgcn_mfma_f32_16x16x32_bf16(Bt[n][k], At[m][k], acc[ai][bj][m][n], 0, 0, 0); __builtin_amdgcn_s_setprio(0); } while (0)
; #define PG8_WAIT_V(n) asm volatile("s_waitcnt vmcnt(" #n ")" ::: "memory")
; #define PG8_WAIT_L(n) asm volatile("s_waitcnt lgkmcnt(" #n ")" ::: "memory")
; #define PG8_BAR __builtin_amdgcn_s_barrier()
; template <class Epi, class Sched, bool ALIGN_EPI = false, bool SP2 = false, bool ABLK = false>
; __device__ __forceinline__ void gemm_phase(PG8_LAS unsigned char* lds, const Gemm g, const Sched& S, const Epi& E) {
;     ...
;             const bool last = (t == nt - 2);
;             const char* a1 = cA + (size_t)(t + 1) * kstep;
;             const char* a2 = last ? nA : cA + (size_t)(t + 2) * kstep; const char* b2 = last ? nB : cB + (size_t)(t + 2) * kstepB;
;             const char* a3 = a2 + kstep; const char* b3 = b2 + kstepB;
;             if (last && has_next) S.a_ready(nxt);
;             if constexpr (SP2) {
;             PG8_LDB(B0, 0, 0); PG8_LDB(B1, 0, 1); PG8_SCHED; PG8_LDA(At, 0, 0); PG8_STAGE(PG8_SA(1, 1), a1 + hstep, voffA);
;             PG8_WAIT_V(8); PG8_WAIT_L(0); PG8_BAR; PG8_MMA(0, 0, At, B0); PG8_MMA(0, 1, At, B1); PG8_BAR; PG8_SCHED;
;             PG8_LDA(At, 0, 1); PG8_STAGE(PG8_SB(0, 0), b2, voffB); PG8_STAGE(PG8_SB(0, 1), b2 + hstep, voffB); PG8_STAGE(PG8_SA(0, 0), a2, voffA);
.LBB0_1533:
	ds_read_b128 v[114:117], v167
	ds_read_b128 v[126:129], v167 offset:1024
	ds_read_b128 v[130:133], v167 offset:2048
	ds_read_b128 v[142:145], v167 offset:3072
	ds_read_b128 v[146:149], v168
	ds_read_b128 v[150:153], v168 offset:1024
	ds_read_b128 v[174:177], v168 offset:2048
	ds_read_b128 v[178:181], v168 offset:3072
	s_add_i32 s41, s39, 2
	s_add_u32 s70, s68, 0xfff00800
	s_addc_u32 s71, s69, -1
	s_cmp_eq_u32 s3, s39
	s_cselect_b32 s71, s43, s71
	s_cselect_b32 s70, s42, s70
	s_cselect_b32 s81, s65, s37
	s_cselect_b32 s80, s64, s11
	v_lshl_add_u64 v[162:163], s[68:69], 0, v[158:159]
	s_add_i32 m0, s56, 0xc000
	ds_read_b128 v[184:187], v169
	ds_read_b128 v[188:191], v169 offset:1024
	ds_read_b128 v[192:195], v169 offset:2048
	ds_read_b128 v[196:199], v169 offset:3072
	ds_read_b128 v[200:203], v169 offset:4096
	ds_read_b128 v[204:207], v169 offset:5120
	ds_read_b128 v[208:211], v169 offset:6144
	ds_read_b128 v[212:215], v169 offset:7168
	global_load_lds_dwordx4 v[162:163], off
	v_lshl_add_u64 v[162:163], v[162:163], 0, s[12:13]
	s_add_i32 m0, s56, 0xe000
	s_nop 0
	global_load_lds_dwordx4 v[162:163], off
	s_waitcnt vmcnt(8)
	s_waitcnt lgkmcnt(0)
	s_barrier
	s_setprio 1
	s_waitcnt lgkmcnt(0)
	v_mfma_f32_16x16x32_bf16 v[138:141], v[114:117], v[184:187], v[138:141]
	v_mfma_f32_16x16x32_bf16 v[138:141], v[126:129], v[188:191], v[138:141]
	v_mfma_f32_16x16x32_bf16 v[110:113], v[126:129], v[196:199], v[110:113]
	v_mfma_f32_16x16x32_bf16 v[110:113], v[114:117], v[192:195], v[110:113]
	v_mfma_f32_16x16x32_bf16 v[94:97], v[114:117], v[200:203], v[94:97]
	v_mfma_f32_16x16x32_bf16 v[94:97], v[126:129], v[204:207], v[94:97]
	v_mfma_f32_16x16x32_bf16 v[78:81], v[126:129], v[212:215], v[78:81]
	v_mfma_f32_16x16x32_bf16 v[78:81], v[114:117], v[208:211], v[78:81]
	v_mfma_f32_16x16x32_bf16 v[74:77], v[130:133], v[208:211], v[74:77]
	v_mfma_f32_16x16x32_bf16 v[74:77], v[142:145], v[212:215], v[74:77]
	v_mfma_f32_16x16x32_bf16 v[90:93], v[142:145], v[204:207], v[90:93]
	v_mfma_f32_16x16x32_bf16 v[90:93], v[130:133], v[200:203], v[90:93]
	v_mfma_f32_16x16x32_bf16 v[106:109], v[130:133], v[192:195], v[106:109]
	v_mfma_f32_16x16x32_bf16 v[106:109], v[142:145], v[196:199], v[106:109]
	v_mfma_f32_16x16x32_bf16 v[134:137], v[142:145], v[188:191], v[134:137]
	v_mfma_f32_16x16x32_bf16 v[134:137], v[130:133], v[184:187], v[134:137]
	v_mfma_f32_16x16x32_bf16 v[122:125], v[146:149], v[184:187], v[122:125]
	v_mfma_f32_16x16x32_bf16 v[122:125], v[150:153], v[188:191], v[122:125]
	v_mfma_f32_16x16x32_bf16 v[102:105], v[150:153], v[196:199], v[102:105]
	v_mfma_f32_16x16x32_bf16 v[102:105], v[146:149], v[192:195], v[102:105]
	v_mfma_f32_16x16x32_bf16 v[86:89], v[146:149], v[200:203], v[86:89]
	v_mfma_f32_16x16x32_bf16 v[86:89], v[150:153], v[204:207], v[86:89]
	v_mfma_f32_16x16x32_bf16 v[70:73], v[150:153], v[212:215], v[70:73]
	v_mfma_f32_16x16x32_bf16 v[70:73], v[146:149], v[208:211], v[70:73]
	v_mfma_f32_16x16x32_bf16 v[66:69], v[174:177], v[208:211], v[66:69]
	v_mfma_f32_16x16x32_bf16 v[66:69], v[178:181], v[212:215], v[66:69]
	v_mfma_f32_16x16x32_bf16 v[82:85], v[178:181], v[204:207], v[82:85]
	v_mfma_f32_16x16x32_bf16 v[82:85], v[174:177], v[200:203], v[82:85]
	s_barrier
	s_setprio 2
	v_mfma_f32_16x16x32_bf16 v[98:101], v[174:177], v[192:195], v[98:101]
	v_mfma_f32_16x16x32_bf16 v[98:101], v[178:181], v[196:199], v[98:101]
	v_mfma_f32_16x16x32_bf16 v[118:121], v[178:181], v[188:191], v[118:121]
	v_mfma_f32_16x16x32_bf16 v[118:121], v[174:177], v[184:187], v[118:121]
	s_setprio 0
	s_add_i32 s39, s74, s55
	v_lshl_add_u64 v[162:163], s[80:81], 0, v[154:155]
	s_mov_b32 m0, s39
	ds_read_b128 v[184:187], v169 offset:16384
	ds_read_b128 v[188:191], v169 offset:17408
	ds_read_b128 v[192:195], v169 offset:18432
	ds_read_b128 v[196:199], v169 offset:19456
	ds_read_b128 v[200:203], v169 offset:20480
	ds_read_b128 v[204:207], v169 offset:21504
	ds_read_b128 v[208:211], v169 offset:22528
	ds_read_b128 v[212:215], v169 offset:23552
	global_load_lds_dwordx4 v[162:163], off
	v_lshl_add_u64 v[216:217], v[162:163], 0, s[12:13]
	s_add_i32 m0, s39, 0x2000
	s_add_i32 s39, s75, s55
	global_load_lds_dwordx4 v[216:217], off
	v_lshl_add_u64 v[216:217], v[162:163], 0, s[14:15]
	s_mov_b32 m0, s39
	s_nop 0
	global_load_lds_dwordx4 v[216:217], off
	v_lshl_add_u64 v[216:217], v[162:163], 0, s[16:17]
	s_add_i32 m0, s39, 0x2000
	s_nop 0
	global_load_lds_dwordx4 v[216:217], off
	v_lshl_add_u64 v[216:217], s[70:71], 0, v[154:155]
	s_mov_b32 m0, s56
	v_lshl_add_u64 v[218:219], v[216:217], 0, s[12:13]
	global_load_lds_dwordx4 v[216:217], off
	s_mov_b32 m0, s57
	s_nop 0
	global_load_lds_dwordx4 v[218:219], off
	s_waitcnt vmcnt(8)
	s_waitcnt lgkmcnt(0)
	s_barrier
; #define PG8_STAGE(bufoff, gbase, voff) do { if constexpr (!pg8_noload<Epi>::value) { _Pragma("unroll") for (int _i = 0; _i < 2; ++_i) \
;         __builtin_amdgcn_global_load_lds((const unsigned*)((const char*)(gbase) + (size_t)_i * pstep + (voff)[0]), (PG8_LAS unsigned*)(lds + (bufoff) + ldsw + _i * 8192), 16, 0, 0); } } while (0)
; #define PG8_LDA(dst, b, h) do { _Pragma("unroll") for (int m = 0; m < 4; ++m) _Pragma("unroll") for (int k = 0; k < 2; ++k) dst[m][k] = *(const PG8_LAS bf16x8*)(lds + PG8_SA(b, h) + aoff + m * 2048 + k * 1024); } while (0)
; #define PG8_LDB(dst, b, h) do { _Pragma("unroll") for (int n = 0; n < 2; ++n) _Pragma("unroll") for (int k = 0; k < 2; ++k) dst[n][k] = *(const PG8_LAS bf16x8*)(lds + PG8_SB(b, h) + boff + n * 2048 + k * 1024); } while (0)
; #define PG8_MMA(ai, bj, At, Bt) do { __builtin_amdgcn_s_setprio(1); _Pragma("unroll") for (int m = 0; m < 4; ++m) _Pragma("unroll") for (int n = 0; n < 2; ++n) _Pragma("unroll") for (int k = 0; k < 2; ++k) \
;         acc[ai][bj][m][n] = __builtin_amdgcn_mfma_f32_16x16x32_bf16(Bt[n][k], At[m][k], acc[ai][bj][m][n], 0, 0, 0); __builtin_amdgcn_s_setprio(0); } while (0)
; #define PG8_WAIT_V(n) asm volatile("s_waitcnt vmcnt(" #n ")" ::: "memory")
; #define PG8_WAIT_L(n) asm volatile("s_waitcnt lgkmcnt(" #n ")" ::: "memory")
; #define PG8_BAR __builtin_amdgcn_s_barrier()
; #define PG8_SCHED __builtin_amdgcn_sched_barrier(0)
; template <class Epi, class Sched, bool ALIGN_EPI = false, bool SP2 = false, bool ABLK = false>
; __device__ __forceinline__ void gemm_phase(PG8_LAS unsigned char* lds, const Gemm g, const Sched& S, const Epi& E) {
;     ...
;             PG8_WAIT_V(8); PG8_WAIT_L(0); PG8_BAR; PG8_MMA(1, 0, At, B0); PG8_MMA(1, 1, At, B1); PG8_BAR; PG8_SCHED;
;             PG8_LDB(B0, 1, 0); PG8_LDB(B1, 1, 1); PG8_SCHED; PG8_LDA(At, 1, 0); PG8_STAGE(PG8_SA(0, 1), a2 + hstep, voffA);
;             PG8_WAIT_V(8); PG8_WAIT_L(0); PG8_BAR; PG8_MMA(0, 0, At, B0); PG8_MMA(0, 1, At, B1); PG8_BAR; PG8_SCHED;
	s_setprio 1
	s_waitcnt lgkmcnt(0)
	v_mfma_f32_16x16x32_bf16 v[62:65], v[114:117], v[184:187], v[62:65]
	v_mfma_f32_16x16x32_bf16 v[62:65], v[126:129], v[188:191], v[62:65]
	v_mfma_f32_16x16x32_bf16 v[46:49], v[126:129], v[196:199], v[46:49]
	v_mfma_f32_16x16x32_bf16 v[46:49], v[114:117], v[192:195], v[46:49]
	v_mfma_f32_16x16x32_bf16 v[30:33], v[114:117], v[200:203], v[30:33]
	v_mfma_f32_16x16x32_bf16 v[30:33], v[126:129], v[204:207], v[30:33]
	v_mfma_f32_16x16x32_bf16 v[14:17], v[126:129], v[212:215], v[14:17]
	v_mfma_f32_16x16x32_bf16 v[14:17], v[114:117], v[208:211], v[14:17]
	v_mfma_f32_16x16x32_bf16 v[10:13], v[130:133], v[208:211], v[10:13]
	v_mfma_f32_16x16x32_bf16 v[10:13], v[142:145], v[212:215], v[10:13]
	v_mfma_f32_16x16x32_bf16 v[26:29], v[142:145], v[204:207], v[26:29]
	v_mfma_f32_16x16x32_bf16 v[26:29], v[130:133], v[200:203], v[26:29]
	v_mfma_f32_16x16x32_bf16 v[42:45], v[130:133], v[192:195], v[42:45]
	v_mfma_f32_16x16x32_bf16 v[42:45], v[142:145], v[196:199], v[42:45]
	v_mfma_f32_16x16x32_bf16 v[58:61], v[142:145], v[188:191], v[58:61]
	v_mfma_f32_16x16x32_bf16 v[58:61], v[130:133], v[184:187], v[58:61]
	v_mfma_f32_16x16x32_bf16 v[54:57], v[146:149], v[184:187], v[54:57]
	v_mfma_f32_16x16x32_bf16 v[54:57], v[150:153], v[188:191], v[54:57]
	s_add_i32 s39, 0, 0x18000
	v_add_u32_e32 v142, s39, v1
	ds_read_b128 v[114:117], v142
	v_mfma_f32_16x16x32_bf16 v[38:41], v[150:153], v[196:199], v[38:41]
	v_mfma_f32_16x16x32_bf16 v[38:41], v[146:149], v[192:195], v[38:41]
	ds_read_b128 v[126:129], v142 offset:1024
	v_mfma_f32_16x16x32_bf16 v[22:25], v[146:149], v[200:203], v[22:25]
	v_mfma_f32_16x16x32_bf16 v[22:25], v[150:153], v[204:207], v[22:25]
	ds_read_b128 v[130:133], v142 offset:2048
	v_mfma_f32_16x16x32_bf16 v[6:9], v[150:153], v[212:215], v[6:9]
	v_mfma_f32_16x16x32_bf16 v[6:9], v[146:149], v[208:211], v[6:9]
	ds_read_b128 v[142:145], v142 offset:3072
	v_mfma_f32_16x16x32_bf16 v[2:5], v[174:177], v[208:211], v[2:5]
	v_mfma_f32_16x16x32_bf16 v[2:5], v[178:181], v[212:215], v[2:5]
	v_mfma_f32_16x16x32_bf16 v[18:21], v[178:181], v[204:207], v[18:21]
	v_mfma_f32_16x16x32_bf16 v[18:21], v[174:177], v[200:203], v[18:21]
	s_barrier
	s_setprio 2
	v_mfma_f32_16x16x32_bf16 v[34:37], v[174:177], v[192:195], v[34:37]
	v_mfma_f32_16x16x32_bf16 v[34:37], v[178:181], v[196:199], v[34:37]
	v_mfma_f32_16x16x32_bf16 v[50:53], v[178:181], v[188:191], v[50:53]
	v_mfma_f32_16x16x32_bf16 v[50:53], v[174:177], v[184:187], v[50:53]
	s_setprio 0
	s_add_i32 s70, 0, 0x1c000
	v_add_u32_e32 v173, s70, v1
	ds_read_b128 v[146:149], v173
	ds_read_b128 v[150:153], v173 offset:1024
	ds_read_b128 v[174:177], v173 offset:2048
	ds_read_b128 v[178:181], v173 offset:3072
	s_mov_b32 m0, s58
	v_lshl_add_u64 v[218:219], v[216:217], 0, s[14:15]
	ds_read_b128 v[184:187], v169 offset:32768
	ds_read_b128 v[188:191], v169 offset:33792
	ds_read_b128 v[192:195], v169 offset:34816
	ds_read_b128 v[196:199], v169 offset:35840
	ds_read_b128 v[200:203], v169 offset:36864
	ds_read_b128 v[204:207], v169 offset:37888
	ds_read_b128 v[208:211], v169 offset:38912
	ds_read_b128 v[212:215], v169 offset:39936
	global_load_lds_dwordx4 v[218:219], off
	v_lshl_add_u64 v[218:219], v[216:217], 0, s[16:17]
	s_mov_b32 m0, s59
	s_nop 0
	global_load_lds_dwordx4 v[218:219], off
	s_waitcnt vmcnt(8)
	s_waitcnt lgkmcnt(0)
	s_barrier
	s_setprio 1
	s_waitcnt lgkmcnt(0)
	v_mfma_f32_16x16x32_bf16 v[138:141], v[114:117], v[184:187], v[138:141]
	v_mfma_f32_16x16x32_bf16 v[138:141], v[126:129], v[188:191], v[138:141]
	v_mfma_f32_16x16x32_bf16 v[110:113], v[126:129], v[196:199], v[110:113]
	v_mfma_f32_16x16x32_bf16 v[110:113], v[114:117], v[192:195], v[110:113]
	v_mfma_f32_16x16x32_bf16 v[94:97], v[114:117], v[200:203], v[94:97]
	v_mfma_f32_16x16x32_bf16 v[94:97], v[126:129], v[204:207], v[94:97]
	v_mfma_f32_16x16x32_bf16 v[78:81], v[126:129], v[212:215], v[78:81]
	v_mfma_f32_16x16x32_bf16 v[78:81], v[114:117], v[208:211], v[78:81]
	v_mfma_f32_16x16x32_bf16 v[74:77], v[130:133], v[208:211], v[74:77]
	v_mfma_f32_16x16x32_bf16 v[74:77], v[142:145], v[212:215], v[74:77]
	v_mfma_f32_16x16x32_bf16 v[90:93], v[142:145], v[204:207], v[90:93]
	v_mfma_f32_16x16x32_bf16 v[90:93], v[130:133], v[200:203], v[90:93]
	v_mfma_f32_16x16x32_bf16 v[106:109], v[130:133], v[192:195], v[106:109]
	v_mfma_f32_16x16x32_bf16 v[106:109], v[142:145], v[196:199], v[106:109]
	v_mfma_f32_16x16x32_bf16 v[134:137], v[142:145], v[188:191], v[134:137]
	v_mfma_f32_16x16x32_bf16 v[134:137], v[130:133], v[184:187], v[134:137]
	v_mfma_f32_16x16x32_bf16 v[122:125], v[146:149], v[184:187], v[122:125]
	v_mfma_f32_16x16x32_bf16 v[122:125], v[150:153], v[188:191], v[122:125]
	v_mfma_f32_16x16x32_bf16 v[102:105], v[150:153], v[196:199], v[102:105]
	v_mfma_f32_16x16x32_bf16 v[102:105], v[146:149], v[192:195], v[102:105]
	v_mfma_f32_16x16x32_bf16 v[86:89], v[146:149], v[200:203], v[86:89]
	v_mfma_f32_16x16x32_bf16 v[86:89], v[150:153], v[204:207], v[86:89]
	v_mfma_f32_16x16x32_bf16 v[70:73], v[150:153], v[212:215], v[70:73]
	v_mfma_f32_16x16x32_bf16 v[70:73], v[146:149], v[208:211], v[70:73]
	v_mfma_f32_16x16x32_bf16 v[66:69], v[174:177], v[208:211], v[66:69]
	v_mfma_f32_16x16x32_bf16 v[66:69], v[178:181], v[212:215], v[66:69]
	v_mfma_f32_16x16x32_bf16 v[82:85], v[178:181], v[204:207], v[82:85]
	v_mfma_f32_16x16x32_bf16 v[82:85], v[174:177], v[200:203], v[82:85]
	s_barrier
; #define PG8_STAGE(bufoff, gbase, voff) do { if constexpr (!pg8_noload<Epi>::value) { _Pragma("unroll") for (int _i = 0; _i < 2; ++_i) \
;         __builtin_amdgcn_global_load_lds((const unsigned*)((const char*)(gbase) + (size_t)_i * pstep + (voff)[0]), (PG8_LAS unsigned*)(lds + (bufoff) + ldsw + _i * 8192), 16, 0, 0); } } while (0)
; #define PG8_LDA(dst, b, h) do { _Pragma("unroll") for (int m = 0; m < 4; ++m) _Pragma("unroll") for (int k = 0; k < 2; ++k) dst[m][k] = *(const PG8_LAS bf16x8*)(lds + PG8_SA(b, h) + aoff + m * 2048 + k * 1024); } while (0)
; #define PG8_MMA(ai, bj, At, Bt) do { __builtin_amdgcn_s_setprio(1); _Pragma("unroll") for (int m = 0; m < 4; ++m) _Pragma("unroll") for (int n = 0; n < 2; ++n) _Pragma("unroll") for (int k = 0; k < 2; ++k) \
;         acc[ai][bj][m][n] = __builtin_amdgcn_mfma_f32_16x16x32_bf16(Bt[n][k], At[m][k], acc[ai][bj][m][n], 0, 0, 0); __builtin_amdgcn_s_setprio(0); } while (0)
; #define PG8_WAIT_V(n) asm volatile("s_waitcnt vmcnt(" #n ")" ::: "memory")
; #define PG8_WAIT_L(n) asm volatile("s_waitcnt lgkmcnt(" #n ")" ::: "memory")
; #define PG8_BAR __builtin_amdgcn_s_barrier()
; #define PG8_SCHED __builtin_amdgcn_sched_barrier(0)
;     __device__ __forceinline__ void operator()(const f32x4 (&acc)[2][2][4][2], const Unit& u, int wr, int wc, int fr, int fq) const {
;     ...
;         if (u.pm * BM < seq) {
; template <class Epi, class Sched, bool ALIGN_EPI = false, bool SP2 = false, bool ABLK = false>
; __device__ __forceinline__ void gemm_phase(PG8_LAS unsigned char* lds, const Gemm g, const Sched& S, const Epi& E) {
;     ...
;             PG8_WAIT_V(8); PG8_WAIT_L(0); PG8_BAR; PG8_MMA(0, 0, At, B0); PG8_MMA(0, 1, At, B1); PG8_BAR; PG8_SCHED;
;             PG8_LDA(At, 1, 1); PG8_STAGE(PG8_SB(1, 0), b3, voffB); PG8_STAGE(PG8_SB(1, 1), b3 + hstep, voffB); PG8_STAGE(PG8_SA(1, 0), a3, voffA);
;             PG8_WAIT_V(8); PG8_WAIT_L(0); PG8_BAR; PG8_MMA(1, 0, At, B0); PG8_MMA(1, 1, At, B1); PG8_BAR; PG8_SCHED;
	s_setprio 2
	v_mfma_f32_16x16x32_bf16 v[98:101], v[174:177], v[192:195], v[98:101]
	v_mfma_f32_16x16x32_bf16 v[98:101], v[178:181], v[196:199], v[98:101]
	v_mfma_f32_16x16x32_bf16 v[118:121], v[178:181], v[188:191], v[118:121]
	v_mfma_f32_16x16x32_bf16 v[118:121], v[174:177], v[184:187], v[118:121]
	s_setprio 0
	s_add_i32 s39, s39, s55
	v_lshl_add_u64 v[218:219], v[162:163], 0, s[24:25]
	s_mov_b32 m0, s39
	ds_read_b128 v[184:187], v169 offset:49152
	ds_read_b128 v[188:191], v169 offset:50176
	ds_read_b128 v[192:195], v169 offset:51200
	ds_read_b128 v[196:199], v169 offset:52224
	ds_read_b128 v[200:203], v169 offset:53248
	ds_read_b128 v[204:207], v169 offset:54272
	ds_read_b128 v[208:211], v169 offset:55296
	ds_read_b128 v[212:215], v169 offset:56320
	global_load_lds_dwordx4 v[218:219], off
	v_lshl_add_u64 v[218:219], v[162:163], 0, s[26:27]
	s_add_i32 m0, s39, 0x2000
	s_add_i32 s39, s70, s55
	global_load_lds_dwordx4 v[218:219], off
	v_lshl_add_u64 v[218:219], v[162:163], 0, s[28:29]
	s_mov_b32 m0, s39
	v_lshl_add_u64 v[162:163], v[162:163], 0, s[30:31]
	global_load_lds_dwordx4 v[218:219], off
	s_add_i32 m0, s39, 0x2000
	s_nop 0
	global_load_lds_dwordx4 v[162:163], off
	v_lshl_add_u64 v[162:163], v[216:217], 0, s[24:25]
	s_mov_b32 m0, s62
	s_nop 0
	global_load_lds_dwordx4 v[162:163], off
	v_lshl_add_u64 v[162:163], v[216:217], 0, s[26:27]
	s_mov_b32 m0, s63
	s_nop 0
	global_load_lds_dwordx4 v[162:163], off
	s_waitcnt vmcnt(8)
	s_waitcnt lgkmcnt(0)
	s_barrier
	s_setprio 1
	s_waitcnt lgkmcnt(0)
	v_mfma_f32_16x16x32_bf16 v[62:65], v[114:117], v[184:187], v[62:65]
	v_mfma_f32_16x16x32_bf16 v[62:65], v[126:129], v[188:191], v[62:65]
	v_mfma_f32_16x16x32_bf16 v[46:49], v[126:129], v[196:199], v[46:49]
	v_mfma_f32_16x16x32_bf16 v[46:49], v[114:117], v[192:195], v[46:49]
	v_mfma_f32_16x16x32_bf16 v[30:33], v[114:117], v[200:203], v[30:33]
	v_mfma_f32_16x16x32_bf16 v[30:33], v[126:129], v[204:207], v[30:33]
	v_mfma_f32_16x16x32_bf16 v[14:17], v[126:129], v[212:215], v[14:17]
	v_mfma_f32_16x16x32_bf16 v[14:17], v[114:117], v[208:211], v[14:17]
	v_mfma_f32_16x16x32_bf16 v[10:13], v[130:133], v[208:211], v[10:13]
	v_mfma_f32_16x16x32_bf16 v[10:13], v[142:145], v[212:215], v[10:13]
	v_mfma_f32_16x16x32_bf16 v[26:29], v[142:145], v[204:207], v[26:29]
	v_mfma_f32_16x16x32_bf16 v[26:29], v[130:133], v[200:203], v[26:29]
	v_mfma_f32_16x16x32_bf16 v[42:45], v[130:133], v[192:195], v[42:45]
	v_mfma_f32_16x16x32_bf16 v[42:45], v[142:145], v[196:199], v[42:45]
	v_mfma_f32_16x16x32_bf16 v[58:61], v[142:145], v[188:191], v[58:61]
	v_mfma_f32_16x16x32_bf16 v[58:61], v[130:133], v[184:187], v[58:61]
	v_mfma_f32_16x16x32_bf16 v[54:57], v[146:149], v[184:187], v[54:57]
	v_mfma_f32_16x16x32_bf16 v[54:57], v[150:153], v[188:191], v[54:57]
	v_mfma_f32_16x16x32_bf16 v[38:41], v[150:153], v[196:199], v[38:41]
	v_mfma_f32_16x16x32_bf16 v[38:41], v[146:149], v[192:195], v[38:41]
	v_mfma_f32_16x16x32_bf16 v[22:25], v[146:149], v[200:203], v[22:25]
	v_mfma_f32_16x16x32_bf16 v[22:25], v[150:153], v[204:207], v[22:25]
	v_mfma_f32_16x16x32_bf16 v[6:9], v[150:153], v[212:215], v[6:9]
	v_mfma_f32_16x16x32_bf16 v[6:9], v[146:149], v[208:211], v[6:9]
	v_mfma_f32_16x16x32_bf16 v[2:5], v[174:177], v[208:211], v[2:5]
	v_mfma_f32_16x16x32_bf16 v[2:5], v[178:181], v[212:215], v[2:5]
	v_mfma_f32_16x16x32_bf16 v[18:21], v[178:181], v[204:207], v[18:21]
	v_mfma_f32_16x16x32_bf16 v[18:21], v[174:177], v[200:203], v[18:21]
	s_barrier
	s_setprio 2
	v_mfma_f32_16x16x32_bf16 v[34:37], v[174:177], v[192:195], v[34:37]
	v_mfma_f32_16x16x32_bf16 v[34:37], v[178:181], v[196:199], v[34:37]
	v_mfma_f32_16x16x32_bf16 v[50:53], v[178:181], v[188:191], v[50:53]
	v_mfma_f32_16x16x32_bf16 v[50:53], v[174:177], v[184:187], v[50:53]
	s_setprio 0
	s_add_u32 s68, s68, 0x1000
	s_addc_u32 s69, s69, 0
	s_add_u32 s11, s11, 0x1000
	s_addc_u32 s37, s37, 0
	s_cmp_ge_i32 s41, s79
	s_mov_b32 s39, s41
	s_cbranch_scc0 .LBB0_1533
	s_and_b64 vcc, exec, s[34:35]
	s_cbranch_vccnz .LBB0_1538
	s_lshl_b32 s11, s2, 8
	s_cmp_gt_i32 s2, 63
	s_mov_b64 s[68:69], -1
	s_cbranch_scc1 .LBB0_1539

; #define PG8_STAGE(bufoff, gbase, voff) do { if constexpr (!pg8_noload<Epi>::value) { _Pragma("unroll") for (int _i = 0; _i < 2; ++_i) \
;         __builtin_amdgcn_global_load_lds((const unsigned*)((const char*)(gbase) + (size_t)_i * pstep + (voff)[0]), (PG8_LAS unsigned*)(lds + (bufoff) + ldsw + _i * 8192), 16, 0, 0); } } while (0)
; #define PG8_LDA(dst, b, h) do { _Pragma("unroll") for (int m = 0; m < 4; ++m) _Pragma("unroll") for (int k = 0; k < 2; ++k) dst[m][k] = *(const PG8_LAS bf16x8*)(lds + PG8_SA(b, h) + aoff + m * 2048 + k * 1024); } while (0)
; #define PG8_LDB(dst, b, h) do { _Pragma("unroll") for (int n = 0; n < 2; ++n) _Pragma("unroll") for (int k = 0; k < 2; ++k) dst[n][k] = *(const PG8_LAS bf16x8*)(lds + PG8_SB(b, h) + boff + n * 2048 + k * 1024); } while (0)
; #define PG8_MMA(ai, bj, At, Bt) do { __builtin_amdgcn_s_setprio(1); _Pragma("unroll") for (int m = 0; m < 4; ++m) _Pragma("unroll") for (int n = 0; n < 2; ++n) _Pragma("unroll") for (int k = 0; k < 2; ++k) \
;         acc[ai][bj][m][n] = __builtin_amdgcn_mfma_f32_16x16x32_bf16(Bt[n][k], At[m][k], acc[ai][bj][m][n], 0, 0, 0); __builtin_amdgcn_s_setprio(0); } while (0)
; #define PG8_WAIT_V(n) asm volatile("s_waitcnt vmcnt(" #n ")" ::: "memory")
; #define PG8_WAIT_L(n) asm volatile("s_waitcnt lgkmcnt(" #n ")" ::: "memory")
; #define PG8_BAR __builtin_amdgcn_s_barrier()
; #define PG8_SCHED __builtin_amdgcn_sched_barrier(0)
; template <class Epi, class Sched, bool ALIGN_EPI = false, bool SP2 = false, bool ABLK = false>
; __device__ __forceinline__ void gemm_phase(PG8_LAS unsigned char* lds, const Gemm g, const Sched& S, const Epi& E) {
;     ...
;             const char* a1 = cA + (size_t)(t + 1) * kstep;
;             const char* a2 = last ? nA : cA + (size_t)(t + 2) * kstep; const char* b2 = last ? nB : cB + (size_t)(t + 2) * kstepB;
;             const char* a3 = a2 + kstep; const char* b3 = b2 + kstepB;
;             if (last && has_next) S.a_ready(nxt);
;             if constexpr (SP2) {
;             PG8_LDB(B0, 0, 0); PG8_LDB(B1, 0, 1); PG8_SCHED; PG8_LDA(At, 0, 0); PG8_STAGE(PG8_SA(1, 1), a1 + hstep, voffA);
;             PG8_WAIT_V(8); PG8_WAIT_L(0); PG8_BAR; PG8_MMA(0, 0, At, B0); PG8_MMA(0, 1, At, B1); PG8_BAR; PG8_SCHED;
;             PG8_LDA(At, 0, 1); PG8_STAGE(PG8_SB(0, 0), b2, voffB); PG8_STAGE(PG8_SB(0, 1), b2 + hstep, voffB); PG8_STAGE(PG8_SA(0, 0), a2, voffA);
.LBB0_1657:
	s_or_b32 s26, s94, 1
	s_lshl_b64 s[82:83], s[26:27], 11
	s_add_u32 s88, s74, s82
	v_add_u32_e32 v140, s12, v173
	s_addc_u32 s89, s75, s83
	s_add_i32 s26, s94, 2
	ds_read_b128 v[130:133], v140
	ds_read_b128 v[134:137], v140 offset:1024
	ds_read_b128 v[154:157], v140 offset:2048
	ds_read_b128 v[158:161], v140 offset:3072
	v_add_u32_e32 v140, s13, v173
	s_lshl_b64 s[90:91], s[26:27], 11
	ds_read_b128 v[162:165], v140
	ds_read_b128 v[166:169], v140 offset:1024
	ds_read_b128 v[184:187], v140 offset:2048
	ds_read_b128 v[188:191], v140 offset:3072
	s_add_u32 s92, s74, s90
	s_addc_u32 s93, s75, s91
	s_and_b64 s[82:83], s[80:81], exec
	s_cselect_b32 s83, s93, s3
	s_cselect_b32 s82, s92, s25
	s_add_u32 s90, s76, s90
	s_addc_u32 s91, s77, s91
	s_and_b64 s[80:81], s[80:81], exec
	s_cselect_b32 s81, s91, s65
	s_cselect_b32 s80, s90, s67
	v_lshl_add_u64 v[170:171], s[88:89], 0, v[138:139]
	v_lshl_add_u64 v[224:225], v[170:171], 0, s[20:21]
	s_add_i32 m0, s56, 0xc000
	ds_read_b128 v[192:195], v178
	ds_read_b128 v[196:199], v178 offset:1024
	ds_read_b128 v[200:203], v178 offset:2048
	ds_read_b128 v[204:207], v178 offset:3072
	ds_read_b128 v[208:211], v178 offset:4096
	ds_read_b128 v[212:215], v178 offset:5120
	ds_read_b128 v[216:219], v178 offset:6144
	ds_read_b128 v[220:223], v178 offset:7168
	global_load_lds_dwordx4 v[224:225], off
	v_lshl_add_u64 v[170:171], v[170:171], 0, s[22:23]
	s_add_i32 m0, s56, 0xe000
	s_nop 0
	global_load_lds_dwordx4 v[170:171], off
	s_waitcnt vmcnt(8)
	s_waitcnt lgkmcnt(0)
	s_barrier
	s_setprio 1
	s_waitcnt lgkmcnt(0)
	v_mfma_f32_16x16x32_bf16 v[126:129], v[130:133], v[192:195], v[126:129]
	v_mfma_f32_16x16x32_bf16 v[126:129], v[134:137], v[196:199], v[126:129]
	v_mfma_f32_16x16x32_bf16 v[110:113], v[134:137], v[204:207], v[110:113]
	v_mfma_f32_16x16x32_bf16 v[110:113], v[130:133], v[200:203], v[110:113]
	v_mfma_f32_16x16x32_bf16 v[94:97], v[130:133], v[208:211], v[94:97]
	v_mfma_f32_16x16x32_bf16 v[94:97], v[134:137], v[212:215], v[94:97]
	v_mfma_f32_16x16x32_bf16 v[78:81], v[134:137], v[220:223], v[78:81]
	v_mfma_f32_16x16x32_bf16 v[78:81], v[130:133], v[216:219], v[78:81]
	v_mfma_f32_16x16x32_bf16 v[74:77], v[154:157], v[216:219], v[74:77]
	v_mfma_f32_16x16x32_bf16 v[74:77], v[158:161], v[220:223], v[74:77]
	v_mfma_f32_16x16x32_bf16 v[90:93], v[158:161], v[212:215], v[90:93]
	v_mfma_f32_16x16x32_bf16 v[90:93], v[154:157], v[208:211], v[90:93]
	v_mfma_f32_16x16x32_bf16 v[106:109], v[154:157], v[200:203], v[106:109]
	v_mfma_f32_16x16x32_bf16 v[106:109], v[158:161], v[204:207], v[106:109]
	v_mfma_f32_16x16x32_bf16 v[122:125], v[158:161], v[196:199], v[122:125]
	v_mfma_f32_16x16x32_bf16 v[122:125], v[154:157], v[192:195], v[122:125]
	v_mfma_f32_16x16x32_bf16 v[118:121], v[162:165], v[192:195], v[118:121]
	v_mfma_f32_16x16x32_bf16 v[118:121], v[166:169], v[196:199], v[118:121]
	v_mfma_f32_16x16x32_bf16 v[102:105], v[166:169], v[204:207], v[102:105]
	v_mfma_f32_16x16x32_bf16 v[102:105], v[162:165], v[200:203], v[102:105]
	v_mfma_f32_16x16x32_bf16 v[86:89], v[162:165], v[208:211], v[86:89]
	v_mfma_f32_16x16x32_bf16 v[86:89], v[166:169], v[212:215], v[86:89]
	v_mfma_f32_16x16x32_bf16 v[70:73], v[166:169], v[220:223], v[70:73]
	v_mfma_f32_16x16x32_bf16 v[70:73], v[162:165], v[216:219], v[70:73]
	v_mfma_f32_16x16x32_bf16 v[66:69], v[184:187], v[216:219], v[66:69]
	v_mfma_f32_16x16x32_bf16 v[66:69], v[188:191], v[220:223], v[66:69]
	v_mfma_f32_16x16x32_bf16 v[82:85], v[188:191], v[212:215], v[82:85]
	v_mfma_f32_16x16x32_bf16 v[82:85], v[184:187], v[208:211], v[82:85]
	s_barrier
	s_setprio 2
	v_mfma_f32_16x16x32_bf16 v[98:101], v[184:187], v[200:203], v[98:101]
	v_mfma_f32_16x16x32_bf16 v[98:101], v[188:191], v[204:207], v[98:101]
	v_mfma_f32_16x16x32_bf16 v[114:117], v[188:191], v[196:199], v[114:117]
	v_mfma_f32_16x16x32_bf16 v[114:117], v[184:187], v[192:195], v[114:117]
	s_setprio 0
	v_lshl_add_u64 v[170:171], s[80:81], 0, v[138:139]
	s_add_i32 s80, s12, s55
	s_mov_b32 m0, s80
	ds_read_b128 v[192:195], v178 offset:16384
	ds_read_b128 v[196:199], v178 offset:17408
	ds_read_b128 v[200:203], v178 offset:18432
	ds_read_b128 v[204:207], v178 offset:19456
	ds_read_b128 v[208:211], v178 offset:20480
	ds_read_b128 v[212:215], v178 offset:21504
	ds_read_b128 v[216:219], v178 offset:22528
	ds_read_b128 v[220:223], v178 offset:23552
	global_load_lds_dwordx4 v[170:171], off
	v_lshl_add_u64 v[224:225], v[170:171], 0, s[18:19]
	s_add_i32 m0, s80, 0x2000
	s_add_i32 s80, s13, s55
	global_load_lds_dwordx4 v[224:225], off
	v_lshl_add_u64 v[224:225], v[170:171], 0, s[20:21]
	s_mov_b32 m0, s80
	s_nop 0
	global_load_lds_dwordx4 v[224:225], off
	v_lshl_add_u64 v[224:225], v[170:171], 0, s[22:23]
	s_add_i32 m0, s80, 0x2000
	s_nop 0
	global_load_lds_dwordx4 v[224:225], off
	v_lshl_add_u64 v[224:225], s[82:83], 0, v[138:139]
	s_mov_b32 m0, s56
	v_lshl_add_u64 v[226:227], v[224:225], 0, s[18:19]
	global_load_lds_dwordx4 v[224:225], off
	s_mov_b32 m0, s57
	s_nop 0
	global_load_lds_dwordx4 v[226:227], off
	s_waitcnt vmcnt(8)
	s_waitcnt lgkmcnt(0)
	s_barrier
; #define PG8_STAGE(bufoff, gbase, voff) do { if constexpr (!pg8_noload<Epi>::value) { _Pragma("unroll") for (int _i = 0; _i < 2; ++_i) \
;         __builtin_amdgcn_global_load_lds((const unsigned*)((const char*)(gbase) + (size_t)_i * pstep + (voff)[0]), (PG8_LAS unsigned*)(lds + (bufoff) + ldsw + _i * 8192), 16, 0, 0); } } while (0)
; #define PG8_LDA(dst, b, h) do { _Pragma("unroll") for (int m = 0; m < 4; ++m) _Pragma("unroll") for (int k = 0; k < 2; ++k) dst[m][k] = *(const PG8_LAS bf16x8*)(lds + PG8_SA(b, h) + aoff + m * 2048 + k * 1024); } while (0)
; #define PG8_LDB(dst, b, h) do { _Pragma("unroll") for (int n = 0; n < 2; ++n) _Pragma("unroll") for (int k = 0; k < 2; ++k) dst[n][k] = *(const PG8_LAS bf16x8*)(lds + PG8_SB(b, h) + boff + n * 2048 + k * 1024); } while (0)
; #define PG8_MMA(ai, bj, At, Bt) do { __builtin_amdgcn_s_setprio(1); _Pragma("unroll") for (int m = 0; m < 4; ++m) _Pragma("unroll") for (int n = 0; n < 2; ++n) _Pragma("unroll") for (int k = 0; k < 2; ++k) \
;         acc[ai][bj][m][n] = __builtin_amdgcn_mfma_f32_16x16x32_bf16(Bt[n][k], At[m][k], acc[ai][bj][m][n], 0, 0, 0); __builtin_amdgcn_s_setprio(0); } while (0)
; #define PG8_WAIT_V(n) asm volatile("s_waitcnt vmcnt(" #n ")" ::: "memory")
; #define PG8_WAIT_L(n) asm volatile("s_waitcnt lgkmcnt(" #n ")" ::: "memory")
; #define PG8_BAR __builtin_amdgcn_s_barrier()
; #define PG8_SCHED __builtin_amdgcn_sched_barrier(0)
; template <class Epi, class Sched, bool ALIGN_EPI = false, bool SP2 = false, bool ABLK = false>
; __device__ __forceinline__ void gemm_phase(PG8_LAS unsigned char* lds, const Gemm g, const Sched& S, const Epi& E) {
;     ...
;             PG8_WAIT_V(8); PG8_WAIT_L(0); PG8_BAR; PG8_MMA(1, 0, At, B0); PG8_MMA(1, 1, At, B1); PG8_BAR; PG8_SCHED;
;             PG8_LDB(B0, 1, 0); PG8_LDB(B1, 1, 1); PG8_SCHED; PG8_LDA(At, 1, 0); PG8_STAGE(PG8_SA(0, 1), a2 + hstep, voffA);
;             PG8_WAIT_V(8); PG8_WAIT_L(0); PG8_BAR; PG8_MMA(0, 0, At, B0); PG8_MMA(0, 1, At, B1); PG8_BAR; PG8_SCHED;
	s_setprio 1
	s_waitcnt lgkmcnt(0)
	v_mfma_f32_16x16x32_bf16 v[62:65], v[130:133], v[192:195], v[62:65]
	v_mfma_f32_16x16x32_bf16 v[62:65], v[134:137], v[196:199], v[62:65]
	v_mfma_f32_16x16x32_bf16 v[46:49], v[134:137], v[204:207], v[46:49]
	v_mfma_f32_16x16x32_bf16 v[46:49], v[130:133], v[200:203], v[46:49]
	v_mfma_f32_16x16x32_bf16 v[30:33], v[130:133], v[208:211], v[30:33]
	v_mfma_f32_16x16x32_bf16 v[30:33], v[134:137], v[212:215], v[30:33]
	v_mfma_f32_16x16x32_bf16 v[14:17], v[134:137], v[220:223], v[14:17]
	v_mfma_f32_16x16x32_bf16 v[14:17], v[130:133], v[216:219], v[14:17]
	v_mfma_f32_16x16x32_bf16 v[10:13], v[154:157], v[216:219], v[10:13]
	v_mfma_f32_16x16x32_bf16 v[10:13], v[158:161], v[220:223], v[10:13]
	v_mfma_f32_16x16x32_bf16 v[26:29], v[158:161], v[212:215], v[26:29]
	v_mfma_f32_16x16x32_bf16 v[26:29], v[154:157], v[208:211], v[26:29]
	v_mfma_f32_16x16x32_bf16 v[42:45], v[154:157], v[200:203], v[42:45]
	v_mfma_f32_16x16x32_bf16 v[42:45], v[158:161], v[204:207], v[42:45]
	v_mfma_f32_16x16x32_bf16 v[58:61], v[158:161], v[196:199], v[58:61]
	v_mfma_f32_16x16x32_bf16 v[58:61], v[154:157], v[192:195], v[58:61]
	v_mfma_f32_16x16x32_bf16 v[54:57], v[162:165], v[192:195], v[54:57]
	v_mfma_f32_16x16x32_bf16 v[54:57], v[166:169], v[196:199], v[54:57]
	s_add_i32 s80, 0, 0x18000
	v_add_u32_e32 v140, s80, v173
	ds_read_b128 v[130:133], v140
	v_mfma_f32_16x16x32_bf16 v[38:41], v[166:169], v[204:207], v[38:41]
	v_mfma_f32_16x16x32_bf16 v[38:41], v[162:165], v[200:203], v[38:41]
	ds_read_b128 v[134:137], v140 offset:1024
	v_mfma_f32_16x16x32_bf16 v[22:25], v[162:165], v[208:211], v[22:25]
	v_mfma_f32_16x16x32_bf16 v[22:25], v[166:169], v[212:215], v[22:25]
	ds_read_b128 v[154:157], v140 offset:2048
	v_mfma_f32_16x16x32_bf16 v[6:9], v[166:169], v[220:223], v[6:9]
	v_mfma_f32_16x16x32_bf16 v[6:9], v[162:165], v[216:219], v[6:9]
	ds_read_b128 v[158:161], v140 offset:3072
	v_mfma_f32_16x16x32_bf16 v[2:5], v[184:187], v[216:219], v[2:5]
	v_mfma_f32_16x16x32_bf16 v[2:5], v[188:191], v[220:223], v[2:5]
	v_mfma_f32_16x16x32_bf16 v[18:21], v[188:191], v[212:215], v[18:21]
	v_mfma_f32_16x16x32_bf16 v[18:21], v[184:187], v[208:211], v[18:21]
	s_barrier
	s_setprio 2
	v_mfma_f32_16x16x32_bf16 v[34:37], v[184:187], v[200:203], v[34:37]
	v_mfma_f32_16x16x32_bf16 v[34:37], v[188:191], v[204:207], v[34:37]
	v_mfma_f32_16x16x32_bf16 v[50:53], v[188:191], v[196:199], v[50:53]
	v_mfma_f32_16x16x32_bf16 v[50:53], v[184:187], v[192:195], v[50:53]
	s_setprio 0
	s_add_i32 s81, 0, 0x1c000
	v_add_u32_e32 v140, s81, v173
	ds_read_b128 v[162:165], v140
	ds_read_b128 v[166:169], v140 offset:1024
	ds_read_b128 v[184:187], v140 offset:2048
	ds_read_b128 v[188:191], v140 offset:3072
	s_mov_b32 m0, s58
	v_lshl_add_u64 v[226:227], v[224:225], 0, s[20:21]
	ds_read_b128 v[192:195], v178 offset:32768
	ds_read_b128 v[196:199], v178 offset:33792
	ds_read_b128 v[200:203], v178 offset:34816
	ds_read_b128 v[204:207], v178 offset:35840
	ds_read_b128 v[208:211], v178 offset:36864
	ds_read_b128 v[212:215], v178 offset:37888
	ds_read_b128 v[216:219], v178 offset:38912
	ds_read_b128 v[220:223], v178 offset:39936
	global_load_lds_dwordx4 v[226:227], off
	v_lshl_add_u64 v[226:227], v[224:225], 0, s[22:23]
	s_mov_b32 m0, s59
	s_nop 0
	global_load_lds_dwordx4 v[226:227], off
	s_waitcnt vmcnt(8)
	s_waitcnt lgkmcnt(0)
	s_barrier
	s_setprio 1
	s_waitcnt lgkmcnt(0)
	v_mfma_f32_16x16x32_bf16 v[126:129], v[130:133], v[192:195], v[126:129]
	v_mfma_f32_16x16x32_bf16 v[126:129], v[134:137], v[196:199], v[126:129]
	v_mfma_f32_16x16x32_bf16 v[110:113], v[134:137], v[204:207], v[110:113]
	v_mfma_f32_16x16x32_bf16 v[110:113], v[130:133], v[200:203], v[110:113]
	v_mfma_f32_16x16x32_bf16 v[94:97], v[130:133], v[208:211], v[94:97]
	v_mfma_f32_16x16x32_bf16 v[94:97], v[134:137], v[212:215], v[94:97]
	v_mfma_f32_16x16x32_bf16 v[78:81], v[134:137], v[220:223], v[78:81]
	v_mfma_f32_16x16x32_bf16 v[78:81], v[130:133], v[216:219], v[78:81]
	v_mfma_f32_16x16x32_bf16 v[74:77], v[154:157], v[216:219], v[74:77]
	v_mfma_f32_16x16x32_bf16 v[74:77], v[158:161], v[220:223], v[74:77]
	v_mfma_f32_16x16x32_bf16 v[90:93], v[158:161], v[212:215], v[90:93]
	v_mfma_f32_16x16x32_bf16 v[90:93], v[154:157], v[208:211], v[90:93]
	v_mfma_f32_16x16x32_bf16 v[106:109], v[154:157], v[200:203], v[106:109]
	v_mfma_f32_16x16x32_bf16 v[106:109], v[158:161], v[204:207], v[106:109]
	v_mfma_f32_16x16x32_bf16 v[122:125], v[158:161], v[196:199], v[122:125]
	v_mfma_f32_16x16x32_bf16 v[122:125], v[154:157], v[192:195], v[122:125]
	v_mfma_f32_16x16x32_bf16 v[118:121], v[162:165], v[192:195], v[118:121]
	v_mfma_f32_16x16x32_bf16 v[118:121], v[166:169], v[196:199], v[118:121]
	v_mfma_f32_16x16x32_bf16 v[102:105], v[166:169], v[204:207], v[102:105]
	v_mfma_f32_16x16x32_bf16 v[102:105], v[162:165], v[200:203], v[102:105]
	v_mfma_f32_16x16x32_bf16 v[86:89], v[162:165], v[208:211], v[86:89]
	v_mfma_f32_16x16x32_bf16 v[86:89], v[166:169], v[212:215], v[86:89]
	v_mfma_f32_16x16x32_bf16 v[70:73], v[166:169], v[220:223], v[70:73]
	v_mfma_f32_16x16x32_bf16 v[70:73], v[162:165], v[216:219], v[70:73]
	v_mfma_f32_16x16x32_bf16 v[66:69], v[184:187], v[216:219], v[66:69]
	v_mfma_f32_16x16x32_bf16 v[66:69], v[188:191], v[220:223], v[66:69]
	v_mfma_f32_16x16x32_bf16 v[82:85], v[188:191], v[212:215], v[82:85]
	v_mfma_f32_16x16x32_bf16 v[82:85], v[184:187], v[208:211], v[82:85]
	s_barrier
; #define PG8_STAGE(bufoff, gbase, voff) do { if constexpr (!pg8_noload<Epi>::value) { _Pragma("unroll") for (int _i = 0; _i < 2; ++_i) \
;         __builtin_amdgcn_global_load_lds((const unsigned*)((const char*)(gbase) + (size_t)_i * pstep + (voff)[0]), (PG8_LAS unsigned*)(lds + (bufoff) + ldsw + _i * 8192), 16, 0, 0); } } while (0)
; #define PG8_LDA(dst, b, h) do { _Pragma("unroll") for (int m = 0; m < 4; ++m) _Pragma("unroll") for (int k = 0; k < 2; ++k) dst[m][k] = *(const PG8_LAS bf16x8*)(lds + PG8_SA(b, h) + aoff + m * 2048 + k * 1024); } while (0)
; #define PG8_MMA(ai, bj, At, Bt) do { __builtin_amdgcn_s_setprio(1); _Pragma("unroll") for (int m = 0; m < 4; ++m) _Pragma("unroll") for (int n = 0; n < 2; ++n) _Pragma("unroll") for (int k = 0; k < 2; ++k) \
;         acc[ai][bj][m][n] = __builtin_amdgcn_mfma_f32_16x16x32_bf16(Bt[n][k], At[m][k], acc[ai][bj][m][n], 0, 0, 0); __builtin_amdgcn_s_setprio(0); } while (0)
; #define PG8_WAIT_V(n) asm volatile("s_waitcnt vmcnt(" #n ")" ::: "memory")
; #define PG8_WAIT_L(n) asm volatile("s_waitcnt lgkmcnt(" #n ")" ::: "memory")
; #define PG8_BAR __builtin_amdgcn_s_barrier()
; #define PG8_SCHED __builtin_amdgcn_sched_barrier(0)
; template <class Epi, class Sched, bool ALIGN_EPI = false, bool SP2 = false, bool ABLK = false>
; __device__ __forceinline__ void gemm_phase(PG8_LAS unsigned char* lds, const Gemm g, const Sched& S, const Epi& E) {
;     ...
;         for (int t = 0; t < nt; t += 2) {
;     ...
;             PG8_WAIT_V(8); PG8_WAIT_L(0); PG8_BAR; PG8_MMA(0, 0, At, B0); PG8_MMA(0, 1, At, B1); PG8_BAR; PG8_SCHED;
;             PG8_LDA(At, 1, 1); PG8_STAGE(PG8_SB(1, 0), b3, voffB); PG8_STAGE(PG8_SB(1, 1), b3 + hstep, voffB); PG8_STAGE(PG8_SA(1, 0), a3, voffA);
;             PG8_WAIT_V(8); PG8_WAIT_L(0); PG8_BAR; PG8_MMA(1, 0, At, B0); PG8_MMA(1, 1, At, B1); PG8_BAR; PG8_SCHED;
	s_setprio 2
	v_mfma_f32_16x16x32_bf16 v[98:101], v[184:187], v[200:203], v[98:101]
	v_mfma_f32_16x16x32_bf16 v[98:101], v[188:191], v[204:207], v[98:101]
	v_mfma_f32_16x16x32_bf16 v[114:117], v[188:191], v[196:199], v[114:117]
	v_mfma_f32_16x16x32_bf16 v[114:117], v[184:187], v[192:195], v[114:117]
	s_setprio 0
	s_add_i32 s80, s80, s55
	v_lshl_add_u64 v[226:227], v[170:171], 0, s[30:31]
	s_mov_b32 m0, s80
	ds_read_b128 v[192:195], v178 offset:49152
	ds_read_b128 v[196:199], v178 offset:50176
	ds_read_b128 v[200:203], v178 offset:51200
	ds_read_b128 v[204:207], v178 offset:52224
	ds_read_b128 v[208:211], v178 offset:53248
	ds_read_b128 v[212:215], v178 offset:54272
	ds_read_b128 v[216:219], v178 offset:55296
	ds_read_b128 v[220:223], v178 offset:56320
	global_load_lds_dwordx4 v[226:227], off
	v_lshl_add_u64 v[226:227], v[170:171], 0, s[34:35]
	s_add_i32 m0, s80, 0x2000
	s_add_i32 s80, s81, s55
	global_load_lds_dwordx4 v[226:227], off
	v_lshl_add_u64 v[226:227], v[170:171], 0, s[36:37]
	s_mov_b32 m0, s80
	v_lshl_add_u64 v[170:171], v[170:171], 0, s[38:39]
	global_load_lds_dwordx4 v[226:227], off
	s_add_i32 m0, s80, 0x2000
	s_nop 0
	global_load_lds_dwordx4 v[170:171], off
	v_lshl_add_u64 v[170:171], v[224:225], 0, s[30:31]
	s_mov_b32 m0, s63
	s_nop 0
	global_load_lds_dwordx4 v[170:171], off
	v_lshl_add_u64 v[170:171], v[224:225], 0, s[34:35]
	s_mov_b32 m0, s73
	s_nop 0
	global_load_lds_dwordx4 v[170:171], off
	s_waitcnt vmcnt(8)
	s_waitcnt lgkmcnt(0)
	s_barrier
	s_setprio 1
	s_waitcnt lgkmcnt(0)
	v_mfma_f32_16x16x32_bf16 v[62:65], v[130:133], v[192:195], v[62:65]
	v_mfma_f32_16x16x32_bf16 v[62:65], v[134:137], v[196:199], v[62:65]
	v_mfma_f32_16x16x32_bf16 v[46:49], v[134:137], v[204:207], v[46:49]
	v_mfma_f32_16x16x32_bf16 v[46:49], v[130:133], v[200:203], v[46:49]
	v_mfma_f32_16x16x32_bf16 v[30:33], v[130:133], v[208:211], v[30:33]
	v_mfma_f32_16x16x32_bf16 v[30:33], v[134:137], v[212:215], v[30:33]
	v_mfma_f32_16x16x32_bf16 v[14:17], v[134:137], v[220:223], v[14:17]
	v_mfma_f32_16x16x32_bf16 v[14:17], v[130:133], v[216:219], v[14:17]
	v_mfma_f32_16x16x32_bf16 v[10:13], v[154:157], v[216:219], v[10:13]
	v_mfma_f32_16x16x32_bf16 v[10:13], v[158:161], v[220:223], v[10:13]
	v_mfma_f32_16x16x32_bf16 v[26:29], v[158:161], v[212:215], v[26:29]
	v_mfma_f32_16x16x32_bf16 v[26:29], v[154:157], v[208:211], v[26:29]
	v_mfma_f32_16x16x32_bf16 v[42:45], v[154:157], v[200:203], v[42:45]
	v_mfma_f32_16x16x32_bf16 v[42:45], v[158:161], v[204:207], v[42:45]
	v_mfma_f32_16x16x32_bf16 v[58:61], v[158:161], v[196:199], v[58:61]
	v_mfma_f32_16x16x32_bf16 v[58:61], v[154:157], v[192:195], v[58:61]
	v_mfma_f32_16x16x32_bf16 v[54:57], v[162:165], v[192:195], v[54:57]
	v_mfma_f32_16x16x32_bf16 v[54:57], v[166:169], v[196:199], v[54:57]
	v_mfma_f32_16x16x32_bf16 v[38:41], v[166:169], v[204:207], v[38:41]
	v_mfma_f32_16x16x32_bf16 v[38:41], v[162:165], v[200:203], v[38:41]
	v_mfma_f32_16x16x32_bf16 v[22:25], v[162:165], v[208:211], v[22:25]
	v_mfma_f32_16x16x32_bf16 v[22:25], v[166:169], v[212:215], v[22:25]
	v_mfma_f32_16x16x32_bf16 v[6:9], v[166:169], v[220:223], v[6:9]
	v_mfma_f32_16x16x32_bf16 v[6:9], v[162:165], v[216:219], v[6:9]
	v_mfma_f32_16x16x32_bf16 v[2:5], v[184:187], v[216:219], v[2:5]
	v_mfma_f32_16x16x32_bf16 v[2:5], v[188:191], v[220:223], v[2:5]
	v_mfma_f32_16x16x32_bf16 v[18:21], v[188:191], v[212:215], v[18:21]
	v_mfma_f32_16x16x32_bf16 v[18:21], v[184:187], v[208:211], v[18:21]
	s_barrier
	s_setprio 2
	v_mfma_f32_16x16x32_bf16 v[34:37], v[184:187], v[200:203], v[34:37]
	v_mfma_f32_16x16x32_bf16 v[34:37], v[188:191], v[204:207], v[34:37]
	v_mfma_f32_16x16x32_bf16 v[50:53], v[188:191], v[196:199], v[50:53]
	v_mfma_f32_16x16x32_bf16 v[50:53], v[184:187], v[192:195], v[50:53]
	s_setprio 0
	s_cmp_gt_u32 s94, 29
	s_mov_b32 s94, s26
	s_cbranch_scc1 .LBB0_1669

; #define PG8_STAGE(bufoff, gbase, voff) do { if constexpr (!pg8_noload<Epi>::value) { _Pragma("unroll") for (int _i = 0; _i < 2; ++_i) \
;         __builtin_amdgcn_global_load_lds((const unsigned*)((const char*)(gbase) + (size_t)_i * pstep + (voff)[0]), (PG8_LAS unsigned*)(lds + (bufoff) + ldsw + _i * 8192), 16, 0, 0); } } while (0)
; #define PG8_LDA(dst, b, h) do { _Pragma("unroll") for (int m = 0; m < 4; ++m) _Pragma("unroll") for (int k = 0; k < 2; ++k) dst[m][k] = *(const PG8_LAS bf16x8*)(lds + PG8_SA(b, h) + aoff + m * 2048 + k * 1024); } while (0)
; #define PG8_LDB(dst, b, h) do { _Pragma("unroll") for (int n = 0; n < 2; ++n) _Pragma("unroll") for (int k = 0; k < 2; ++k) dst[n][k] = *(const PG8_LAS bf16x8*)(lds + PG8_SB(b, h) + boff + n * 2048 + k * 1024); } while (0)
; #define PG8_MMA(ai, bj, At, Bt) do { __builtin_amdgcn_s_setprio(1); _Pragma("unroll") for (int m = 0; m < 4; ++m) _Pragma("unroll") for (int n = 0; n < 2; ++n) _Pragma("unroll") for (int k = 0; k < 2; ++k) \
;         acc[ai][bj][m][n] = __builtin_amdgcn_mfma_f32_16x16x32_bf16(Bt[n][k], At[m][k], acc[ai][bj][m][n], 0, 0, 0); __builtin_amdgcn_s_setprio(0); } while (0)
; #define PG8_WAIT_V(n) asm volatile("s_waitcnt vmcnt(" #n ")" ::: "memory")
; #define PG8_WAIT_L(n) asm volatile("s_waitcnt lgkmcnt(" #n ")" ::: "memory")
; #define PG8_BAR __builtin_amdgcn_s_barrier()
; template <class Epi, class Sched, bool ALIGN_EPI = false, bool SP2 = false, bool ABLK = false>
; __device__ __forceinline__ void gemm_phase(PG8_LAS unsigned char* lds, const Gemm g, const Sched& S, const Epi& E) {
;     ...
;             const bool last = (t == nt - 2);
;             const char* a1 = cA + (size_t)(t + 1) * kstep;
;             const char* a2 = last ? nA : cA + (size_t)(t + 2) * kstep; const char* b2 = last ? nB : cB + (size_t)(t + 2) * kstepB;
;             const char* a3 = a2 + kstep; const char* b3 = b2 + kstepB;
;             if (last && has_next) S.a_ready(nxt);
;             if constexpr (SP2) {
;             PG8_LDB(B0, 0, 0); PG8_LDB(B1, 0, 1); PG8_SCHED; PG8_LDA(At, 0, 0); PG8_STAGE(PG8_SA(1, 1), a1 + hstep, voffA);
;             PG8_WAIT_V(8); PG8_WAIT_L(0); PG8_BAR; PG8_MMA(0, 0, At, B0); PG8_MMA(0, 1, At, B1); PG8_BAR; PG8_SCHED;
;             PG8_LDA(At, 0, 1); PG8_STAGE(PG8_SB(0, 0), b2, voffB); PG8_STAGE(PG8_SB(0, 1), b2 + hstep, voffB); PG8_STAGE(PG8_SA(0, 0), a2, voffA);
.LBB0_1997:
	ds_read_b128 v[130:133], v175
	ds_read_b128 v[134:137], v175 offset:1024
	ds_read_b128 v[138:141], v175 offset:2048
	ds_read_b128 v[142:145], v175 offset:3072
	ds_read_b128 v[146:149], v176
	ds_read_b128 v[150:153], v176 offset:1024
	ds_read_b128 v[154:157], v176 offset:2048
	ds_read_b128 v[158:161], v176 offset:3072
	s_add_i32 s43, s41, 2
	s_add_u32 s62, s52, 0xfff80800
	s_addc_u32 s63, s53, -1
	s_cmp_eq_u32 s3, s41
	s_cselect_b32 s63, s45, s63
	s_cselect_b32 s62, s44, s62
	s_cselect_b32 s77, s47, s39
	s_cselect_b32 s76, s46, s11
	v_lshl_add_u64 v[170:171], s[52:53], 0, v[166:167]
	s_add_i32 m0, s49, 0xc000
	ds_read_b128 v[184:187], v177
	ds_read_b128 v[188:191], v177 offset:1024
	ds_read_b128 v[192:195], v177 offset:2048
	ds_read_b128 v[196:199], v177 offset:3072
	ds_read_b128 v[200:203], v177 offset:4096
	ds_read_b128 v[204:207], v177 offset:5120
	ds_read_b128 v[208:211], v177 offset:6144
	ds_read_b128 v[212:215], v177 offset:7168
	global_load_lds_dwordx4 v[170:171], off
	v_lshl_add_u64 v[170:171], v[170:171], 0, s[12:13]
	s_add_i32 m0, s49, 0xe000
	s_nop 0
	global_load_lds_dwordx4 v[170:171], off
	s_waitcnt vmcnt(8)
	s_waitcnt lgkmcnt(0)
	s_barrier
	s_setprio 1
	s_waitcnt lgkmcnt(0)
	v_mfma_f32_16x16x32_bf16 v[126:129], v[130:133], v[184:187], v[126:129]
	v_mfma_f32_16x16x32_bf16 v[126:129], v[134:137], v[188:191], v[126:129]
	v_mfma_f32_16x16x32_bf16 v[110:113], v[134:137], v[196:199], v[110:113]
	v_mfma_f32_16x16x32_bf16 v[110:113], v[130:133], v[192:195], v[110:113]
	v_mfma_f32_16x16x32_bf16 v[94:97], v[130:133], v[200:203], v[94:97]
	v_mfma_f32_16x16x32_bf16 v[94:97], v[134:137], v[204:207], v[94:97]
	v_mfma_f32_16x16x32_bf16 v[78:81], v[134:137], v[212:215], v[78:81]
	v_mfma_f32_16x16x32_bf16 v[78:81], v[130:133], v[208:211], v[78:81]
	v_mfma_f32_16x16x32_bf16 v[74:77], v[138:141], v[208:211], v[74:77]
	v_mfma_f32_16x16x32_bf16 v[74:77], v[142:145], v[212:215], v[74:77]
	v_mfma_f32_16x16x32_bf16 v[90:93], v[142:145], v[204:207], v[90:93]
	v_mfma_f32_16x16x32_bf16 v[90:93], v[138:141], v[200:203], v[90:93]
	v_mfma_f32_16x16x32_bf16 v[106:109], v[138:141], v[192:195], v[106:109]
	v_mfma_f32_16x16x32_bf16 v[106:109], v[142:145], v[196:199], v[106:109]
	v_mfma_f32_16x16x32_bf16 v[122:125], v[142:145], v[188:191], v[122:125]
	v_mfma_f32_16x16x32_bf16 v[122:125], v[138:141], v[184:187], v[122:125]
	v_mfma_f32_16x16x32_bf16 v[118:121], v[146:149], v[184:187], v[118:121]
	v_mfma_f32_16x16x32_bf16 v[118:121], v[150:153], v[188:191], v[118:121]
	v_mfma_f32_16x16x32_bf16 v[102:105], v[150:153], v[196:199], v[102:105]
	v_mfma_f32_16x16x32_bf16 v[102:105], v[146:149], v[192:195], v[102:105]
	v_mfma_f32_16x16x32_bf16 v[86:89], v[146:149], v[200:203], v[86:89]
	v_mfma_f32_16x16x32_bf16 v[86:89], v[150:153], v[204:207], v[86:89]
	v_mfma_f32_16x16x32_bf16 v[70:73], v[150:153], v[212:215], v[70:73]
	v_mfma_f32_16x16x32_bf16 v[70:73], v[146:149], v[208:211], v[70:73]
	v_mfma_f32_16x16x32_bf16 v[66:69], v[154:157], v[208:211], v[66:69]
	v_mfma_f32_16x16x32_bf16 v[66:69], v[158:161], v[212:215], v[66:69]
	v_mfma_f32_16x16x32_bf16 v[82:85], v[158:161], v[204:207], v[82:85]
	v_mfma_f32_16x16x32_bf16 v[82:85], v[154:157], v[200:203], v[82:85]
	s_barrier
	s_setprio 2
	v_mfma_f32_16x16x32_bf16 v[98:101], v[154:157], v[192:195], v[98:101]
	v_mfma_f32_16x16x32_bf16 v[98:101], v[158:161], v[196:199], v[98:101]
	v_mfma_f32_16x16x32_bf16 v[114:117], v[158:161], v[188:191], v[114:117]
	v_mfma_f32_16x16x32_bf16 v[114:117], v[154:157], v[184:187], v[114:117]
	s_setprio 0
	s_add_i32 s41, s70, s57
	v_lshl_add_u64 v[170:171], s[76:77], 0, v[162:163]
	s_mov_b32 m0, s41
	ds_read_b128 v[184:187], v177 offset:16384
	ds_read_b128 v[188:191], v177 offset:17408
	ds_read_b128 v[192:195], v177 offset:18432
	ds_read_b128 v[196:199], v177 offset:19456
	ds_read_b128 v[200:203], v177 offset:20480
	ds_read_b128 v[204:207], v177 offset:21504
	ds_read_b128 v[208:211], v177 offset:22528
	ds_read_b128 v[212:215], v177 offset:23552
	global_load_lds_dwordx4 v[170:171], off
	v_lshl_add_u64 v[216:217], v[170:171], 0, s[12:13]
	s_add_i32 m0, s41, 0x2000
	s_add_i32 s41, s71, s57
	global_load_lds_dwordx4 v[216:217], off
	v_lshl_add_u64 v[216:217], v[170:171], 0, s[14:15]
	s_mov_b32 m0, s41
	s_nop 0
	global_load_lds_dwordx4 v[216:217], off
	v_lshl_add_u64 v[216:217], v[170:171], 0, s[16:17]
	s_add_i32 m0, s41, 0x2000
	s_nop 0
	global_load_lds_dwordx4 v[216:217], off
	v_lshl_add_u64 v[216:217], s[62:63], 0, v[162:163]
	s_mov_b32 m0, s49
	v_lshl_add_u64 v[218:219], v[216:217], 0, s[12:13]
	global_load_lds_dwordx4 v[216:217], off
	s_mov_b32 m0, s58
	s_nop 0
	global_load_lds_dwordx4 v[218:219], off
	s_waitcnt vmcnt(8)
	s_waitcnt lgkmcnt(0)
	s_barrier
; #define PG8_STAGE(bufoff, gbase, voff) do { if constexpr (!pg8_noload<Epi>::value) { _Pragma("unroll") for (int _i = 0; _i < 2; ++_i) \
;         __builtin_amdgcn_global_load_lds((const unsigned*)((const char*)(gbase) + (size_t)_i * pstep + (voff)[0]), (PG8_LAS unsigned*)(lds + (bufoff) + ldsw + _i * 8192), 16, 0, 0); } } while (0)
; #define PG8_LDA(dst, b, h) do { _Pragma("unroll") for (int m = 0; m < 4; ++m) _Pragma("unroll") for (int k = 0; k < 2; ++k) dst[m][k] = *(const PG8_LAS bf16x8*)(lds + PG8_SA(b, h) + aoff + m * 2048 + k * 1024); } while (0)
; #define PG8_LDB(dst, b, h) do { _Pragma("unroll") for (int n = 0; n < 2; ++n) _Pragma("unroll") for (int k = 0; k < 2; ++k) dst[n][k] = *(const PG8_LAS bf16x8*)(lds + PG8_SB(b, h) + boff + n * 2048 + k * 1024); } while (0)
; #define PG8_MMA(ai, bj, At, Bt) do { __builtin_amdgcn_s_setprio(1); _Pragma("unroll") for (int m = 0; m < 4; ++m) _Pragma("unroll") for (int n = 0; n < 2; ++n) _Pragma("unroll") for (int k = 0; k < 2; ++k) \
;         acc[ai][bj][m][n] = __builtin_amdgcn_mfma_f32_16x16x32_bf16(Bt[n][k], At[m][k], acc[ai][bj][m][n], 0, 0, 0); __builtin_amdgcn_s_setprio(0); } while (0)
; #define PG8_WAIT_V(n) asm volatile("s_waitcnt vmcnt(" #n ")" ::: "memory")
; #define PG8_WAIT_L(n) asm volatile("s_waitcnt lgkmcnt(" #n ")" ::: "memory")
; #define PG8_BAR __builtin_amdgcn_s_barrier()
; #define PG8_SCHED __builtin_amdgcn_sched_barrier(0)
; template <class Epi, class Sched, bool ALIGN_EPI = false, bool SP2 = false, bool ABLK = false>
; __device__ __forceinline__ void gemm_phase(PG8_LAS unsigned char* lds, const Gemm g, const Sched& S, const Epi& E) {
;     ...
;             PG8_WAIT_V(8); PG8_WAIT_L(0); PG8_BAR; PG8_MMA(1, 0, At, B0); PG8_MMA(1, 1, At, B1); PG8_BAR; PG8_SCHED;
;             PG8_LDB(B0, 1, 0); PG8_LDB(B1, 1, 1); PG8_SCHED; PG8_LDA(At, 1, 0); PG8_STAGE(PG8_SA(0, 1), a2 + hstep, voffA);
;             PG8_WAIT_V(8); PG8_WAIT_L(0); PG8_BAR; PG8_MMA(0, 0, At, B0); PG8_MMA(0, 1, At, B1); PG8_BAR; PG8_SCHED;
	s_setprio 1
	s_waitcnt lgkmcnt(0)
	v_mfma_f32_16x16x32_bf16 v[62:65], v[130:133], v[184:187], v[62:65]
	v_mfma_f32_16x16x32_bf16 v[62:65], v[134:137], v[188:191], v[62:65]
	v_mfma_f32_16x16x32_bf16 v[46:49], v[134:137], v[196:199], v[46:49]
	v_mfma_f32_16x16x32_bf16 v[46:49], v[130:133], v[192:195], v[46:49]
	v_mfma_f32_16x16x32_bf16 v[30:33], v[130:133], v[200:203], v[30:33]
	v_mfma_f32_16x16x32_bf16 v[30:33], v[134:137], v[204:207], v[30:33]
	v_mfma_f32_16x16x32_bf16 v[14:17], v[134:137], v[212:215], v[14:17]
	v_mfma_f32_16x16x32_bf16 v[14:17], v[130:133], v[208:211], v[14:17]
	v_mfma_f32_16x16x32_bf16 v[10:13], v[138:141], v[208:211], v[10:13]
	v_mfma_f32_16x16x32_bf16 v[10:13], v[142:145], v[212:215], v[10:13]
	v_mfma_f32_16x16x32_bf16 v[26:29], v[142:145], v[204:207], v[26:29]
	v_mfma_f32_16x16x32_bf16 v[26:29], v[138:141], v[200:203], v[26:29]
	v_mfma_f32_16x16x32_bf16 v[42:45], v[138:141], v[192:195], v[42:45]
	v_mfma_f32_16x16x32_bf16 v[42:45], v[142:145], v[196:199], v[42:45]
	v_mfma_f32_16x16x32_bf16 v[58:61], v[142:145], v[188:191], v[58:61]
	v_mfma_f32_16x16x32_bf16 v[58:61], v[138:141], v[184:187], v[58:61]
	v_mfma_f32_16x16x32_bf16 v[54:57], v[146:149], v[184:187], v[54:57]
	v_mfma_f32_16x16x32_bf16 v[54:57], v[150:153], v[188:191], v[54:57]
	s_add_i32 s41, 0, 0x18000
	v_add_u32_e32 v142, s41, v1
	ds_read_b128 v[130:133], v142
	v_mfma_f32_16x16x32_bf16 v[38:41], v[150:153], v[196:199], v[38:41]
	v_mfma_f32_16x16x32_bf16 v[38:41], v[146:149], v[192:195], v[38:41]
	ds_read_b128 v[134:137], v142 offset:1024
	v_mfma_f32_16x16x32_bf16 v[22:25], v[146:149], v[200:203], v[22:25]
	v_mfma_f32_16x16x32_bf16 v[22:25], v[150:153], v[204:207], v[22:25]
	ds_read_b128 v[138:141], v142 offset:2048
	v_mfma_f32_16x16x32_bf16 v[6:9], v[150:153], v[212:215], v[6:9]
	v_mfma_f32_16x16x32_bf16 v[6:9], v[146:149], v[208:211], v[6:9]
	ds_read_b128 v[142:145], v142 offset:3072
	v_mfma_f32_16x16x32_bf16 v[2:5], v[154:157], v[208:211], v[2:5]
	v_mfma_f32_16x16x32_bf16 v[2:5], v[158:161], v[212:215], v[2:5]
	v_mfma_f32_16x16x32_bf16 v[18:21], v[158:161], v[204:207], v[18:21]
	v_mfma_f32_16x16x32_bf16 v[18:21], v[154:157], v[200:203], v[18:21]
	s_barrier
	s_setprio 2
	v_mfma_f32_16x16x32_bf16 v[34:37], v[154:157], v[192:195], v[34:37]
	v_mfma_f32_16x16x32_bf16 v[34:37], v[158:161], v[196:199], v[34:37]
	v_mfma_f32_16x16x32_bf16 v[50:53], v[158:161], v[188:191], v[50:53]
	v_mfma_f32_16x16x32_bf16 v[50:53], v[154:157], v[184:187], v[50:53]
	s_setprio 0
	s_add_i32 s62, 0, 0x1c000
	v_add_u32_e32 v158, s62, v1
	ds_read_b128 v[146:149], v158
	ds_read_b128 v[150:153], v158 offset:1024
	ds_read_b128 v[154:157], v158 offset:2048
	ds_read_b128 v[158:161], v158 offset:3072
	s_mov_b32 m0, s59
	v_lshl_add_u64 v[218:219], v[216:217], 0, s[14:15]
	ds_read_b128 v[184:187], v177 offset:32768
	ds_read_b128 v[188:191], v177 offset:33792
	ds_read_b128 v[192:195], v177 offset:34816
	ds_read_b128 v[196:199], v177 offset:35840
	ds_read_b128 v[200:203], v177 offset:36864
	ds_read_b128 v[204:207], v177 offset:37888
	ds_read_b128 v[208:211], v177 offset:38912
	ds_read_b128 v[212:215], v177 offset:39936
	global_load_lds_dwordx4 v[218:219], off
	v_lshl_add_u64 v[218:219], v[216:217], 0, s[16:17]
	s_mov_b32 m0, s60
	s_nop 0
	global_load_lds_dwordx4 v[218:219], off
	s_waitcnt vmcnt(8)
	s_waitcnt lgkmcnt(0)
	s_barrier
	s_setprio 1
	s_waitcnt lgkmcnt(0)
	v_mfma_f32_16x16x32_bf16 v[126:129], v[130:133], v[184:187], v[126:129]
	v_mfma_f32_16x16x32_bf16 v[126:129], v[134:137], v[188:191], v[126:129]
	v_mfma_f32_16x16x32_bf16 v[110:113], v[134:137], v[196:199], v[110:113]
	v_mfma_f32_16x16x32_bf16 v[110:113], v[130:133], v[192:195], v[110:113]
	v_mfma_f32_16x16x32_bf16 v[94:97], v[130:133], v[200:203], v[94:97]
	v_mfma_f32_16x16x32_bf16 v[94:97], v[134:137], v[204:207], v[94:97]
	v_mfma_f32_16x16x32_bf16 v[78:81], v[134:137], v[212:215], v[78:81]
	v_mfma_f32_16x16x32_bf16 v[78:81], v[130:133], v[208:211], v[78:81]
	v_mfma_f32_16x16x32_bf16 v[74:77], v[138:141], v[208:211], v[74:77]
	v_mfma_f32_16x16x32_bf16 v[74:77], v[142:145], v[212:215], v[74:77]
	v_mfma_f32_16x16x32_bf16 v[90:93], v[142:145], v[204:207], v[90:93]
	v_mfma_f32_16x16x32_bf16 v[90:93], v[138:141], v[200:203], v[90:93]
	v_mfma_f32_16x16x32_bf16 v[106:109], v[138:141], v[192:195], v[106:109]
	v_mfma_f32_16x16x32_bf16 v[106:109], v[142:145], v[196:199], v[106:109]
	v_mfma_f32_16x16x32_bf16 v[122:125], v[142:145], v[188:191], v[122:125]
	v_mfma_f32_16x16x32_bf16 v[122:125], v[138:141], v[184:187], v[122:125]
	v_mfma_f32_16x16x32_bf16 v[118:121], v[146:149], v[184:187], v[118:121]
	v_mfma_f32_16x16x32_bf16 v[118:121], v[150:153], v[188:191], v[118:121]
	v_mfma_f32_16x16x32_bf16 v[102:105], v[150:153], v[196:199], v[102:105]
	v_mfma_f32_16x16x32_bf16 v[102:105], v[146:149], v[192:195], v[102:105]
	v_mfma_f32_16x16x32_bf16 v[86:89], v[146:149], v[200:203], v[86:89]
	v_mfma_f32_16x16x32_bf16 v[86:89], v[150:153], v[204:207], v[86:89]
	v_mfma_f32_16x16x32_bf16 v[70:73], v[150:153], v[212:215], v[70:73]
	v_mfma_f32_16x16x32_bf16 v[70:73], v[146:149], v[208:211], v[70:73]
	v_mfma_f32_16x16x32_bf16 v[66:69], v[154:157], v[208:211], v[66:69]
	v_mfma_f32_16x16x32_bf16 v[66:69], v[158:161], v[212:215], v[66:69]
	v_mfma_f32_16x16x32_bf16 v[82:85], v[158:161], v[204:207], v[82:85]
	v_mfma_f32_16x16x32_bf16 v[82:85], v[154:157], v[200:203], v[82:85]
	s_barrier
; #define PG8_STAGE(bufoff, gbase, voff) do { if constexpr (!pg8_noload<Epi>::value) { _Pragma("unroll") for (int _i = 0; _i < 2; ++_i) \
;         __builtin_amdgcn_global_load_lds((const unsigned*)((const char*)(gbase) + (size_t)_i * pstep + (voff)[0]), (PG8_LAS unsigned*)(lds + (bufoff) + ldsw + _i * 8192), 16, 0, 0); } } while (0)
; #define PG8_LDA(dst, b, h) do { _Pragma("unroll") for (int m = 0; m < 4; ++m) _Pragma("unroll") for (int k = 0; k < 2; ++k) dst[m][k] = *(const PG8_LAS bf16x8*)(lds + PG8_SA(b, h) + aoff + m * 2048 + k * 1024); } while (0)
; #define PG8_MMA(ai, bj, At, Bt) do { __builtin_amdgcn_s_setprio(1); _Pragma("unroll") for (int m = 0; m < 4; ++m) _Pragma("unroll") for (int n = 0; n < 2; ++n) _Pragma("unroll") for (int k = 0; k < 2; ++k) \
;         acc[ai][bj][m][n] = __builtin_amdgcn_mfma_f32_16x16x32_bf16(Bt[n][k], At[m][k], acc[ai][bj][m][n], 0, 0, 0); __builtin_amdgcn_s_setprio(0); } while (0)
; #define PG8_WAIT_V(n) asm volatile("s_waitcnt vmcnt(" #n ")" ::: "memory")
; #define PG8_WAIT_L(n) asm volatile("s_waitcnt lgkmcnt(" #n ")" ::: "memory")
; #define PG8_BAR __builtin_amdgcn_s_barrier()
; #define PG8_SCHED __builtin_amdgcn_sched_barrier(0)
;     __device__ __forceinline__ void operator()(const f32x4 (&acc)[2][2][4][2], const Unit& u, int wr, int wc, int fr, int fq) const {
;     ...
;         if (u.pm * BM < seq) {
; template <class Epi, class Sched, bool ALIGN_EPI = false, bool SP2 = false, bool ABLK = false>
; __device__ __forceinline__ void gemm_phase(PG8_LAS unsigned char* lds, const Gemm g, const Sched& S, const Epi& E) {
;     ...
;             PG8_WAIT_V(8); PG8_WAIT_L(0); PG8_BAR; PG8_MMA(0, 0, At, B0); PG8_MMA(0, 1, At, B1); PG8_BAR; PG8_SCHED;
;             PG8_LDA(At, 1, 1); PG8_STAGE(PG8_SB(1, 0), b3, voffB); PG8_STAGE(PG8_SB(1, 1), b3 + hstep, voffB); PG8_STAGE(PG8_SA(1, 0), a3, voffA);
;             PG8_WAIT_V(8); PG8_WAIT_L(0); PG8_BAR; PG8_MMA(1, 0, At, B0); PG8_MMA(1, 1, At, B1); PG8_BAR; PG8_SCHED;
	s_setprio 2
	v_mfma_f32_16x16x32_bf16 v[98:101], v[154:157], v[192:195], v[98:101]
	v_mfma_f32_16x16x32_bf16 v[98:101], v[158:161], v[196:199], v[98:101]
	v_mfma_f32_16x16x32_bf16 v[114:117], v[158:161], v[188:191], v[114:117]
	v_mfma_f32_16x16x32_bf16 v[114:117], v[154:157], v[184:187], v[114:117]
	s_setprio 0
	s_add_i32 s41, s41, s57
	v_lshl_add_u64 v[218:219], v[170:171], 0, s[24:25]
	s_mov_b32 m0, s41
	ds_read_b128 v[184:187], v177 offset:49152
	ds_read_b128 v[188:191], v177 offset:50176
	ds_read_b128 v[192:195], v177 offset:51200
	ds_read_b128 v[196:199], v177 offset:52224
	ds_read_b128 v[200:203], v177 offset:53248
	ds_read_b128 v[204:207], v177 offset:54272
	ds_read_b128 v[208:211], v177 offset:55296
	ds_read_b128 v[212:215], v177 offset:56320
	global_load_lds_dwordx4 v[218:219], off
	v_lshl_add_u64 v[218:219], v[170:171], 0, s[26:27]
	s_add_i32 m0, s41, 0x2000
	s_add_i32 s41, s62, s57
	global_load_lds_dwordx4 v[218:219], off
	v_lshl_add_u64 v[218:219], v[170:171], 0, s[28:29]
	s_mov_b32 m0, s41
	v_lshl_add_u64 v[170:171], v[170:171], 0, s[30:31]
	global_load_lds_dwordx4 v[218:219], off
	s_add_i32 m0, s41, 0x2000
	s_nop 0
	global_load_lds_dwordx4 v[170:171], off
	v_lshl_add_u64 v[170:171], v[216:217], 0, s[24:25]
	s_mov_b32 m0, s65
	s_nop 0
	global_load_lds_dwordx4 v[170:171], off
	v_lshl_add_u64 v[170:171], v[216:217], 0, s[26:27]
	s_mov_b32 m0, s66
	s_nop 0
	global_load_lds_dwordx4 v[170:171], off
	s_waitcnt vmcnt(8)
	s_waitcnt lgkmcnt(0)
	s_barrier
	s_setprio 1
	s_waitcnt lgkmcnt(0)
	v_mfma_f32_16x16x32_bf16 v[62:65], v[130:133], v[184:187], v[62:65]
	v_mfma_f32_16x16x32_bf16 v[62:65], v[134:137], v[188:191], v[62:65]
	v_mfma_f32_16x16x32_bf16 v[46:49], v[134:137], v[196:199], v[46:49]
	v_mfma_f32_16x16x32_bf16 v[46:49], v[130:133], v[192:195], v[46:49]
	v_mfma_f32_16x16x32_bf16 v[30:33], v[130:133], v[200:203], v[30:33]
	v_mfma_f32_16x16x32_bf16 v[30:33], v[134:137], v[204:207], v[30:33]
	v_mfma_f32_16x16x32_bf16 v[14:17], v[134:137], v[212:215], v[14:17]
	v_mfma_f32_16x16x32_bf16 v[14:17], v[130:133], v[208:211], v[14:17]
	v_mfma_f32_16x16x32_bf16 v[10:13], v[138:141], v[208:211], v[10:13]
	v_mfma_f32_16x16x32_bf16 v[10:13], v[142:145], v[212:215], v[10:13]
	v_mfma_f32_16x16x32_bf16 v[26:29], v[142:145], v[204:207], v[26:29]
	v_mfma_f32_16x16x32_bf16 v[26:29], v[138:141], v[200:203], v[26:29]
	v_mfma_f32_16x16x32_bf16 v[42:45], v[138:141], v[192:195], v[42:45]
	v_mfma_f32_16x16x32_bf16 v[42:45], v[142:145], v[196:199], v[42:45]
	v_mfma_f32_16x16x32_bf16 v[58:61], v[142:145], v[188:191], v[58:61]
	v_mfma_f32_16x16x32_bf16 v[58:61], v[138:141], v[184:187], v[58:61]
	v_mfma_f32_16x16x32_bf16 v[54:57], v[146:149], v[184:187], v[54:57]
	v_mfma_f32_16x16x32_bf16 v[54:57], v[150:153], v[188:191], v[54:57]
	v_mfma_f32_16x16x32_bf16 v[38:41], v[150:153], v[196:199], v[38:41]
	v_mfma_f32_16x16x32_bf16 v[38:41], v[146:149], v[192:195], v[38:41]
	v_mfma_f32_16x16x32_bf16 v[22:25], v[146:149], v[200:203], v[22:25]
	v_mfma_f32_16x16x32_bf16 v[22:25], v[150:153], v[204:207], v[22:25]
	v_mfma_f32_16x16x32_bf16 v[6:9], v[150:153], v[212:215], v[6:9]
	v_mfma_f32_16x16x32_bf16 v[6:9], v[146:149], v[208:211], v[6:9]
	v_mfma_f32_16x16x32_bf16 v[2:5], v[154:157], v[208:211], v[2:5]
	v_mfma_f32_16x16x32_bf16 v[2:5], v[158:161], v[212:215], v[2:5]
	v_mfma_f32_16x16x32_bf16 v[18:21], v[158:161], v[204:207], v[18:21]
	v_mfma_f32_16x16x32_bf16 v[18:21], v[154:157], v[200:203], v[18:21]
	s_barrier
	s_setprio 2
	v_mfma_f32_16x16x32_bf16 v[34:37], v[154:157], v[192:195], v[34:37]
	v_mfma_f32_16x16x32_bf16 v[34:37], v[158:161], v[196:199], v[34:37]
	v_mfma_f32_16x16x32_bf16 v[50:53], v[158:161], v[188:191], v[50:53]
	v_mfma_f32_16x16x32_bf16 v[50:53], v[154:157], v[184:187], v[50:53]
	s_setprio 0
	s_add_u32 s52, s52, 0x1000
	s_addc_u32 s53, s53, 0
	s_add_u32 s11, s11, 0x1000
	s_addc_u32 s39, s39, 0
	s_cmp_ge_i32 s43, s75
	s_mov_b32 s41, s43
	s_cbranch_scc0 .LBB0_1997
	s_and_b64 vcc, exec, s[34:35]
	s_cbranch_vccnz .LBB0_2002
	s_lshl_b32 s11, s2, 8
	s_cmp_gt_i32 s2, 63
	s_mov_b64 s[52:53], -1
	s_cbranch_scc1 .LBB0_2003

; #define PG8_STAGE(bufoff, gbase, voff) do { if constexpr (!pg8_noload<Epi>::value) { _Pragma("unroll") for (int _i = 0; _i < 2; ++_i) \
;         __builtin_amdgcn_global_load_lds((const unsigned*)((const char*)(gbase) + (size_t)_i * pstep + (voff)[0]), (PG8_LAS unsigned*)(lds + (bufoff) + ldsw + _i * 8192), 16, 0, 0); } } while (0)
; #define PG8_LDA(dst, b, h) do { _Pragma("unroll") for (int m = 0; m < 4; ++m) _Pragma("unroll") for (int k = 0; k < 2; ++k) dst[m][k] = *(const PG8_LAS bf16x8*)(lds + PG8_SA(b, h) + aoff + m * 2048 + k * 1024); } while (0)
; #define PG8_LDB(dst, b, h) do { _Pragma("unroll") for (int n = 0; n < 2; ++n) _Pragma("unroll") for (int k = 0; k < 2; ++k) dst[n][k] = *(const PG8_LAS bf16x8*)(lds + PG8_SB(b, h) + boff + n * 2048 + k * 1024); } while (0)
; #define PG8_MMA(ai, bj, At, Bt) do { __builtin_amdgcn_s_setprio(1); _Pragma("unroll") for (int m = 0; m < 4; ++m) _Pragma("unroll") for (int n = 0; n < 2; ++n) _Pragma("unroll") for (int k = 0; k < 2; ++k) \
;         acc[ai][bj][m][n] = __builtin_amdgcn_mfma_f32_16x16x32_bf16(Bt[n][k], At[m][k], acc[ai][bj][m][n], 0, 0, 0); __builtin_amdgcn_s_setprio(0); } while (0)
; #define PG8_WAIT_V(n) asm volatile("s_waitcnt vmcnt(" #n ")" ::: "memory")
; #define PG8_WAIT_L(n) asm volatile("s_waitcnt lgkmcnt(" #n ")" ::: "memory")
; #define PG8_BAR __builtin_amdgcn_s_barrier()
; #define PG8_SCHED __builtin_amdgcn_sched_barrier(0)
; template <class Epi, class Sched, bool ALIGN_EPI = false, bool SP2 = false, bool ABLK = false>
; __device__ __forceinline__ void gemm_phase(PG8_LAS unsigned char* lds, const Gemm g, const Sched& S, const Epi& E) {
;     ...
;             const char* a1 = cA + (size_t)(t + 1) * kstep;
;             const char* a2 = last ? nA : cA + (size_t)(t + 2) * kstep; const char* b2 = last ? nB : cB + (size_t)(t + 2) * kstepB;
;             const char* a3 = a2 + kstep; const char* b3 = b2 + kstepB;
;             if (last && has_next) S.a_ready(nxt);
;             if constexpr (SP2) {
;             PG8_LDB(B0, 0, 0); PG8_LDB(B1, 0, 1); PG8_SCHED; PG8_LDA(At, 0, 0); PG8_STAGE(PG8_SA(1, 1), a1 + hstep, voffA);
;             PG8_WAIT_V(8); PG8_WAIT_L(0); PG8_BAR; PG8_MMA(0, 0, At, B0); PG8_MMA(0, 1, At, B1); PG8_BAR; PG8_SCHED;
;             PG8_LDA(At, 0, 1); PG8_STAGE(PG8_SB(0, 0), b2, voffB); PG8_STAGE(PG8_SB(0, 1), b2 + hstep, voffB); PG8_STAGE(PG8_SA(0, 0), a2, voffA);
.LBB0_2119:
	s_or_b32 s30, s59, 1
	s_lshl_b64 s[14:15], s[30:31], 11
	s_add_u32 s14, s82, s14
	v_add_u32_e32 v133, s71, v148
	s_addc_u32 s15, s83, s15
	s_add_i32 s30, s59, 2
	ds_read_b128 v[144:147], v133
	ds_read_b128 v[184:187], v133 offset:1024
	ds_read_b128 v[188:191], v133 offset:2048
	ds_read_b128 v[192:195], v133 offset:3072
	v_add_u32_e32 v133, s73, v148
	s_lshl_b64 s[34:35], s[30:31], 11
	ds_read_b128 v[196:199], v133
	ds_read_b128 v[200:203], v133 offset:1024
	ds_read_b128 v[204:207], v133 offset:2048
	ds_read_b128 v[208:211], v133 offset:3072
	s_add_u32 s96, s82, s34
	s_addc_u32 s97, s83, s35
	s_and_b64 s[94:95], s[92:93], exec
	s_cselect_b32 s95, s97, s77
	s_cselect_b32 s94, s96, s28
	s_add_u32 s96, s88, s34
	s_addc_u32 s97, s89, s35
	s_and_b64 s[34:35], s[92:93], exec
	s_cselect_b32 s35, s97, s29
	s_cselect_b32 s34, s96, s75
	v_lshl_add_u64 v[180:181], s[14:15], 0, v[130:131]
	v_lshl_add_u64 v[244:245], v[180:181], 0, s[24:25]
	s_add_i32 m0, s17, 0xc000
	ds_read_b128 v[212:215], v168
	ds_read_b128 v[216:219], v168 offset:1024
	ds_read_b128 v[220:223], v168 offset:2048
	ds_read_b128 v[224:227], v168 offset:3072
	ds_read_b128 v[228:231], v168 offset:4096
	ds_read_b128 v[232:235], v168 offset:5120
	ds_read_b128 v[236:239], v168 offset:6144
	ds_read_b128 v[240:243], v168 offset:7168
	global_load_lds_dwordx4 v[244:245], off
	v_lshl_add_u64 v[180:181], v[180:181], 0, s[26:27]
	s_add_i32 m0, s17, 0xe000
	s_nop 0
	global_load_lds_dwordx4 v[180:181], off
	s_waitcnt vmcnt(8)
	s_waitcnt lgkmcnt(0)
	s_barrier
	s_setprio 1
	s_waitcnt lgkmcnt(0)
	v_mfma_f32_16x16x32_bf16 v[126:129], v[144:147], v[212:215], v[126:129]
	v_mfma_f32_16x16x32_bf16 v[126:129], v[184:187], v[216:219], v[126:129]
	v_mfma_f32_16x16x32_bf16 v[110:113], v[184:187], v[224:227], v[110:113]
	v_mfma_f32_16x16x32_bf16 v[110:113], v[144:147], v[220:223], v[110:113]
	v_mfma_f32_16x16x32_bf16 v[94:97], v[144:147], v[228:231], v[94:97]
	v_mfma_f32_16x16x32_bf16 v[94:97], v[184:187], v[232:235], v[94:97]
	v_mfma_f32_16x16x32_bf16 v[78:81], v[184:187], v[240:243], v[78:81]
	v_mfma_f32_16x16x32_bf16 v[78:81], v[144:147], v[236:239], v[78:81]
	v_mfma_f32_16x16x32_bf16 v[74:77], v[188:191], v[236:239], v[74:77]
	v_mfma_f32_16x16x32_bf16 v[74:77], v[192:195], v[240:243], v[74:77]
	v_mfma_f32_16x16x32_bf16 v[90:93], v[192:195], v[232:235], v[90:93]
	v_mfma_f32_16x16x32_bf16 v[90:93], v[188:191], v[228:231], v[90:93]
	v_mfma_f32_16x16x32_bf16 v[106:109], v[188:191], v[220:223], v[106:109]
	v_mfma_f32_16x16x32_bf16 v[106:109], v[192:195], v[224:227], v[106:109]
	v_mfma_f32_16x16x32_bf16 v[122:125], v[192:195], v[216:219], v[122:125]
	v_mfma_f32_16x16x32_bf16 v[122:125], v[188:191], v[212:215], v[122:125]
	v_mfma_f32_16x16x32_bf16 v[118:121], v[196:199], v[212:215], v[118:121]
	v_mfma_f32_16x16x32_bf16 v[118:121], v[200:203], v[216:219], v[118:121]
	v_mfma_f32_16x16x32_bf16 v[102:105], v[200:203], v[224:227], v[102:105]
	v_mfma_f32_16x16x32_bf16 v[102:105], v[196:199], v[220:223], v[102:105]
	v_mfma_f32_16x16x32_bf16 v[86:89], v[196:199], v[228:231], v[86:89]
	v_mfma_f32_16x16x32_bf16 v[86:89], v[200:203], v[232:235], v[86:89]
	v_mfma_f32_16x16x32_bf16 v[70:73], v[200:203], v[240:243], v[70:73]
	v_mfma_f32_16x16x32_bf16 v[70:73], v[196:199], v[236:239], v[70:73]
	v_mfma_f32_16x16x32_bf16 v[66:69], v[204:207], v[236:239], v[66:69]
	v_mfma_f32_16x16x32_bf16 v[66:69], v[208:211], v[240:243], v[66:69]
	v_mfma_f32_16x16x32_bf16 v[82:85], v[208:211], v[232:235], v[82:85]
	v_mfma_f32_16x16x32_bf16 v[82:85], v[204:207], v[228:231], v[82:85]
	s_barrier
	s_setprio 2
	v_mfma_f32_16x16x32_bf16 v[98:101], v[204:207], v[220:223], v[98:101]
	v_mfma_f32_16x16x32_bf16 v[98:101], v[208:211], v[224:227], v[98:101]
	v_mfma_f32_16x16x32_bf16 v[114:117], v[208:211], v[216:219], v[114:117]
	v_mfma_f32_16x16x32_bf16 v[114:117], v[204:207], v[212:215], v[114:117]
	s_setprio 0
	s_add_i32 s14, s71, s3
	v_lshl_add_u64 v[180:181], s[34:35], 0, v[130:131]
	s_mov_b32 m0, s14
	ds_read_b128 v[212:215], v168 offset:16384
	ds_read_b128 v[216:219], v168 offset:17408
	ds_read_b128 v[220:223], v168 offset:18432
	ds_read_b128 v[224:227], v168 offset:19456
	ds_read_b128 v[228:231], v168 offset:20480
	ds_read_b128 v[232:235], v168 offset:21504
	ds_read_b128 v[236:239], v168 offset:22528
	ds_read_b128 v[240:243], v168 offset:23552
	global_load_lds_dwordx4 v[180:181], off
	v_lshl_add_u64 v[244:245], v[180:181], 0, s[22:23]
	s_add_i32 m0, s14, 0x2000
	s_add_i32 s14, s73, s3
	global_load_lds_dwordx4 v[244:245], off
	v_lshl_add_u64 v[244:245], v[180:181], 0, s[24:25]
	s_mov_b32 m0, s14
	s_nop 0
	global_load_lds_dwordx4 v[244:245], off
	v_lshl_add_u64 v[244:245], v[180:181], 0, s[26:27]
	s_add_i32 m0, s14, 0x2000
	s_nop 0
	global_load_lds_dwordx4 v[244:245], off
	v_lshl_add_u64 v[244:245], s[94:95], 0, v[130:131]
	s_mov_b32 m0, s17
	v_lshl_add_u64 v[246:247], v[244:245], 0, s[22:23]
	global_load_lds_dwordx4 v[244:245], off
	s_mov_b32 m0, s56
	s_nop 0
	global_load_lds_dwordx4 v[246:247], off
	s_waitcnt vmcnt(8)
	s_waitcnt lgkmcnt(0)
	s_barrier
; #define PG8_STAGE(bufoff, gbase, voff) do { if constexpr (!pg8_noload<Epi>::value) { _Pragma("unroll") for (int _i = 0; _i < 2; ++_i) \
;         __builtin_amdgcn_global_load_lds((const unsigned*)((const char*)(gbase) + (size_t)_i * pstep + (voff)[0]), (PG8_LAS unsigned*)(lds + (bufoff) + ldsw + _i * 8192), 16, 0, 0); } } while (0)
; #define PG8_LDA(dst, b, h) do { _Pragma("unroll") for (int m = 0; m < 4; ++m) _Pragma("unroll") for (int k = 0; k < 2; ++k) dst[m][k] = *(const PG8_LAS bf16x8*)(lds + PG8_SA(b, h) + aoff + m * 2048 + k * 1024); } while (0)
; #define PG8_LDB(dst, b, h) do { _Pragma("unroll") for (int n = 0; n < 2; ++n) _Pragma("unroll") for (int k = 0; k < 2; ++k) dst[n][k] = *(const PG8_LAS bf16x8*)(lds + PG8_SB(b, h) + boff + n * 2048 + k * 1024); } while (0)
; #define PG8_MMA(ai, bj, At, Bt) do { __builtin_amdgcn_s_setprio(1); _Pragma("unroll") for (int m = 0; m < 4; ++m) _Pragma("unroll") for (int n = 0; n < 2; ++n) _Pragma("unroll") for (int k = 0; k < 2; ++k) \
;         acc[ai][bj][m][n] = __builtin_amdgcn_mfma_f32_16x16x32_bf16(Bt[n][k], At[m][k], acc[ai][bj][m][n], 0, 0, 0); __builtin_amdgcn_s_setprio(0); } while (0)
; #define PG8_WAIT_V(n) asm volatile("s_waitcnt vmcnt(" #n ")" ::: "memory")
; #define PG8_WAIT_L(n) asm volatile("s_waitcnt lgkmcnt(" #n ")" ::: "memory")
; #define PG8_BAR __builtin_amdgcn_s_barrier()
; #define PG8_SCHED __builtin_amdgcn_sched_barrier(0)
; template <class Epi, class Sched, bool ALIGN_EPI = false, bool SP2 = false, bool ABLK = false>
; __device__ __forceinline__ void gemm_phase(PG8_LAS unsigned char* lds, const Gemm g, const Sched& S, const Epi& E) {
;     ...
;             PG8_WAIT_V(8); PG8_WAIT_L(0); PG8_BAR; PG8_MMA(1, 0, At, B0); PG8_MMA(1, 1, At, B1); PG8_BAR; PG8_SCHED;
;             PG8_LDB(B0, 1, 0); PG8_LDB(B1, 1, 1); PG8_SCHED; PG8_LDA(At, 1, 0); PG8_STAGE(PG8_SA(0, 1), a2 + hstep, voffA);
;             PG8_WAIT_V(8); PG8_WAIT_L(0); PG8_BAR; PG8_MMA(0, 0, At, B0); PG8_MMA(0, 1, At, B1); PG8_BAR; PG8_SCHED;
	s_setprio 1
	s_waitcnt lgkmcnt(0)
	v_mfma_f32_16x16x32_bf16 v[62:65], v[144:147], v[212:215], v[62:65]
	v_mfma_f32_16x16x32_bf16 v[62:65], v[184:187], v[216:219], v[62:65]
	v_mfma_f32_16x16x32_bf16 v[46:49], v[184:187], v[224:227], v[46:49]
	v_mfma_f32_16x16x32_bf16 v[46:49], v[144:147], v[220:223], v[46:49]
	v_mfma_f32_16x16x32_bf16 v[30:33], v[144:147], v[228:231], v[30:33]
	v_mfma_f32_16x16x32_bf16 v[30:33], v[184:187], v[232:235], v[30:33]
	v_mfma_f32_16x16x32_bf16 v[14:17], v[184:187], v[240:243], v[14:17]
	v_mfma_f32_16x16x32_bf16 v[14:17], v[144:147], v[236:239], v[14:17]
	v_mfma_f32_16x16x32_bf16 v[10:13], v[188:191], v[236:239], v[10:13]
	v_mfma_f32_16x16x32_bf16 v[10:13], v[192:195], v[240:243], v[10:13]
	v_mfma_f32_16x16x32_bf16 v[26:29], v[192:195], v[232:235], v[26:29]
	v_mfma_f32_16x16x32_bf16 v[26:29], v[188:191], v[228:231], v[26:29]
	v_mfma_f32_16x16x32_bf16 v[42:45], v[188:191], v[220:223], v[42:45]
	v_mfma_f32_16x16x32_bf16 v[42:45], v[192:195], v[224:227], v[42:45]
	v_mfma_f32_16x16x32_bf16 v[58:61], v[192:195], v[216:219], v[58:61]
	v_mfma_f32_16x16x32_bf16 v[58:61], v[188:191], v[212:215], v[58:61]
	v_mfma_f32_16x16x32_bf16 v[54:57], v[196:199], v[212:215], v[54:57]
	v_mfma_f32_16x16x32_bf16 v[54:57], v[200:203], v[216:219], v[54:57]
	s_add_i32 s14, 0, 0x18000
	v_add_u32_e32 v133, s14, v148
	ds_read_b128 v[144:147], v133
	v_mfma_f32_16x16x32_bf16 v[38:41], v[200:203], v[224:227], v[38:41]
	v_mfma_f32_16x16x32_bf16 v[38:41], v[196:199], v[220:223], v[38:41]
	ds_read_b128 v[184:187], v133 offset:1024
	v_mfma_f32_16x16x32_bf16 v[22:25], v[196:199], v[228:231], v[22:25]
	v_mfma_f32_16x16x32_bf16 v[22:25], v[200:203], v[232:235], v[22:25]
	ds_read_b128 v[188:191], v133 offset:2048
	v_mfma_f32_16x16x32_bf16 v[6:9], v[200:203], v[240:243], v[6:9]
	v_mfma_f32_16x16x32_bf16 v[6:9], v[196:199], v[236:239], v[6:9]
	ds_read_b128 v[192:195], v133 offset:3072
	v_mfma_f32_16x16x32_bf16 v[2:5], v[204:207], v[236:239], v[2:5]
	v_mfma_f32_16x16x32_bf16 v[2:5], v[208:211], v[240:243], v[2:5]
	v_mfma_f32_16x16x32_bf16 v[18:21], v[208:211], v[232:235], v[18:21]
	v_mfma_f32_16x16x32_bf16 v[18:21], v[204:207], v[228:231], v[18:21]
	s_barrier
	s_setprio 2
	v_mfma_f32_16x16x32_bf16 v[34:37], v[204:207], v[220:223], v[34:37]
	v_mfma_f32_16x16x32_bf16 v[34:37], v[208:211], v[224:227], v[34:37]
	v_mfma_f32_16x16x32_bf16 v[50:53], v[208:211], v[216:219], v[50:53]
	v_mfma_f32_16x16x32_bf16 v[50:53], v[204:207], v[212:215], v[50:53]
	s_setprio 0
	s_add_i32 s15, 0, 0x1c000
	v_add_u32_e32 v133, s15, v148
	ds_read_b128 v[196:199], v133
	ds_read_b128 v[200:203], v133 offset:1024
	ds_read_b128 v[204:207], v133 offset:2048
	ds_read_b128 v[208:211], v133 offset:3072
	s_mov_b32 m0, s57
	v_lshl_add_u64 v[246:247], v[244:245], 0, s[24:25]
	ds_read_b128 v[212:215], v168 offset:32768
	ds_read_b128 v[216:219], v168 offset:33792
	ds_read_b128 v[220:223], v168 offset:34816
	ds_read_b128 v[224:227], v168 offset:35840
	ds_read_b128 v[228:231], v168 offset:36864
	ds_read_b128 v[232:235], v168 offset:37888
	ds_read_b128 v[236:239], v168 offset:38912
	ds_read_b128 v[240:243], v168 offset:39936
	global_load_lds_dwordx4 v[246:247], off
	v_lshl_add_u64 v[246:247], v[244:245], 0, s[26:27]
	s_mov_b32 m0, s58
	s_nop 0
	global_load_lds_dwordx4 v[246:247], off
	s_waitcnt vmcnt(8)
	s_waitcnt lgkmcnt(0)
	s_barrier
	s_setprio 1
	s_waitcnt lgkmcnt(0)
	v_mfma_f32_16x16x32_bf16 v[126:129], v[144:147], v[212:215], v[126:129]
	v_mfma_f32_16x16x32_bf16 v[126:129], v[184:187], v[216:219], v[126:129]
	v_mfma_f32_16x16x32_bf16 v[110:113], v[184:187], v[224:227], v[110:113]
	v_mfma_f32_16x16x32_bf16 v[110:113], v[144:147], v[220:223], v[110:113]
	v_mfma_f32_16x16x32_bf16 v[94:97], v[144:147], v[228:231], v[94:97]
	v_mfma_f32_16x16x32_bf16 v[94:97], v[184:187], v[232:235], v[94:97]
	v_mfma_f32_16x16x32_bf16 v[78:81], v[184:187], v[240:243], v[78:81]
	v_mfma_f32_16x16x32_bf16 v[78:81], v[144:147], v[236:239], v[78:81]
	v_mfma_f32_16x16x32_bf16 v[74:77], v[188:191], v[236:239], v[74:77]
	v_mfma_f32_16x16x32_bf16 v[74:77], v[192:195], v[240:243], v[74:77]
	v_mfma_f32_16x16x32_bf16 v[90:93], v[192:195], v[232:235], v[90:93]
	v_mfma_f32_16x16x32_bf16 v[90:93], v[188:191], v[228:231], v[90:93]
	v_mfma_f32_16x16x32_bf16 v[106:109], v[188:191], v[220:223], v[106:109]
	v_mfma_f32_16x16x32_bf16 v[106:109], v[192:195], v[224:227], v[106:109]
	v_mfma_f32_16x16x32_bf16 v[122:125], v[192:195], v[216:219], v[122:125]
	v_mfma_f32_16x16x32_bf16 v[122:125], v[188:191], v[212:215], v[122:125]
	v_mfma_f32_16x16x32_bf16 v[118:121], v[196:199], v[212:215], v[118:121]
	v_mfma_f32_16x16x32_bf16 v[118:121], v[200:203], v[216:219], v[118:121]
	v_mfma_f32_16x16x32_bf16 v[102:105], v[200:203], v[224:227], v[102:105]
	v_mfma_f32_16x16x32_bf16 v[102:105], v[196:199], v[220:223], v[102:105]
	v_mfma_f32_16x16x32_bf16 v[86:89], v[196:199], v[228:231], v[86:89]
	v_mfma_f32_16x16x32_bf16 v[86:89], v[200:203], v[232:235], v[86:89]
	v_mfma_f32_16x16x32_bf16 v[70:73], v[200:203], v[240:243], v[70:73]
	v_mfma_f32_16x16x32_bf16 v[70:73], v[196:199], v[236:239], v[70:73]
	v_mfma_f32_16x16x32_bf16 v[66:69], v[204:207], v[236:239], v[66:69]
	v_mfma_f32_16x16x32_bf16 v[66:69], v[208:211], v[240:243], v[66:69]
	v_mfma_f32_16x16x32_bf16 v[82:85], v[208:211], v[232:235], v[82:85]
	v_mfma_f32_16x16x32_bf16 v[82:85], v[204:207], v[228:231], v[82:85]
	s_barrier
; #define PG8_STAGE(bufoff, gbase, voff) do { if constexpr (!pg8_noload<Epi>::value) { _Pragma("unroll") for (int _i = 0; _i < 2; ++_i) \
;         __builtin_amdgcn_global_load_lds((const unsigned*)((const char*)(gbase) + (size_t)_i * pstep + (voff)[0]), (PG8_LAS unsigned*)(lds + (bufoff) + ldsw + _i * 8192), 16, 0, 0); } } while (0)
; #define PG8_LDA(dst, b, h) do { _Pragma("unroll") for (int m = 0; m < 4; ++m) _Pragma("unroll") for (int k = 0; k < 2; ++k) dst[m][k] = *(const PG8_LAS bf16x8*)(lds + PG8_SA(b, h) + aoff + m * 2048 + k * 1024); } while (0)
; #define PG8_MMA(ai, bj, At, Bt) do { __builtin_amdgcn_s_setprio(1); _Pragma("unroll") for (int m = 0; m < 4; ++m) _Pragma("unroll") for (int n = 0; n < 2; ++n) _Pragma("unroll") for (int k = 0; k < 2; ++k) \
;         acc[ai][bj][m][n] = __builtin_amdgcn_mfma_f32_16x16x32_bf16(Bt[n][k], At[m][k], acc[ai][bj][m][n], 0, 0, 0); __builtin_amdgcn_s_setprio(0); } while (0)
; #define PG8_WAIT_V(n) asm volatile("s_waitcnt vmcnt(" #n ")" ::: "memory")
; #define PG8_WAIT_L(n) asm volatile("s_waitcnt lgkmcnt(" #n ")" ::: "memory")
; #define PG8_BAR __builtin_amdgcn_s_barrier()
; #define PG8_SCHED __builtin_amdgcn_sched_barrier(0)
; template <class Epi, class Sched, bool ALIGN_EPI = false, bool SP2 = false, bool ABLK = false>
; __device__ __forceinline__ void gemm_phase(PG8_LAS unsigned char* lds, const Gemm g, const Sched& S, const Epi& E) {
;     ...
;         for (int t = 0; t < nt; t += 2) {
;     ...
;             PG8_WAIT_V(8); PG8_WAIT_L(0); PG8_BAR; PG8_MMA(0, 0, At, B0); PG8_MMA(0, 1, At, B1); PG8_BAR; PG8_SCHED;
;             PG8_LDA(At, 1, 1); PG8_STAGE(PG8_SB(1, 0), b3, voffB); PG8_STAGE(PG8_SB(1, 1), b3 + hstep, voffB); PG8_STAGE(PG8_SA(1, 0), a3, voffA);
;             PG8_WAIT_V(8); PG8_WAIT_L(0); PG8_BAR; PG8_MMA(1, 0, At, B0); PG8_MMA(1, 1, At, B1); PG8_BAR; PG8_SCHED;
	s_setprio 2
	v_mfma_f32_16x16x32_bf16 v[98:101], v[204:207], v[220:223], v[98:101]
	v_mfma_f32_16x16x32_bf16 v[98:101], v[208:211], v[224:227], v[98:101]
	v_mfma_f32_16x16x32_bf16 v[114:117], v[208:211], v[216:219], v[114:117]
	v_mfma_f32_16x16x32_bf16 v[114:117], v[204:207], v[212:215], v[114:117]
	s_setprio 0
	s_add_i32 s14, s14, s3
	v_lshl_add_u64 v[246:247], v[180:181], 0, s[38:39]
	s_mov_b32 m0, s14
	ds_read_b128 v[212:215], v168 offset:49152
	ds_read_b128 v[216:219], v168 offset:50176
	ds_read_b128 v[220:223], v168 offset:51200
	ds_read_b128 v[224:227], v168 offset:52224
	ds_read_b128 v[228:231], v168 offset:53248
	ds_read_b128 v[232:235], v168 offset:54272
	ds_read_b128 v[236:239], v168 offset:55296
	ds_read_b128 v[240:243], v168 offset:56320
	global_load_lds_dwordx4 v[246:247], off
	v_lshl_add_u64 v[246:247], v[180:181], 0, s[40:41]
	s_add_i32 m0, s14, 0x2000
	s_add_i32 s14, s15, s3
	global_load_lds_dwordx4 v[246:247], off
	v_lshl_add_u64 v[246:247], v[180:181], 0, s[42:43]
	s_mov_b32 m0, s14
	v_lshl_add_u64 v[180:181], v[180:181], 0, s[44:45]
	global_load_lds_dwordx4 v[246:247], off
	s_add_i32 m0, s14, 0x2000
	s_nop 0
	global_load_lds_dwordx4 v[180:181], off
	v_lshl_add_u64 v[180:181], v[244:245], 0, s[38:39]
	s_mov_b32 m0, s61
	s_nop 0
	global_load_lds_dwordx4 v[180:181], off
	v_lshl_add_u64 v[180:181], v[244:245], 0, s[40:41]
	s_mov_b32 m0, s63
	s_nop 0
	global_load_lds_dwordx4 v[180:181], off
	s_waitcnt vmcnt(8)
	s_waitcnt lgkmcnt(0)
	s_barrier
	s_setprio 1
	s_waitcnt lgkmcnt(0)
	v_mfma_f32_16x16x32_bf16 v[62:65], v[144:147], v[212:215], v[62:65]
	v_mfma_f32_16x16x32_bf16 v[62:65], v[184:187], v[216:219], v[62:65]
	v_mfma_f32_16x16x32_bf16 v[46:49], v[184:187], v[224:227], v[46:49]
	v_mfma_f32_16x16x32_bf16 v[46:49], v[144:147], v[220:223], v[46:49]
	v_mfma_f32_16x16x32_bf16 v[30:33], v[144:147], v[228:231], v[30:33]
	v_mfma_f32_16x16x32_bf16 v[30:33], v[184:187], v[232:235], v[30:33]
	v_mfma_f32_16x16x32_bf16 v[14:17], v[184:187], v[240:243], v[14:17]
	v_mfma_f32_16x16x32_bf16 v[14:17], v[144:147], v[236:239], v[14:17]
	v_mfma_f32_16x16x32_bf16 v[10:13], v[188:191], v[236:239], v[10:13]
	v_mfma_f32_16x16x32_bf16 v[10:13], v[192:195], v[240:243], v[10:13]
	v_mfma_f32_16x16x32_bf16 v[26:29], v[192:195], v[232:235], v[26:29]
	v_mfma_f32_16x16x32_bf16 v[26:29], v[188:191], v[228:231], v[26:29]
	v_mfma_f32_16x16x32_bf16 v[42:45], v[188:191], v[220:223], v[42:45]
	v_mfma_f32_16x16x32_bf16 v[42:45], v[192:195], v[224:227], v[42:45]
	v_mfma_f32_16x16x32_bf16 v[58:61], v[192:195], v[216:219], v[58:61]
	v_mfma_f32_16x16x32_bf16 v[58:61], v[188:191], v[212:215], v[58:61]
	v_mfma_f32_16x16x32_bf16 v[54:57], v[196:199], v[212:215], v[54:57]
	v_mfma_f32_16x16x32_bf16 v[54:57], v[200:203], v[216:219], v[54:57]
	v_mfma_f32_16x16x32_bf16 v[38:41], v[200:203], v[224:227], v[38:41]
	v_mfma_f32_16x16x32_bf16 v[38:41], v[196:199], v[220:223], v[38:41]
	v_mfma_f32_16x16x32_bf16 v[22:25], v[196:199], v[228:231], v[22:25]
	v_mfma_f32_16x16x32_bf16 v[22:25], v[200:203], v[232:235], v[22:25]
	v_mfma_f32_16x16x32_bf16 v[6:9], v[200:203], v[240:243], v[6:9]
	v_mfma_f32_16x16x32_bf16 v[6:9], v[196:199], v[236:239], v[6:9]
	v_mfma_f32_16x16x32_bf16 v[2:5], v[204:207], v[236:239], v[2:5]
	v_mfma_f32_16x16x32_bf16 v[2:5], v[208:211], v[240:243], v[2:5]
	v_mfma_f32_16x16x32_bf16 v[18:21], v[208:211], v[232:235], v[18:21]
	v_mfma_f32_16x16x32_bf16 v[18:21], v[204:207], v[228:231], v[18:21]
	s_barrier
	s_setprio 2
	v_mfma_f32_16x16x32_bf16 v[34:37], v[204:207], v[220:223], v[34:37]
	v_mfma_f32_16x16x32_bf16 v[34:37], v[208:211], v[224:227], v[34:37]
	v_mfma_f32_16x16x32_bf16 v[50:53], v[208:211], v[216:219], v[50:53]
	v_mfma_f32_16x16x32_bf16 v[50:53], v[204:207], v[212:215], v[50:53]
	s_setprio 0
	s_cmp_gt_u32 s59, 29
	s_mov_b32 s59, s30
	s_cbranch_scc1 .LBB0_2131

; #define PG8_STAGE(bufoff, gbase, voff) do { if constexpr (!pg8_noload<Epi>::value) { _Pragma("unroll") for (int _i = 0; _i < 2; ++_i) \
;         __builtin_amdgcn_global_load_lds((const unsigned*)((const char*)(gbase) + (size_t)_i * pstep + (voff)[0]), (PG8_LAS unsigned*)(lds + (bufoff) + ldsw + _i * 8192), 16, 0, 0); } } while (0)
; #define PG8_LDA(dst, b, h) do { _Pragma("unroll") for (int m = 0; m < 4; ++m) _Pragma("unroll") for (int k = 0; k < 2; ++k) dst[m][k] = *(const PG8_LAS bf16x8*)(lds + PG8_SA(b, h) + aoff + m * 2048 + k * 1024); } while (0)
; #define PG8_LDB(dst, b, h) do { _Pragma("unroll") for (int n = 0; n < 2; ++n) _Pragma("unroll") for (int k = 0; k < 2; ++k) dst[n][k] = *(const PG8_LAS bf16x8*)(lds + PG8_SB(b, h) + boff + n * 2048 + k * 1024); } while (0)
; #define PG8_MMA(ai, bj, At, Bt) do { __builtin_amdgcn_s_setprio(1); _Pragma("unroll") for (int m = 0; m < 4; ++m) _Pragma("unroll") for (int n = 0; n < 2; ++n) _Pragma("unroll") for (int k = 0; k < 2; ++k) \
;         acc[ai][bj][m][n] = __builtin_amdgcn_mfma_f32_16x16x32_bf16(Bt[n][k], At[m][k], acc[ai][bj][m][n], 0, 0, 0); __builtin_amdgcn_s_setprio(0); } while (0)
; #define PG8_WAIT_V(n) asm volatile("s_waitcnt vmcnt(" #n ")" ::: "memory")
; #define PG8_WAIT_L(n) asm volatile("s_waitcnt lgkmcnt(" #n ")" ::: "memory")
; #define PG8_BAR __builtin_amdgcn_s_barrier()
; template <class Epi, class Sched, bool ALIGN_EPI = false, bool SP2 = false, bool ABLK = false>
; __device__ __forceinline__ void gemm_phase(PG8_LAS unsigned char* lds, const Gemm g, const Sched& S, const Epi& E) {
;     ...
;             const bool last = (t == nt - 2);
;             const char* a1 = cA + (size_t)(t + 1) * kstep;
;             const char* a2 = last ? nA : cA + (size_t)(t + 2) * kstep; const char* b2 = last ? nB : cB + (size_t)(t + 2) * kstepB;
;             const char* a3 = a2 + kstep; const char* b3 = b2 + kstepB;
;             if (last && has_next) S.a_ready(nxt);
;             if constexpr (SP2) {
;             PG8_LDB(B0, 0, 0); PG8_LDB(B1, 0, 1); PG8_SCHED; PG8_LDA(At, 0, 0); PG8_STAGE(PG8_SA(1, 1), a1 + hstep, voffA);
;             PG8_WAIT_V(8); PG8_WAIT_L(0); PG8_BAR; PG8_MMA(0, 0, At, B0); PG8_MMA(0, 1, At, B1); PG8_BAR; PG8_SCHED;
;             PG8_LDA(At, 0, 1); PG8_STAGE(PG8_SB(0, 0), b2, voffB); PG8_STAGE(PG8_SB(0, 1), b2 + hstep, voffB); PG8_STAGE(PG8_SA(0, 0), a2, voffA);
.LBB0_2399:
	ds_read_b128 v[130:133], v175
	ds_read_b128 v[134:137], v175 offset:1024
	ds_read_b128 v[138:141], v175 offset:2048
	ds_read_b128 v[142:145], v175 offset:3072
	ds_read_b128 v[146:149], v176
	ds_read_b128 v[150:153], v176 offset:1024
	ds_read_b128 v[154:157], v176 offset:2048
	ds_read_b128 v[158:161], v176 offset:3072
	s_add_i32 s55, s53, 2
	s_add_u32 s64, s62, 0xfff00800
	s_addc_u32 s65, s63, -1
	s_cmp_eq_u32 s3, s53
	s_cselect_b32 s65, s57, s65
	s_cselect_b32 s64, s56, s64
	s_cselect_b32 s91, s59, s49
	s_cselect_b32 s90, s58, s11
	v_lshl_add_u64 v[170:171], s[62:63], 0, v[166:167]
	s_add_i32 m0, s61, 0xc000
	ds_read_b128 v[184:187], v177
	ds_read_b128 v[188:191], v177 offset:1024
	ds_read_b128 v[192:195], v177 offset:2048
	ds_read_b128 v[196:199], v177 offset:3072
	ds_read_b128 v[200:203], v177 offset:4096
	ds_read_b128 v[204:207], v177 offset:5120
	ds_read_b128 v[208:211], v177 offset:6144
	ds_read_b128 v[212:215], v177 offset:7168
	global_load_lds_dwordx4 v[170:171], off
	v_lshl_add_u64 v[170:171], v[170:171], 0, s[12:13]
	s_add_i32 m0, s61, 0xe000
	s_nop 0
	global_load_lds_dwordx4 v[170:171], off
	s_waitcnt vmcnt(8)
	s_waitcnt lgkmcnt(0)
	s_barrier
	s_setprio 1
	s_waitcnt lgkmcnt(0)
	v_mfma_f32_16x16x32_bf16 v[126:129], v[130:133], v[184:187], v[126:129]
	v_mfma_f32_16x16x32_bf16 v[126:129], v[134:137], v[188:191], v[126:129]
	v_mfma_f32_16x16x32_bf16 v[110:113], v[134:137], v[196:199], v[110:113]
	v_mfma_f32_16x16x32_bf16 v[110:113], v[130:133], v[192:195], v[110:113]
	v_mfma_f32_16x16x32_bf16 v[94:97], v[130:133], v[200:203], v[94:97]
	v_mfma_f32_16x16x32_bf16 v[94:97], v[134:137], v[204:207], v[94:97]
	v_mfma_f32_16x16x32_bf16 v[78:81], v[134:137], v[212:215], v[78:81]
	v_mfma_f32_16x16x32_bf16 v[78:81], v[130:133], v[208:211], v[78:81]
	v_mfma_f32_16x16x32_bf16 v[74:77], v[138:141], v[208:211], v[74:77]
	v_mfma_f32_16x16x32_bf16 v[74:77], v[142:145], v[212:215], v[74:77]
	v_mfma_f32_16x16x32_bf16 v[90:93], v[142:145], v[204:207], v[90:93]
	v_mfma_f32_16x16x32_bf16 v[90:93], v[138:141], v[200:203], v[90:93]
	v_mfma_f32_16x16x32_bf16 v[106:109], v[138:141], v[192:195], v[106:109]
	v_mfma_f32_16x16x32_bf16 v[106:109], v[142:145], v[196:199], v[106:109]
	v_mfma_f32_16x16x32_bf16 v[122:125], v[142:145], v[188:191], v[122:125]
	v_mfma_f32_16x16x32_bf16 v[122:125], v[138:141], v[184:187], v[122:125]
	v_mfma_f32_16x16x32_bf16 v[118:121], v[146:149], v[184:187], v[118:121]
	v_mfma_f32_16x16x32_bf16 v[118:121], v[150:153], v[188:191], v[118:121]
	v_mfma_f32_16x16x32_bf16 v[102:105], v[150:153], v[196:199], v[102:105]
	v_mfma_f32_16x16x32_bf16 v[102:105], v[146:149], v[192:195], v[102:105]
	v_mfma_f32_16x16x32_bf16 v[86:89], v[146:149], v[200:203], v[86:89]
	v_mfma_f32_16x16x32_bf16 v[86:89], v[150:153], v[204:207], v[86:89]
	v_mfma_f32_16x16x32_bf16 v[70:73], v[150:153], v[212:215], v[70:73]
	v_mfma_f32_16x16x32_bf16 v[70:73], v[146:149], v[208:211], v[70:73]
	v_mfma_f32_16x16x32_bf16 v[66:69], v[154:157], v[208:211], v[66:69]
	v_mfma_f32_16x16x32_bf16 v[66:69], v[158:161], v[212:215], v[66:69]
	v_mfma_f32_16x16x32_bf16 v[82:85], v[158:161], v[204:207], v[82:85]
	v_mfma_f32_16x16x32_bf16 v[82:85], v[154:157], v[200:203], v[82:85]
	s_barrier
	s_setprio 2
	v_mfma_f32_16x16x32_bf16 v[98:101], v[154:157], v[192:195], v[98:101]
	v_mfma_f32_16x16x32_bf16 v[98:101], v[158:161], v[196:199], v[98:101]
	v_mfma_f32_16x16x32_bf16 v[114:117], v[158:161], v[188:191], v[114:117]
	v_mfma_f32_16x16x32_bf16 v[114:117], v[154:157], v[184:187], v[114:117]
	s_setprio 0
	s_add_i32 s53, s80, s69
	v_lshl_add_u64 v[170:171], s[90:91], 0, v[162:163]
	s_mov_b32 m0, s53
	ds_read_b128 v[184:187], v177 offset:16384
	ds_read_b128 v[188:191], v177 offset:17408
	ds_read_b128 v[192:195], v177 offset:18432
	ds_read_b128 v[196:199], v177 offset:19456
	ds_read_b128 v[200:203], v177 offset:20480
	ds_read_b128 v[204:207], v177 offset:21504
	ds_read_b128 v[208:211], v177 offset:22528
	ds_read_b128 v[212:215], v177 offset:23552
	global_load_lds_dwordx4 v[170:171], off
	v_lshl_add_u64 v[216:217], v[170:171], 0, s[12:13]
	s_add_i32 m0, s53, 0x2000
	s_add_i32 s53, s81, s69
	global_load_lds_dwordx4 v[216:217], off
	v_lshl_add_u64 v[216:217], v[170:171], 0, s[14:15]
	s_mov_b32 m0, s53
	s_nop 0
	global_load_lds_dwordx4 v[216:217], off
	v_lshl_add_u64 v[216:217], v[170:171], 0, s[16:17]
	s_add_i32 m0, s53, 0x2000
	s_nop 0
	global_load_lds_dwordx4 v[216:217], off
	v_lshl_add_u64 v[216:217], s[64:65], 0, v[162:163]
	s_mov_b32 m0, s61
	v_lshl_add_u64 v[218:219], v[216:217], 0, s[12:13]
	global_load_lds_dwordx4 v[216:217], off
	s_mov_b32 m0, s70
	s_nop 0
	global_load_lds_dwordx4 v[218:219], off
	s_waitcnt vmcnt(8)
	s_waitcnt lgkmcnt(0)
	s_barrier
; #define PG8_STAGE(bufoff, gbase, voff) do { if constexpr (!pg8_noload<Epi>::value) { _Pragma("unroll") for (int _i = 0; _i < 2; ++_i) \
;         __builtin_amdgcn_global_load_lds((const unsigned*)((const char*)(gbase) + (size_t)_i * pstep + (voff)[0]), (PG8_LAS unsigned*)(lds + (bufoff) + ldsw + _i * 8192), 16, 0, 0); } } while (0)
; #define PG8_LDA(dst, b, h) do { _Pragma("unroll") for (int m = 0; m < 4; ++m) _Pragma("unroll") for (int k = 0; k < 2; ++k) dst[m][k] = *(const PG8_LAS bf16x8*)(lds + PG8_SA(b, h) + aoff + m * 2048 + k * 1024); } while (0)
; #define PG8_LDB(dst, b, h) do { _Pragma("unroll") for (int n = 0; n < 2; ++n) _Pragma("unroll") for (int k = 0; k < 2; ++k) dst[n][k] = *(const PG8_LAS bf16x8*)(lds + PG8_SB(b, h) + boff + n * 2048 + k * 1024); } while (0)
; #define PG8_MMA(ai, bj, At, Bt) do { __builtin_amdgcn_s_setprio(1); _Pragma("unroll") for (int m = 0; m < 4; ++m) _Pragma("unroll") for (int n = 0; n < 2; ++n) _Pragma("unroll") for (int k = 0; k < 2; ++k) \
;         acc[ai][bj][m][n] = __builtin_amdgcn_mfma_f32_16x16x32_bf16(Bt[n][k], At[m][k], acc[ai][bj][m][n], 0, 0, 0); __builtin_amdgcn_s_setprio(0); } while (0)
; #define PG8_WAIT_V(n) asm volatile("s_waitcnt vmcnt(" #n ")" ::: "memory")
; #define PG8_WAIT_L(n) asm volatile("s_waitcnt lgkmcnt(" #n ")" ::: "memory")
; #define PG8_BAR __builtin_amdgcn_s_barrier()
; #define PG8_SCHED __builtin_amdgcn_sched_barrier(0)
; template <class Epi, class Sched, bool ALIGN_EPI = false, bool SP2 = false, bool ABLK = false>
; __device__ __forceinline__ void gemm_phase(PG8_LAS unsigned char* lds, const Gemm g, const Sched& S, const Epi& E) {
;     ...
;             PG8_WAIT_V(8); PG8_WAIT_L(0); PG8_BAR; PG8_MMA(1, 0, At, B0); PG8_MMA(1, 1, At, B1); PG8_BAR; PG8_SCHED;
;             PG8_LDB(B0, 1, 0); PG8_LDB(B1, 1, 1); PG8_SCHED; PG8_LDA(At, 1, 0); PG8_STAGE(PG8_SA(0, 1), a2 + hstep, voffA);
;             PG8_WAIT_V(8); PG8_WAIT_L(0); PG8_BAR; PG8_MMA(0, 0, At, B0); PG8_MMA(0, 1, At, B1); PG8_BAR; PG8_SCHED;
	s_setprio 1
	s_waitcnt lgkmcnt(0)
	v_mfma_f32_16x16x32_bf16 v[62:65], v[130:133], v[184:187], v[62:65]
	v_mfma_f32_16x16x32_bf16 v[62:65], v[134:137], v[188:191], v[62:65]
	v_mfma_f32_16x16x32_bf16 v[46:49], v[134:137], v[196:199], v[46:49]
	v_mfma_f32_16x16x32_bf16 v[46:49], v[130:133], v[192:195], v[46:49]
	v_mfma_f32_16x16x32_bf16 v[30:33], v[130:133], v[200:203], v[30:33]
	v_mfma_f32_16x16x32_bf16 v[30:33], v[134:137], v[204:207], v[30:33]
	v_mfma_f32_16x16x32_bf16 v[14:17], v[134:137], v[212:215], v[14:17]
	v_mfma_f32_16x16x32_bf16 v[14:17], v[130:133], v[208:211], v[14:17]
	v_mfma_f32_16x16x32_bf16 v[10:13], v[138:141], v[208:211], v[10:13]
	v_mfma_f32_16x16x32_bf16 v[10:13], v[142:145], v[212:215], v[10:13]
	v_mfma_f32_16x16x32_bf16 v[26:29], v[142:145], v[204:207], v[26:29]
	v_mfma_f32_16x16x32_bf16 v[26:29], v[138:141], v[200:203], v[26:29]
	v_mfma_f32_16x16x32_bf16 v[42:45], v[138:141], v[192:195], v[42:45]
	v_mfma_f32_16x16x32_bf16 v[42:45], v[142:145], v[196:199], v[42:45]
	v_mfma_f32_16x16x32_bf16 v[58:61], v[142:145], v[188:191], v[58:61]
	v_mfma_f32_16x16x32_bf16 v[58:61], v[138:141], v[184:187], v[58:61]
	v_mfma_f32_16x16x32_bf16 v[54:57], v[146:149], v[184:187], v[54:57]
	v_mfma_f32_16x16x32_bf16 v[54:57], v[150:153], v[188:191], v[54:57]
	s_add_i32 s53, 0, 0x18000
	v_add_u32_e32 v142, s53, v1
	ds_read_b128 v[130:133], v142
	v_mfma_f32_16x16x32_bf16 v[38:41], v[150:153], v[196:199], v[38:41]
	v_mfma_f32_16x16x32_bf16 v[38:41], v[146:149], v[192:195], v[38:41]
	ds_read_b128 v[134:137], v142 offset:1024
	v_mfma_f32_16x16x32_bf16 v[22:25], v[146:149], v[200:203], v[22:25]
	v_mfma_f32_16x16x32_bf16 v[22:25], v[150:153], v[204:207], v[22:25]
	ds_read_b128 v[138:141], v142 offset:2048
	v_mfma_f32_16x16x32_bf16 v[6:9], v[150:153], v[212:215], v[6:9]
	v_mfma_f32_16x16x32_bf16 v[6:9], v[146:149], v[208:211], v[6:9]
	ds_read_b128 v[142:145], v142 offset:3072
	v_mfma_f32_16x16x32_bf16 v[2:5], v[154:157], v[208:211], v[2:5]
	v_mfma_f32_16x16x32_bf16 v[2:5], v[158:161], v[212:215], v[2:5]
	v_mfma_f32_16x16x32_bf16 v[18:21], v[158:161], v[204:207], v[18:21]
	v_mfma_f32_16x16x32_bf16 v[18:21], v[154:157], v[200:203], v[18:21]
	s_barrier
	s_setprio 2
	v_mfma_f32_16x16x32_bf16 v[34:37], v[154:157], v[192:195], v[34:37]
	v_mfma_f32_16x16x32_bf16 v[34:37], v[158:161], v[196:199], v[34:37]
	v_mfma_f32_16x16x32_bf16 v[50:53], v[158:161], v[188:191], v[50:53]
	v_mfma_f32_16x16x32_bf16 v[50:53], v[154:157], v[184:187], v[50:53]
	s_setprio 0
	s_add_i32 s64, 0, 0x1c000
	v_add_u32_e32 v158, s64, v1
	ds_read_b128 v[146:149], v158
	ds_read_b128 v[150:153], v158 offset:1024
	ds_read_b128 v[154:157], v158 offset:2048
	ds_read_b128 v[158:161], v158 offset:3072
	s_mov_b32 m0, s71
	v_lshl_add_u64 v[218:219], v[216:217], 0, s[14:15]
	ds_read_b128 v[184:187], v177 offset:32768
	ds_read_b128 v[188:191], v177 offset:33792
	ds_read_b128 v[192:195], v177 offset:34816
	ds_read_b128 v[196:199], v177 offset:35840
	ds_read_b128 v[200:203], v177 offset:36864
	ds_read_b128 v[204:207], v177 offset:37888
	ds_read_b128 v[208:211], v177 offset:38912
	ds_read_b128 v[212:215], v177 offset:39936
	global_load_lds_dwordx4 v[218:219], off
	v_lshl_add_u64 v[218:219], v[216:217], 0, s[16:17]
	s_mov_b32 m0, s72
	s_nop 0
	global_load_lds_dwordx4 v[218:219], off
	s_waitcnt vmcnt(8)
	s_waitcnt lgkmcnt(0)
	s_barrier
	s_setprio 1
	s_waitcnt lgkmcnt(0)
	v_mfma_f32_16x16x32_bf16 v[126:129], v[130:133], v[184:187], v[126:129]
	v_mfma_f32_16x16x32_bf16 v[126:129], v[134:137], v[188:191], v[126:129]
	v_mfma_f32_16x16x32_bf16 v[110:113], v[134:137], v[196:199], v[110:113]
	v_mfma_f32_16x16x32_bf16 v[110:113], v[130:133], v[192:195], v[110:113]
	v_mfma_f32_16x16x32_bf16 v[94:97], v[130:133], v[200:203], v[94:97]
	v_mfma_f32_16x16x32_bf16 v[94:97], v[134:137], v[204:207], v[94:97]
	v_mfma_f32_16x16x32_bf16 v[78:81], v[134:137], v[212:215], v[78:81]
	v_mfma_f32_16x16x32_bf16 v[78:81], v[130:133], v[208:211], v[78:81]
	v_mfma_f32_16x16x32_bf16 v[74:77], v[138:141], v[208:211], v[74:77]
	v_mfma_f32_16x16x32_bf16 v[74:77], v[142:145], v[212:215], v[74:77]
	v_mfma_f32_16x16x32_bf16 v[90:93], v[142:145], v[204:207], v[90:93]
	v_mfma_f32_16x16x32_bf16 v[90:93], v[138:141], v[200:203], v[90:93]
	v_mfma_f32_16x16x32_bf16 v[106:109], v[138:141], v[192:195], v[106:109]
	v_mfma_f32_16x16x32_bf16 v[106:109], v[142:145], v[196:199], v[106:109]
	v_mfma_f32_16x16x32_bf16 v[122:125], v[142:145], v[188:191], v[122:125]
	v_mfma_f32_16x16x32_bf16 v[122:125], v[138:141], v[184:187], v[122:125]
	v_mfma_f32_16x16x32_bf16 v[118:121], v[146:149], v[184:187], v[118:121]
	v_mfma_f32_16x16x32_bf16 v[118:121], v[150:153], v[188:191], v[118:121]
	v_mfma_f32_16x16x32_bf16 v[102:105], v[150:153], v[196:199], v[102:105]
	v_mfma_f32_16x16x32_bf16 v[102:105], v[146:149], v[192:195], v[102:105]
	v_mfma_f32_16x16x32_bf16 v[86:89], v[146:149], v[200:203], v[86:89]
	v_mfma_f32_16x16x32_bf16 v[86:89], v[150:153], v[204:207], v[86:89]
	v_mfma_f32_16x16x32_bf16 v[70:73], v[150:153], v[212:215], v[70:73]
	v_mfma_f32_16x16x32_bf16 v[70:73], v[146:149], v[208:211], v[70:73]
	v_mfma_f32_16x16x32_bf16 v[66:69], v[154:157], v[208:211], v[66:69]
	v_mfma_f32_16x16x32_bf16 v[66:69], v[158:161], v[212:215], v[66:69]
	v_mfma_f32_16x16x32_bf16 v[82:85], v[158:161], v[204:207], v[82:85]
	v_mfma_f32_16x16x32_bf16 v[82:85], v[154:157], v[200:203], v[82:85]
	s_barrier
; #define PG8_STAGE(bufoff, gbase, voff) do { if constexpr (!pg8_noload<Epi>::value) { _Pragma("unroll") for (int _i = 0; _i < 2; ++_i) \
;         __builtin_amdgcn_global_load_lds((const unsigned*)((const char*)(gbase) + (size_t)_i * pstep + (voff)[0]), (PG8_LAS unsigned*)(lds + (bufoff) + ldsw + _i * 8192), 16, 0, 0); } } while (0)
; #define PG8_LDA(dst, b, h) do { _Pragma("unroll") for (int m = 0; m < 4; ++m) _Pragma("unroll") for (int k = 0; k < 2; ++k) dst[m][k] = *(const PG8_LAS bf16x8*)(lds + PG8_SA(b, h) + aoff + m * 2048 + k * 1024); } while (0)
; #define PG8_MMA(ai, bj, At, Bt) do { __builtin_amdgcn_s_setprio(1); _Pragma("unroll") for (int m = 0; m < 4; ++m) _Pragma("unroll") for (int n = 0; n < 2; ++n) _Pragma("unroll") for (int k = 0; k < 2; ++k) \
;         acc[ai][bj][m][n] = __builtin_amdgcn_mfma_f32_16x16x32_bf16(Bt[n][k], At[m][k], acc[ai][bj][m][n], 0, 0, 0); __builtin_amdgcn_s_setprio(0); } while (0)
; #define PG8_WAIT_V(n) asm volatile("s_waitcnt vmcnt(" #n ")" ::: "memory")
; #define PG8_WAIT_L(n) asm volatile("s_waitcnt lgkmcnt(" #n ")" ::: "memory")
; #define PG8_BAR __builtin_amdgcn_s_barrier()
; #define PG8_SCHED __builtin_amdgcn_sched_barrier(0)
;     __device__ __forceinline__ void operator()(const f32x4 (&acc)[2][2][4][2], const Unit& u, int wr, int wc, int fr, int fq) const {
;     ...
;         if (u.pm * BM < seq) {
; template <class Epi, class Sched, bool ALIGN_EPI = false, bool SP2 = false, bool ABLK = false>
; __device__ __forceinline__ void gemm_phase(PG8_LAS unsigned char* lds, const Gemm g, const Sched& S, const Epi& E) {
;     ...
;             PG8_WAIT_V(8); PG8_WAIT_L(0); PG8_BAR; PG8_MMA(0, 0, At, B0); PG8_MMA(0, 1, At, B1); PG8_BAR; PG8_SCHED;
;             PG8_LDA(At, 1, 1); PG8_STAGE(PG8_SB(1, 0), b3, voffB); PG8_STAGE(PG8_SB(1, 1), b3 + hstep, voffB); PG8_STAGE(PG8_SA(1, 0), a3, voffA);
;             PG8_WAIT_V(8); PG8_WAIT_L(0); PG8_BAR; PG8_MMA(1, 0, At, B0); PG8_MMA(1, 1, At, B1); PG8_BAR; PG8_SCHED;
	s_setprio 2
	v_mfma_f32_16x16x32_bf16 v[98:101], v[154:157], v[192:195], v[98:101]
	v_mfma_f32_16x16x32_bf16 v[98:101], v[158:161], v[196:199], v[98:101]
	v_mfma_f32_16x16x32_bf16 v[114:117], v[158:161], v[188:191], v[114:117]
	v_mfma_f32_16x16x32_bf16 v[114:117], v[154:157], v[184:187], v[114:117]
	s_setprio 0
	s_add_i32 s53, s53, s69
	v_lshl_add_u64 v[218:219], v[170:171], 0, s[24:25]
	s_mov_b32 m0, s53
	ds_read_b128 v[184:187], v177 offset:49152
	ds_read_b128 v[188:191], v177 offset:50176
	ds_read_b128 v[192:195], v177 offset:51200
	ds_read_b128 v[196:199], v177 offset:52224
	ds_read_b128 v[200:203], v177 offset:53248
	ds_read_b128 v[204:207], v177 offset:54272
	ds_read_b128 v[208:211], v177 offset:55296
	ds_read_b128 v[212:215], v177 offset:56320
	global_load_lds_dwordx4 v[218:219], off
	v_lshl_add_u64 v[218:219], v[170:171], 0, s[26:27]
	s_add_i32 m0, s53, 0x2000
	s_add_i32 s53, s64, s69
	global_load_lds_dwordx4 v[218:219], off
	v_lshl_add_u64 v[218:219], v[170:171], 0, s[28:29]
	s_mov_b32 m0, s53
	v_lshl_add_u64 v[170:171], v[170:171], 0, s[30:31]
	global_load_lds_dwordx4 v[218:219], off
	s_add_i32 m0, s53, 0x2000
	s_nop 0
	global_load_lds_dwordx4 v[170:171], off
	v_lshl_add_u64 v[170:171], v[216:217], 0, s[24:25]
	s_mov_b32 m0, s75
	s_nop 0
	global_load_lds_dwordx4 v[170:171], off
	v_lshl_add_u64 v[170:171], v[216:217], 0, s[26:27]
	s_mov_b32 m0, s76
	s_nop 0
	global_load_lds_dwordx4 v[170:171], off
	s_waitcnt vmcnt(8)
	s_waitcnt lgkmcnt(0)
	s_barrier
	s_setprio 1
	s_waitcnt lgkmcnt(0)
	v_mfma_f32_16x16x32_bf16 v[62:65], v[130:133], v[184:187], v[62:65]
	v_mfma_f32_16x16x32_bf16 v[62:65], v[134:137], v[188:191], v[62:65]
	v_mfma_f32_16x16x32_bf16 v[46:49], v[134:137], v[196:199], v[46:49]
	v_mfma_f32_16x16x32_bf16 v[46:49], v[130:133], v[192:195], v[46:49]
	v_mfma_f32_16x16x32_bf16 v[30:33], v[130:133], v[200:203], v[30:33]
	v_mfma_f32_16x16x32_bf16 v[30:33], v[134:137], v[204:207], v[30:33]
	v_mfma_f32_16x16x32_bf16 v[14:17], v[134:137], v[212:215], v[14:17]
	v_mfma_f32_16x16x32_bf16 v[14:17], v[130:133], v[208:211], v[14:17]
	v_mfma_f32_16x16x32_bf16 v[10:13], v[138:141], v[208:211], v[10:13]
	v_mfma_f32_16x16x32_bf16 v[10:13], v[142:145], v[212:215], v[10:13]
	v_mfma_f32_16x16x32_bf16 v[26:29], v[142:145], v[204:207], v[26:29]
	v_mfma_f32_16x16x32_bf16 v[26:29], v[138:141], v[200:203], v[26:29]
	v_mfma_f32_16x16x32_bf16 v[42:45], v[138:141], v[192:195], v[42:45]
	v_mfma_f32_16x16x32_bf16 v[42:45], v[142:145], v[196:199], v[42:45]
	v_mfma_f32_16x16x32_bf16 v[58:61], v[142:145], v[188:191], v[58:61]
	v_mfma_f32_16x16x32_bf16 v[58:61], v[138:141], v[184:187], v[58:61]
	v_mfma_f32_16x16x32_bf16 v[54:57], v[146:149], v[184:187], v[54:57]
	v_mfma_f32_16x16x32_bf16 v[54:57], v[150:153], v[188:191], v[54:57]
	v_mfma_f32_16x16x32_bf16 v[38:41], v[150:153], v[196:199], v[38:41]
	v_mfma_f32_16x16x32_bf16 v[38:41], v[146:149], v[192:195], v[38:41]
	v_mfma_f32_16x16x32_bf16 v[22:25], v[146:149], v[200:203], v[22:25]
	v_mfma_f32_16x16x32_bf16 v[22:25], v[150:153], v[204:207], v[22:25]
	v_mfma_f32_16x16x32_bf16 v[6:9], v[150:153], v[212:215], v[6:9]
	v_mfma_f32_16x16x32_bf16 v[6:9], v[146:149], v[208:211], v[6:9]
	v_mfma_f32_16x16x32_bf16 v[2:5], v[154:157], v[208:211], v[2:5]
	v_mfma_f32_16x16x32_bf16 v[2:5], v[158:161], v[212:215], v[2:5]
	v_mfma_f32_16x16x32_bf16 v[18:21], v[158:161], v[204:207], v[18:21]
	v_mfma_f32_16x16x32_bf16 v[18:21], v[154:157], v[200:203], v[18:21]
	s_barrier
	s_setprio 2
	v_mfma_f32_16x16x32_bf16 v[34:37], v[154:157], v[192:195], v[34:37]
	v_mfma_f32_16x16x32_bf16 v[34:37], v[158:161], v[196:199], v[34:37]
	v_mfma_f32_16x16x32_bf16 v[50:53], v[158:161], v[188:191], v[50:53]
	v_mfma_f32_16x16x32_bf16 v[50:53], v[154:157], v[184:187], v[50:53]
	s_setprio 0
	s_add_u32 s62, s62, 0x1000
	s_addc_u32 s63, s63, 0
	s_add_u32 s11, s11, 0x1000
	s_addc_u32 s49, s49, 0
	s_cmp_ge_i32 s55, s89
	s_mov_b32 s53, s55
	s_cbranch_scc0 .LBB0_2399
	s_and_b64 vcc, exec, s[34:35]
	s_cbranch_vccnz .LBB0_2404
	s_lshl_b32 s11, s2, 8
	s_cmp_gt_i32 s2, 63
	s_mov_b64 s[62:63], -1
	s_cbranch_scc1 .LBB0_2405
